# WIN epilogue: hoist redundant s[88:95] spill reloads (1872 v_readlane removed)
# baseline (speedup 1.0000x reference)
.LBB0_390:
	v_readlane_b32 s92, v254, 12
	v_readlane_b32 s93, v254, 13
	v_readlane_b32 s94, v254, 14
	v_readlane_b32 s95, v254, 15
	s_cmp_gt_i32 s22, 11
	s_cselect_b64 s[18:19], -1, 0
	s_cmp_gt_u32 s22, 15
	s_cselect_b64 s[70:71], -1, 0
	s_cmp_gt_u32 s22, 39
	s_cselect_b64 s[68:69], -1, 0
	s_cmp_gt_u32 s22, 63
	s_cselect_b64 s[66:67], -1, 0
	s_cmp_gt_u32 s22, 47
	v_lshl_add_u32 v230, s0, 8, v1
	s_cselect_b64 s[62:63], -1, 0
	s_cmp_lt_u32 s22, 56
	s_mov_b32 s0, 0x2b7bc200
	s_cselect_b32 s46, s0, 0x2d8bc200
	s_lshl_b32 s12, s22, 8
	s_lshl_b32 s97, s22, 2
	s_and_b32 s0, s12, 0x700
	s_add_i32 s97, s97, s80
	s_cmp_lt_i32 s22, 10
	v_or_b32_e32 v229, s0, v205
	s_cselect_b64 s[0:1], -1, 0
	s_and_b64 s[2:3], s[0:1], exec
	s_mov_b32 s2, 0x1596000
	s_cselect_b32 s55, s2, 0x1597000
	s_mov_b32 s2, 0x1004000
	s_cselect_b32 s96, s2, 0x1404000
	s_mov_b32 s2, 0x21020200
	s_cselect_b32 s23, s2, 0x21860200
	s_and_b64 s[10:11], s[34:35], s[0:1]
	s_and_b64 s[0:1], s[10:11], exec
	s_cselect_b32 s53, 16, 4
	s_cmp_gt_i32 s22, 7
	v_add_u32_e32 v18, s14, v207
	s_cselect_b64 s[60:61], -1, 0
	s_add_i32 s14, s14, s81
	v_add_u32_e32 v231, s14, v217
	ds_read_b128 v[46:49], v18 offset:2048
	ds_read_b128 v[38:41], v18 offset:2112
	ds_read_b128 v[42:45], v18 offset:3072
	ds_read_b128 v[34:37], v18 offset:3136
	ds_read_b128 v[30:33], v18 offset:2560
	ds_read_b128 v[22:25], v18 offset:2624
	ds_read_b128 v[26:29], v18 offset:3584
	ds_read_b128 v[18:21], v18 offset:3648
	ds_read2_b64 v[150:153], v231 offset1:16
	ds_read2_b64 v[114:117], v231 offset0:32 offset1:48
	v_mov_b32_e32 v232, v230
	v_add_u32_e32 v228, s12, v206
	s_waitcnt lgkmcnt(0)
	v_pk_mul_f32 v[150:151], v[150:151], s[42:43] op_sel_hi:[1,0]
	v_and_b32_e32 v234, 0x7ff, v232
	v_fma_f32 v151, -v150, v150, v151
	v_max_f32_e32 v151, 0, v151
	v_add_f32_e32 v151, 0x3727c5ac, v151
	v_rsq_f32_e32 v170, v151
	v_cmp_gt_i32_e64 s[12:13], s76, v232
	s_mov_b64 s[2:3], -1
	v_cmp_gt_i32_e64 s[0:1], s86, v232
	v_mul_f32_e32 v150, v150, v170
	v_pk_mul_f32 v[172:173], v[48:49], v[150:151] op_sel_hi:[1,0]
	v_pk_mul_f32 v[174:175], v[46:47], v[150:151] op_sel_hi:[1,0]
	v_pk_fma_f32 v[168:169], v[168:169], v[170:171], v[172:173] op_sel_hi:[1,0,1] neg_lo:[0,0,1] neg_hi:[0,0,1]
	v_pk_mul_f32 v[172:173], v[40:41], v[150:151] op_sel_hi:[1,0]
	v_pk_fma_f32 v[166:167], v[166:167], v[170:171], v[174:175] op_sel_hi:[1,0,1] neg_lo:[0,0,1] neg_hi:[0,0,1]
	v_pk_mul_f32 v[174:175], v[38:39], v[150:151] op_sel_hi:[1,0]
	v_pk_fma_f32 v[164:165], v[164:165], v[170:171], v[172:173] op_sel_hi:[1,0,1] neg_lo:[0,0,1] neg_hi:[0,0,1]
	v_pk_mul_f32 v[172:173], v[32:33], v[150:151] op_sel_hi:[1,0]
	v_pk_fma_f32 v[162:163], v[162:163], v[170:171], v[174:175] op_sel_hi:[1,0,1] neg_lo:[0,0,1] neg_hi:[0,0,1]
	v_pk_mul_f32 v[174:175], v[30:31], v[150:151] op_sel_hi:[1,0]
	v_pk_fma_f32 v[160:161], v[160:161], v[170:171], v[172:173] op_sel_hi:[1,0,1] neg_lo:[0,0,1] neg_hi:[0,0,1]
	v_pk_mul_f32 v[172:173], v[24:25], v[150:151] op_sel_hi:[1,0]
	v_pk_mul_f32 v[150:151], v[22:23], v[150:151] op_sel_hi:[1,0]
	v_pk_fma_f32 v[158:159], v[158:159], v[170:171], v[174:175] op_sel_hi:[1,0,1] neg_lo:[0,0,1] neg_hi:[0,0,1]
	v_pk_fma_f32 v[150:151], v[154:155], v[170:171], v[150:151] op_sel_hi:[1,0,1] neg_lo:[0,0,1] neg_hi:[0,0,1]
	v_pk_fma_f32 v[154:155], v[156:157], v[170:171], v[172:173] op_sel_hi:[1,0,1] neg_lo:[0,0,1] neg_hi:[0,0,1]
	v_pk_add_f32 v[168:169], v[44:45], v[168:169]
	v_pk_add_f32 v[166:167], v[42:43], v[166:167]
	v_pk_add_f32 v[164:165], v[36:37], v[164:165]
	v_pk_add_f32 v[162:163], v[34:35], v[162:163]
	v_pk_add_f32 v[160:161], v[28:29], v[160:161]
	v_pk_add_f32 v[158:159], v[26:27], v[158:159]
	v_pk_add_f32 v[156:157], v[20:21], v[154:155]
	v_pk_add_f32 v[154:155], v[18:19], v[150:151]
	v_cndmask_b32_e64 v233, v222, v234, s[12:13]
	s_and_b64 vcc, exec, s[18:19]
	s_cbranch_vccz .LBB0_454
	s_and_b64 vcc, exec, s[70:71]
	s_cbranch_vccz .LBB0_434
	s_and_b64 vcc, exec, s[68:69]
	s_cbranch_vccz .LBB0_418
	s_and_b64 vcc, exec, s[66:67]
	s_cbranch_vccz .LBB0_406
	s_andn2_b64 vcc, exec, s[34:35]
	s_cbranch_vccz .LBB0_396
	v_mov_b32_e32 v170, v166
	v_mov_b32_e32 v171, v167
	v_mov_b32_e32 v172, v168
	v_mov_b32_e32 v173, v169
	s_and_saveexec_b64 s[14:15], s[0:1]
	s_cbranch_execnz .LBB0_397
	s_branch .LBB0_405
.LBB0_396:
	v_lshl_or_b32 v186, v233, 6, v209
	v_lshl_add_u64 v[150:151], s[94:95], 0, v[186:187]
	v_lshl_add_u64 v[174:175], v[150:151], 0, s[44:45]
	v_add_co_u32_e32 v150, vcc, 0x140000, v150
	s_nop 0
	s_nop 0
	v_addc_co_u32_e32 v151, vcc, 0, v151, vcc
	global_load_dwordx4 v[170:173], v[150:151], off offset:256
	s_nop 0
	global_load_dwordx4 v[174:177], v[174:175], off offset:16
	ds_bpermute_b32 v150, v218, v166
	ds_bpermute_b32 v151, v218, v167
	s_waitcnt vmcnt(0)
	v_mov_b32_e32 v179, v172
	v_mov_b32_e32 v172, v171
	s_waitcnt lgkmcnt(0)
	v_pk_mul_f32 v[150:151], v[172:173], v[150:151]
	v_mov_b32_e32 v178, v170
	v_cndmask_b32_e64 v151, v151, -v151, s[4:5]
	v_cndmask_b32_e64 v150, v150, -v150, s[4:5]
	v_pk_fma_f32 v[170:171], v[166:167], v[178:179], v[150:151]
	ds_bpermute_b32 v150, v218, v168
	ds_bpermute_b32 v151, v218, v169
	v_mov_b32_e32 v173, v176
	v_mov_b32_e32 v176, v175
	v_mov_b32_e32 v172, v174
	s_waitcnt lgkmcnt(0)
	v_pk_mul_f32 v[150:151], v[176:177], v[150:151]
	s_nop 0
	v_cndmask_b32_e64 v151, v151, -v151, s[4:5]
	v_cndmask_b32_e64 v150, v150, -v150, s[4:5]
	v_pk_fma_f32 v[172:173], v[168:169], v[172:173], v[150:151]
	s_and_saveexec_b64 s[14:15], s[0:1]
	s_cbranch_execz .LBB0_405
.LBB0_397:
	v_readlane_b32 s16, v254, 18
	v_readlane_b32 s17, v254, 19
	s_and_b64 vcc, exec, s[16:17]
	s_cbranch_vccz .LBB0_403
	v_readlane_b32 s16, v254, 20
	v_readlane_b32 s17, v254, 21
	s_and_b64 vcc, exec, s[16:17]
	s_cbranch_vccz .LBB0_400
	v_mul_f32_e32 v150, 0xbfb8aa3b, v170
	v_exp_f32_e32 v150, v150
	v_mul_f32_e32 v151, 0xbfb8aa3b, v171
	v_mul_f32_e32 v175, 0xbfb8aa3b, v173
	v_exp_f32_e32 v151, v151
	v_add_f32_e32 v150, 1.0, v150
	v_rcp_f32_e32 v174, v150
	v_mul_f32_e32 v150, 0xbfb8aa3b, v172
	v_exp_f32_e32 v150, v150
	v_exp_f32_e32 v177, v175
	v_add_f32_e32 v151, 1.0, v151
	v_rcp_f32_e32 v175, v151
	v_add_f32_e32 v150, 1.0, v150
	v_rcp_f32_e32 v176, v150
	v_add_f32_e32 v150, 1.0, v177
	v_rcp_f32_e32 v177, v150
	v_lshl_add_u32 v150, v232, 6, v252
	global_store_dwordx4 v150, v[174:177], s[94:95]
	s_mov_b64 s[2:3], 0
.LBB0_400:
	s_andn2_b64 vcc, exec, s[2:3]
	s_cbranch_vccnz .LBB0_402
	s_mov_b32 s2, 0x3d000000
	v_lshl_or_b32 v186, v232, 6, v203
	v_pk_mul_f32 v[176:177], v[172:173], s[2:3] op_sel_hi:[1,0]
	v_pk_mul_f32 v[174:175], v[170:171], s[2:3] op_sel_hi:[1,0]
	v_add_u32_e32 v150, 0x23230200, v186
	s_mov_b32 s16, 0x800000
	s_mov_b32 s17, 0x3f317217
	global_store_dwordx4 v150, v[174:177], s[94:95]
	v_or_b32_e32 v150, 0x6c000, v203
	global_load_dwordx4 v[174:177], v150, s[94:95]
	global_load_dwordx4 v[178:181], v150, s[94:95] offset:64
	s_waitcnt vmcnt(0)
	v_add_f32_e32 v151, v162, v178
	v_max_f32_e32 v150, 0, v151
	v_mul_f32_e64 v151, |v151|, s27
	v_exp_f32_e32 v151, v151
	v_add_f32_e32 v179, v163, v179
	v_add_f32_e32 v151, 1.0, v151
	v_cmp_gt_f32_e32 vcc, s16, v151
	s_nop 1
	v_cndmask_b32_e64 v178, 0, 32, vcc
	v_ldexp_f32 v151, v151, v178
	v_log_f32_e32 v151, v151
	s_nop 0
	v_mul_f32_e32 v178, 0x3f317217, v151
	v_fma_f32 v178, v151, s17, -v178
	v_fmac_f32_e32 v178, 0x3377d1cf, v151
	v_fmac_f32_e32 v178, 0x3f317217, v151
	v_cmp_lt_f32_e64 s[2:3], |v151|, s39
	s_nop 1
	v_cndmask_b32_e64 v151, v151, v178, s[2:3]
	v_cndmask_b32_e32 v178, 0, v223, vcc
	v_sub_f32_e32 v178, v151, v178
	v_max_f32_e32 v151, 0, v179
	v_mul_f32_e64 v179, |v179|, s27
	v_exp_f32_e32 v179, v179
	s_nop 0
	v_add_f32_e32 v179, 1.0, v179
	v_cmp_gt_f32_e32 vcc, s16, v179
	s_nop 1
	v_cndmask_b32_e64 v200, 0, 32, vcc
	v_ldexp_f32 v179, v179, v200
	v_log_f32_e32 v179, v179
	s_nop 0
	v_mul_f32_e32 v200, 0x3f317217, v179
	v_fma_f32 v200, v179, s17, -v200
	v_fmac_f32_e32 v200, 0x3377d1cf, v179
	v_fmac_f32_e32 v200, 0x3f317217, v179
	v_cmp_lt_f32_e64 s[2:3], |v179|, s39
	s_nop 1
	v_cndmask_b32_e64 v179, v179, v200, s[2:3]
	v_cndmask_b32_e32 v200, 0, v223, vcc
	v_sub_f32_e32 v179, v179, v200
	v_add_f32_e32 v200, v164, v180
	v_max_f32_e32 v180, 0, v200
	v_mul_f32_e64 v200, |v200|, s27
	v_exp_f32_e32 v200, v200
	v_pk_add_f32 v[150:151], v[150:151], v[178:179]
	v_add_f32_e32 v200, 1.0, v200
	v_cmp_gt_f32_e32 vcc, s16, v200
	v_pk_mul_f32 v[174:175], v[174:175], v[150:151]
	v_add_u32_e32 v150, 0x232b4200, v186
	v_cndmask_b32_e64 v201, 0, 32, vcc
	v_ldexp_f32 v200, v200, v201
	v_log_f32_e32 v200, v200
	s_nop 0
	v_mul_f32_e32 v201, 0x3f317217, v200
	v_fma_f32 v201, v200, s17, -v201
	v_fmac_f32_e32 v201, 0x3377d1cf, v200
	v_fmac_f32_e32 v201, 0x3f317217, v200
	v_cmp_lt_f32_e64 s[2:3], |v200|, s39
	s_nop 1
	v_cndmask_b32_e64 v200, v200, v201, s[2:3]
	v_cndmask_b32_e32 v201, 0, v223, vcc
	v_sub_f32_e32 v200, v200, v201
	v_add_f32_e32 v201, v165, v181
	v_max_f32_e32 v181, 0, v201
	v_mul_f32_e64 v201, |v201|, s27
	v_exp_f32_e32 v201, v201
	s_nop 0
	v_add_f32_e32 v201, 1.0, v201
	v_cmp_gt_f32_e32 vcc, s16, v201
	s_nop 1
	v_cndmask_b32_e64 v210, 0, 32, vcc
	v_ldexp_f32 v201, v201, v210
	v_log_f32_e32 v201, v201
	s_nop 0
	v_mul_f32_e32 v210, 0x3f317217, v201
	v_fma_f32 v210, v201, s17, -v210
	v_fmac_f32_e32 v210, 0x3377d1cf, v201
	v_fmac_f32_e32 v210, 0x3f317217, v201
	v_cmp_lt_f32_e64 s[2:3], |v201|, s39
	s_nop 1
	v_cndmask_b32_e64 v201, v201, v210, s[2:3]
	v_cndmask_b32_e32 v210, 0, v223, vcc
	v_sub_f32_e32 v201, v201, v210
	v_pk_add_f32 v[178:179], v[180:181], v[200:201]
	s_nop 0
	v_pk_mul_f32 v[176:177], v[176:177], v[178:179]
	global_store_dwordx4 v150, v[174:177], s[94:95]

.LBB0_403:
	s_andn2_b64 vcc, exec, s[2:3]
	s_cbranch_vccnz .LBB0_405
	v_cndmask_b32_e64 v150, v224, v225, s[12:13]
	v_lshl_add_u32 v150, v232, 6, v150
	v_or_b32_e32 v150, v150, v213
	v_lshlrev_b32_e32 v150, 2, v150
	v_lshl_or_b32 v174, v232, 7, v214
	s_nop 1
	global_store_dwordx4 v150, v[170:173], s[92:93]
	global_store_dwordx4 v150, v[162:165], s[92:93] offset:64
	v_add_u32_e32 v175, 0x23120200, v174
	v_cvt_pk_bf16_f32 v150, v170, v171
	v_cvt_pk_bf16_f32 v151, v172, v173
	global_store_dwordx2 v175, v[150:151], s[94:95]
	v_cvt_pk_bf16_f32 v150, v162, v163
	v_cvt_pk_bf16_f32 v151, v164, v165
	v_add_u32_e32 v170, 0x23120220, v174
	global_store_dwordx2 v170, v[150:151], s[94:95]

.LBB0_412:
	s_nop 0
	v_cvt_pk_bf16_f32 v173, v150, v151
	v_lshlrev_b32_e32 v150, 1, v229
	v_lshl_or_b32 v174, v232, 12, v150
	v_add_u32_e32 v150, s14, v174
	s_andn2_b64 vcc, exec, s[62:63]
	s_mov_b64 s[14:15], -1
	global_store_dwordx4 v150, v[170:173], s[94:95]
	s_cbranch_vccnz .LBB0_414
	s_nop 0
	v_cvt_pk_bf16_f32 v170, v158, v159
	v_cvt_pk_bf16_f32 v171, v160, v161
	v_cvt_pk_bf16_f32 v172, v154, v155
	s_mov_b64 s[14:15], 0
	v_mov_b32_e32 v151, v157
	v_mov_b32_e32 v150, v156

.LBB0_416:
	s_nop 0
	v_cvt_pk_bf16_f32 v173, v150, v151
	v_add_u32_e32 v150, s14, v174
	v_add_u32_e32 v150, 0x100, v150
	global_store_dwordx4 v150, v[170:173], s[94:95]

.LBB0_419:
	s_and_saveexec_b64 s[14:15], s[0:1]
	s_cbranch_execz .LBB0_432
	v_ashrrev_i32_e32 v150, 11, v232
	v_mul_lo_u32 v151, v232, s36
	v_mad_i32_i24 v150, v150, 3, v234
	v_mul_lo_u32 v150, v150, s36
	v_add_u32_e32 v174, v151, v228
	v_cmp_gt_i32_e64 s[2:3], s76, v232
	v_cmp_lt_u32_e32 vcc, s37, v234
	v_add_u32_e32 v150, 0xd88800, v150
	v_cvt_pk_bf16_f32 v170, v166, v167
	v_cvt_pk_bf16_f32 v171, v168, v169
	v_cvt_pk_bf16_f32 v172, v162, v163
	v_cvt_pk_bf16_f32 v173, v164, v165
	v_lshl_add_u32 v174, v174, 1, v226
	global_store_dwordx4 v174, v[170:173], s[94:95]
	s_and_saveexec_b64 s[16:17], s[2:3]
	s_xor_b64 s[16:17], exec, s[16:17]
	s_cbranch_execz .LBB0_424
	s_and_saveexec_b64 s[64:65], vcc
	s_cbranch_execz .LBB0_423
	v_add_lshl_u32 v170, v150, v228, 2
	global_store_dwordx4 v170, v[166:169], s[92:93]
	global_store_dwordx4 v170, v[162:165], s[92:93] offset:16

.LBB0_424:
	s_or_saveexec_b64 s[16:17], s[16:17]
	s_movk_i32 s33, 0x4800
	v_mul_lo_u32 v170, v232, s33
	v_add_u32_e32 v170, 0xf8b9b200, v170
	s_xor_b64 exec, exec, s[16:17]
	s_cbranch_execz .LBB0_426
	v_add_lshl_u32 v171, v170, v228, 2
	global_store_dwordx4 v171, v[166:169], s[92:93]
	global_store_dwordx4 v171, v[162:165], s[92:93] offset:16
.LBB0_426:
	s_or_b64 exec, exec, s[16:17]
	v_or_b32_e32 v171, 0x80, v228
	v_add_u32_e32 v151, v151, v171
	v_cvt_pk_bf16_f32 v172, v158, v159
	v_cvt_pk_bf16_f32 v173, v160, v161
	v_cvt_pk_bf16_f32 v174, v154, v155
	v_cvt_pk_bf16_f32 v175, v156, v157
	v_lshl_add_u32 v151, v151, 1, v226
	global_store_dwordx4 v151, v[172:175], s[94:95]
	s_and_saveexec_b64 s[16:17], s[2:3]
	s_xor_b64 s[2:3], exec, s[16:17]
	s_cbranch_execz .LBB0_430
	s_and_saveexec_b64 s[16:17], vcc
	s_cbranch_execz .LBB0_429
	v_add_lshl_u32 v150, v150, v171, 2
	global_store_dwordx4 v150, v[158:161], s[92:93]
	global_store_dwordx4 v150, v[154:157], s[92:93] offset:16

.LBB0_430:
	s_andn2_saveexec_b64 s[2:3], s[2:3]
	s_cbranch_execz .LBB0_432
	v_add_lshl_u32 v150, v170, v171, 2
	global_store_dwordx4 v150, v[158:161], s[92:93]
	global_store_dwordx4 v150, v[154:157], s[92:93] offset:16

.LBB0_434:
	s_andn2_b64 vcc, exec, s[2:3]
	s_cbranch_vccnz .LBB0_453
	v_lshl_or_b32 v186, v233, 6, v209
	v_cndmask_b32_e64 v150, 0, 1, s[6:7]
	v_cmp_ne_u32_e64 s[14:15], 1, v150
	v_lshl_add_u64 v[178:179], s[94:95], 0, v[186:187]
	s_andn2_b64 vcc, exec, s[6:7]
	v_lshl_add_u64 v[150:151], v[178:179], 0, s[44:45]
	s_cbranch_vccnz .LBB0_437
	v_add_co_u32_e32 v170, vcc, 0x140000, v178
	ds_bpermute_b32 v180, v218, v166
	s_nop 0
	v_addc_co_u32_e32 v171, vcc, 0, v179, vcc
	global_load_dwordx4 v[170:173], v[170:171], off offset:256
	s_nop 0
	global_load_dwordx4 v[174:177], v[150:151], off offset:16
	ds_bpermute_b32 v181, v218, v167
	s_waitcnt vmcnt(0)
	v_mov_b32_e32 v201, v172
	v_mov_b32_e32 v172, v171
	v_mov_b32_e32 v200, v170
	s_waitcnt lgkmcnt(0)
	v_pk_mul_f32 v[170:171], v[172:173], v[180:181]
	ds_bpermute_b32 v172, v218, v168
	ds_bpermute_b32 v173, v218, v169
	v_mov_b32_e32 v181, v176
	v_mov_b32_e32 v176, v175
	v_cndmask_b32_e64 v171, v171, -v171, s[4:5]
	v_cndmask_b32_e64 v170, v170, -v170, s[4:5]
	s_waitcnt lgkmcnt(0)
	v_pk_mul_f32 v[172:173], v[176:177], v[172:173]
	v_mov_b32_e32 v180, v174
	v_cndmask_b32_e64 v173, v173, -v173, s[4:5]
	v_cndmask_b32_e64 v172, v172, -v172, s[4:5]
	v_pk_fma_f32 v[170:171], v[166:167], v[200:201], v[170:171]
	v_pk_fma_f32 v[172:173], v[168:169], v[180:181], v[172:173]
	s_branch .LBB0_438

.LBB0_438:
	v_lshlrev_b32_e32 v174, 10, v232
	v_or_b32_e32 v181, v174, v215
	v_cmp_lt_i32_e64 s[2:3], s26, v232
	v_add_u32_e32 v180, v174, v216
	s_and_saveexec_b64 s[16:17], s[0:1]
	s_cbranch_execz .LBB0_443
	s_lshl_b32 s33, s97, 6
	v_add_lshl_u32 v186, v181, s33, 1
	v_add_u32_e32 v200, 0x220a0200, v186
	v_cvt_pk_bf16_f32 v174, v170, v171
	v_cvt_pk_bf16_f32 v175, v172, v173
	s_mov_b64 s[64:65], -1
	s_and_b64 vcc, exec, s[40:41]
	v_cvt_pk_bf16_f32 v176, v162, v163
	v_cvt_pk_bf16_f32 v177, v164, v165
	s_cbranch_vccz .LBB0_445
	global_store_dwordx4 v200, v[174:177], s[94:95]
	s_cbranch_execz .LBB0_446

.LBB0_442:
	v_add_u32_e32 v174, s33, v180
	v_lshl_add_u32 v186, v174, 2, v227
	v_lshl_add_u64 v[174:175], s[94:95], 0, v[186:187]
	v_lshl_add_u64 v[174:175], v[174:175], 0, s[24:25]
	global_store_dwordx4 v186, v[170:173], s[94:95]
	global_store_dwordx4 v[174:175], v[162:165], off

.LBB0_446:
	global_store_dwordx2 v200, v[174:175], s[94:95]
	v_add_u32_e32 v174, 0x220a0220, v186
	global_store_dwordx2 v174, v[176:177], s[94:95]
	s_and_b64 exec, exec, s[2:3]
	s_cbranch_execnz .LBB0_442
	s_branch .LBB0_443

.LBB0_448:
	s_lshl_b32 s33, s97, 6
	s_bitset1_b32 s33, 7
	v_add_lshl_u32 v150, v181, s33, 1
	v_add_u32_e32 v151, 0x220a0200, v150
	v_cvt_pk_bf16_f32 v174, v170, v171
	v_cvt_pk_bf16_f32 v175, v172, v173
	s_mov_b64 s[16:17], -1
	s_andn2_b64 vcc, exec, s[40:41]
	v_cvt_pk_bf16_f32 v176, v154, v155
	v_cvt_pk_bf16_f32 v177, v156, v157
	s_cbranch_vccnz .LBB0_490
	global_store_dwordx4 v151, v[174:177], s[94:95]
	s_cbranch_execz .LBB0_491

.LBB0_451:
	v_add_u32_e32 v150, s33, v180
	v_lshl_add_u32 v186, v150, 2, v227
	v_lshl_add_u64 v[150:151], s[94:95], 0, v[186:187]
	v_lshl_add_u64 v[150:151], v[150:151], 0, s[24:25]
	global_store_dwordx4 v186, v[170:173], s[94:95]
	global_store_dwordx4 v[150:151], v[154:157], off

.LBB0_454:
	s_lshl_b32 s14, s22, 1
	v_cndmask_b32_e64 v150, 0, 1, s[10:11]
	s_xor_b64 s[64:65], s[10:11], -1
	v_cndmask_b32_e64 v176, v205, v212, s[10:11]
	s_and_b32 s87, s14, 2
	s_andn2_b64 vcc, exec, s[2:3]
	v_cmp_ne_u32_e64 s[10:11], 1, v150
	s_cbranch_vccnz .LBB0_484
	v_lshl_or_b32 v186, v233, 7, v208
	s_and_b64 vcc, exec, s[10:11]
	v_lshl_add_u64 v[150:151], s[94:95], 0, v[186:187]
	v_lshl_add_u64 v[174:175], v[150:151], 0, s[48:49]
	s_cbranch_vccnz .LBB0_457
	global_load_dwordx4 v[170:173], v[174:175], off offset:16
	v_add_co_u32_e32 v178, vcc, 0x100000, v150
	s_nop 1
	v_addc_co_u32_e32 v179, vcc, 0, v151, vcc
	global_load_dwordx4 v[178:181], v[178:179], off
	s_waitcnt vmcnt(0)
	v_mul_f32_e32 v200, v168, v170
	v_mul_f32_e32 v234, v168, v171
	v_mov_b32_e32 v168, v165
	v_mul_f32_e32 v210, v164, v171
	v_mul_f32_e32 v170, v164, v170
	v_mov_b32_e32 v164, v169
	v_pk_mul_f32 v[168:169], v[168:169], v[172:173]
	v_pk_mul_f32 v[164:165], v[164:165], v[172:173]
	v_mov_b32_e32 v171, v168
	v_mov_b32_e32 v235, v169
	v_mov_b32_e32 v173, v180
	v_mov_b32_e32 v180, v179
	v_mov_b32_e32 v201, v164
	v_mov_b32_e32 v211, v165
	v_mov_b32_e32 v172, v178
	v_pk_add_f32 v[164:165], v[170:171], v[234:235]
	v_pk_mul_f32 v[170:171], v[162:163], v[180:181]
	v_pk_mul_f32 v[178:179], v[166:167], v[180:181]
	v_pk_add_f32 v[168:169], v[200:201], v[210:211] neg_lo:[0,1] neg_hi:[0,1]
	v_pk_fma_f32 v[166:167], v[166:167], v[172:173], v[170:171] neg_lo:[0,0,1] neg_hi:[0,0,1]
	v_pk_fma_f32 v[162:163], v[162:163], v[172:173], v[178:179]
.LBB0_457:
	v_lshlrev_b32_e32 v170, 9, v232
	v_add_u32_e32 v178, s55, v170
	v_add_u32_e32 v179, s96, v170
	v_or_b32_e32 v177, v170, v176
	s_and_saveexec_b64 s[2:3], s[0:1]
	s_cbranch_execz .LBB0_469
	s_mov_b64 s[14:15], -1
	s_and_b64 vcc, exec, s[60:61]
	s_cbranch_vccz .LBB0_464
	v_cndmask_b32_e64 v170, v178, v179, s[12:13]
	s_lshl_b32 s14, s87, 7
	v_or3_b32 v170, v176, v170, s14
	v_lshlrev_b32_e32 v171, 2, v170
	v_add_lshl_u32 v170, v170, s53, 2
	s_and_b64 vcc, exec, s[64:65]
	v_cvt_pk_bf16_f32 v172, v162, v163
	v_cvt_pk_bf16_f32 v173, v164, v165
	global_store_dwordx4 v171, v[166:169], s[92:93]
	global_store_dwordx4 v170, v[162:165], s[92:93]
	v_or_b32_e32 v170, s14, v177
	v_lshl_add_u32 v180, v170, 1, s23
	v_cvt_pk_bf16_f32 v170, v166, v167
	v_cvt_pk_bf16_f32 v171, v168, v169
	s_mov_b64 s[14:15], -1
	s_cbranch_vccz .LBB0_461
	global_store_dwordx4 v180, v[170:173], s[94:95]
	s_mov_b64 s[14:15], 0
.LBB0_461:
	s_andn2_b64 vcc, exec, s[14:15]
	s_cbranch_vccnz .LBB0_463
	global_store_dwordx2 v180, v[170:171], s[94:95]
	v_add_u32_e32 v170, 32, v180
	global_store_dwordx2 v170, v[172:173], s[94:95]

.LBB0_464:
	s_andn2_b64 vcc, exec, s[14:15]
	s_cbranch_vccnz .LBB0_469
	s_lshl_b32 s14, s22, 9
	v_lshl_or_b32 v170, v176, 1, s14
	v_lshl_add_u32 v170, v232, 12, v170
	v_pk_mul_f32 v[168:169], v[168:169], s[50:51] op_sel_hi:[1,0]
	v_pk_mul_f32 v[166:167], v[166:167], s[50:51] op_sel_hi:[1,0]
	v_add_u32_e32 v171, 0x1ef20200, v170
	v_cvt_pk_bf16_f32 v166, v166, v167
	v_cvt_pk_bf16_f32 v167, v168, v169
	s_mov_b64 s[14:15], -1
	s_and_b64 vcc, exec, s[64:65]
	s_cbranch_vccz .LBB0_467
	v_pk_mul_f32 v[172:173], v[164:165], s[50:51] op_sel_hi:[1,0]
	v_pk_mul_f32 v[168:169], v[162:163], s[50:51] op_sel_hi:[1,0]
	v_cvt_pk_bf16_f32 v168, v168, v169
	v_cvt_pk_bf16_f32 v169, v172, v173
	global_store_dwordx4 v171, v[166:169], s[94:95]
	s_mov_b64 s[14:15], 0
.LBB0_467:
	s_andn2_b64 vcc, exec, s[14:15]
	s_cbranch_vccnz .LBB0_469
	v_pk_mul_f32 v[164:165], v[164:165], s[50:51] op_sel_hi:[1,0]
	v_pk_mul_f32 v[162:163], v[162:163], s[50:51] op_sel_hi:[1,0]
	v_cvt_pk_bf16_f32 v162, v162, v163
	v_cvt_pk_bf16_f32 v163, v164, v165
	v_add_u32_e32 v164, 0x1ef20220, v170
	global_store_dwordx2 v171, v[166:167], s[94:95]
	global_store_dwordx2 v164, v[162:163], s[94:95]

.LBB0_471:
	s_and_saveexec_b64 s[2:3], s[0:1]
	s_cbranch_execz .LBB0_483
	s_andn2_b64 vcc, exec, s[60:61]
	s_mov_b64 s[0:1], -1
	s_cbranch_vccnz .LBB0_478
	s_lshl_b32 s0, s87, 7
	v_cndmask_b32_e64 v150, v178, v179, s[12:13]
	s_bitset1_b32 s0, 7
	v_or3_b32 v150, v176, v150, s0
	v_lshlrev_b32_e32 v151, 2, v150
	v_add_lshl_u32 v150, v150, s53, 2
	v_cvt_pk_bf16_f32 v162, v158, v159
	v_cvt_pk_bf16_f32 v163, v160, v161
	s_andn2_b64 vcc, exec, s[64:65]
	v_cvt_pk_bf16_f32 v164, v154, v155
	global_store_dwordx4 v151, v[158:161], s[92:93]
	global_store_dwordx4 v150, v[154:157], s[92:93]
	v_or_b32_e32 v150, s0, v177
	v_lshl_add_u32 v150, v150, 1, s23
	s_mov_b64 s[0:1], -1
	v_cvt_pk_bf16_f32 v165, v156, v157
	s_cbranch_vccnz .LBB0_475
	s_mov_b64 s[0:1], 0
	global_store_dwordx4 v150, v[162:165], s[94:95]
.LBB0_475:
	s_andn2_b64 vcc, exec, s[0:1]
	s_cbranch_vccnz .LBB0_477
	global_store_dwordx2 v150, v[162:163], s[94:95]
	v_add_u32_e32 v150, 32, v150
	global_store_dwordx2 v150, v[164:165], s[94:95]

.LBB0_478:
	s_andn2_b64 vcc, exec, s[0:1]
	s_cbranch_vccnz .LBB0_483
	s_lshl_b32 s0, s22, 9
	v_lshl_or_b32 v150, v176, 1, s0
	v_lshl_add_u32 v150, v232, 12, v150
	v_pk_mul_f32 v[160:161], v[160:161], s[50:51] op_sel_hi:[1,0]
	v_pk_mul_f32 v[158:159], v[158:159], s[50:51] op_sel_hi:[1,0]
	v_add_u32_e32 v151, 0x1ef20300, v150
	v_cvt_pk_bf16_f32 v158, v158, v159
	v_cvt_pk_bf16_f32 v159, v160, v161
	s_andn2_b64 vcc, exec, s[64:65]
	s_mov_b64 s[0:1], -1
	s_cbranch_vccnz .LBB0_481
	v_pk_mul_f32 v[162:163], v[156:157], s[50:51] op_sel_hi:[1,0]
	v_pk_mul_f32 v[160:161], v[154:155], s[50:51] op_sel_hi:[1,0]
	v_cvt_pk_bf16_f32 v160, v160, v161
	v_cvt_pk_bf16_f32 v161, v162, v163
	s_mov_b64 s[0:1], 0
	global_store_dwordx4 v151, v[158:161], s[94:95]
.LBB0_481:
	s_andn2_b64 vcc, exec, s[0:1]
	s_cbranch_vccnz .LBB0_483
	v_pk_mul_f32 v[156:157], v[156:157], s[50:51] op_sel_hi:[1,0]
	v_pk_mul_f32 v[154:155], v[154:155], s[50:51] op_sel_hi:[1,0]
	v_cvt_pk_bf16_f32 v154, v154, v155
	v_cvt_pk_bf16_f32 v155, v156, v157
	v_add_u32_e32 v150, 0x1ef20320, v150
	global_store_dwordx2 v151, v[158:159], s[94:95]
	global_store_dwordx2 v150, v[154:155], s[94:95]

.LBB0_491:
	v_add_u32_e32 v150, 0x220a0220, v150
	global_store_dwordx2 v151, v[174:175], s[94:95]
	global_store_dwordx2 v150, v[176:177], s[94:95]
	s_and_b64 exec, exec, s[2:3]
	s_cbranch_execnz .LBB0_451
	s_branch .LBB0_452

.LBB0_493:
	v_lshl_or_b32 v186, v167, 6, v209
	ds_bpermute_b32 v158, v218, v146
	ds_bpermute_b32 v159, v218, v147
	v_lshl_add_u64 v[150:151], s[94:95], 0, v[186:187]
	v_lshl_add_u64 v[154:155], v[150:151], 0, s[44:45]
	v_add_co_u32_e32 v150, vcc, 0x140000, v150
	s_nop 0
	s_nop 0
	v_addc_co_u32_e32 v151, vcc, 0, v151, vcc
	global_load_dwordx4 v[150:153], v[150:151], off offset:256
	s_nop 0
	global_load_dwordx4 v[154:157], v[154:155], off offset:16
	s_waitcnt vmcnt(0)
	v_mov_b32_e32 v161, v152
	v_mov_b32_e32 v152, v151
	v_mov_b32_e32 v160, v150
	s_waitcnt lgkmcnt(0)
	v_pk_mul_f32 v[150:151], v[152:153], v[158:159]
	ds_bpermute_b32 v152, v218, v148
	ds_bpermute_b32 v153, v218, v149
	v_mov_b32_e32 v159, v156
	v_mov_b32_e32 v156, v155
	v_cndmask_b32_e64 v151, v151, -v151, s[4:5]
	v_cndmask_b32_e64 v150, v150, -v150, s[4:5]
	s_waitcnt lgkmcnt(0)
	v_pk_mul_f32 v[152:153], v[156:157], v[152:153]
	v_mov_b32_e32 v158, v154
	v_cndmask_b32_e64 v153, v153, -v153, s[4:5]
	v_cndmask_b32_e64 v152, v152, -v152, s[4:5]
	v_pk_fma_f32 v[150:151], v[146:147], v[160:161], v[150:151]
	v_pk_fma_f32 v[152:153], v[148:149], v[158:159], v[152:153]
	s_and_saveexec_b64 s[18:19], s[0:1]
	s_cbranch_execz .LBB0_502
.LBB0_494:
	v_readlane_b32 s2, v254, 18
	v_readlane_b32 s3, v254, 19
	s_andn2_b64 vcc, exec, s[2:3]
	s_mov_b64 s[2:3], -1
	s_cbranch_vccnz .LBB0_500
	v_readlane_b32 s2, v254, 20
	v_readlane_b32 s3, v254, 21
	s_andn2_b64 vcc, exec, s[2:3]
	s_mov_b64 s[2:3], -1
	s_cbranch_vccnz .LBB0_497
	v_mul_f32_e32 v154, 0xbfb8aa3b, v150
	v_mul_f32_e32 v155, 0xbfb8aa3b, v151
	v_mul_f32_e32 v156, 0xbfb8aa3b, v152
	v_mul_f32_e32 v157, 0xbfb8aa3b, v153
	v_exp_f32_e32 v154, v154
	v_exp_f32_e32 v155, v155
	v_exp_f32_e32 v156, v156
	v_exp_f32_e32 v157, v157
	v_add_f32_e32 v154, 1.0, v154
	v_add_f32_e32 v155, 1.0, v155
	v_add_f32_e32 v156, 1.0, v156
	v_add_f32_e32 v157, 1.0, v157
	v_rcp_f32_e32 v154, v154
	v_rcp_f32_e32 v155, v155
	v_rcp_f32_e32 v156, v156
	v_rcp_f32_e32 v157, v157
	v_lshl_add_u32 v158, v166, 6, v252
	s_mov_b64 s[2:3], 0
	global_store_dwordx4 v158, v[154:157], s[94:95]
.LBB0_497:
	s_andn2_b64 vcc, exec, s[2:3]
	s_cbranch_vccnz .LBB0_499
	s_mov_b32 s2, 0x3d000000
	v_lshl_or_b32 v169, v166, 6, v203
	v_pk_mul_f32 v[156:157], v[152:153], s[2:3] op_sel_hi:[1,0]
	v_pk_mul_f32 v[154:155], v[150:151], s[2:3] op_sel_hi:[1,0]
	v_add_u32_e32 v158, 0x23230200, v169
	s_mov_b32 s33, 0x800000
	s_mov_b32 s70, 0x3f317217
	global_store_dwordx4 v158, v[154:157], s[94:95]
	v_or_b32_e32 v158, 0x6c000, v203
	global_load_dwordx4 v[154:157], v158, s[94:95]
	s_nop 0
	global_load_dwordx4 v[158:161], v158, s[94:95] offset:64
	s_waitcnt vmcnt(0)
	v_add_f32_e32 v162, v142, v158
	v_max_f32_e32 v158, 0, v162
	v_mul_f32_e64 v162, |v162|, s27
	v_exp_f32_e32 v162, v162
	s_nop 0
	v_add_f32_e32 v162, 1.0, v162
	v_cmp_gt_f32_e32 vcc, s33, v162
	s_nop 1
	v_cndmask_b32_e64 v163, 0, 32, vcc
	v_ldexp_f32 v162, v162, v163
	v_log_f32_e32 v162, v162
	s_nop 0
	v_mul_f32_e32 v163, 0x3f317217, v162
	v_fma_f32 v163, v162, s70, -v163
	v_fmac_f32_e32 v163, 0x3377d1cf, v162
	v_fmac_f32_e32 v163, 0x3f317217, v162
	v_cmp_lt_f32_e64 s[2:3], |v162|, s39
	s_nop 1
	v_cndmask_b32_e64 v162, v162, v163, s[2:3]
	v_cndmask_b32_e32 v163, 0, v223, vcc
	v_sub_f32_e32 v162, v162, v163
	v_add_f32_e32 v163, v143, v159
	v_max_f32_e32 v159, 0, v163
	v_mul_f32_e64 v163, |v163|, s27
	v_exp_f32_e32 v163, v163
	s_nop 0
	v_add_f32_e32 v163, 1.0, v163
	v_cmp_gt_f32_e32 vcc, s33, v163
	s_nop 1
	v_cndmask_b32_e64 v164, 0, 32, vcc
	v_ldexp_f32 v163, v163, v164
	v_log_f32_e32 v163, v163
	s_nop 0
	v_mul_f32_e32 v164, 0x3f317217, v163
	v_fma_f32 v164, v163, s70, -v164
	v_fmac_f32_e32 v164, 0x3377d1cf, v163
	v_fmac_f32_e32 v164, 0x3f317217, v163
	v_cmp_lt_f32_e64 s[2:3], |v163|, s39
	s_nop 1
	v_cndmask_b32_e64 v163, v163, v164, s[2:3]
	v_cndmask_b32_e32 v164, 0, v223, vcc
	v_sub_f32_e32 v163, v163, v164
	v_add_f32_e32 v164, v144, v160
	v_max_f32_e32 v160, 0, v164
	v_mul_f32_e64 v164, |v164|, s27
	v_exp_f32_e32 v164, v164
	v_pk_add_f32 v[158:159], v[158:159], v[162:163]
	v_add_f32_e32 v164, 1.0, v164
	v_cmp_gt_f32_e32 vcc, s33, v164
	v_pk_mul_f32 v[154:155], v[154:155], v[158:159]
	v_add_u32_e32 v158, 0x232b4200, v169
	v_cndmask_b32_e64 v165, 0, 32, vcc
	v_ldexp_f32 v164, v164, v165
	v_log_f32_e32 v164, v164
	s_nop 0
	v_mul_f32_e32 v165, 0x3f317217, v164
	v_fma_f32 v165, v164, s70, -v165
	v_fmac_f32_e32 v165, 0x3377d1cf, v164
	v_fmac_f32_e32 v165, 0x3f317217, v164
	v_cmp_lt_f32_e64 s[2:3], |v164|, s39
	s_nop 1
	v_cndmask_b32_e64 v164, v164, v165, s[2:3]
	v_cndmask_b32_e32 v165, 0, v223, vcc
	v_sub_f32_e32 v164, v164, v165
	v_add_f32_e32 v165, v145, v161
	v_max_f32_e32 v161, 0, v165
	v_mul_f32_e64 v165, |v165|, s27
	v_exp_f32_e32 v165, v165
	s_nop 0
	v_add_f32_e32 v165, 1.0, v165
	v_cmp_gt_f32_e32 vcc, s33, v165
	s_nop 1
	v_cndmask_b32_e64 v170, 0, 32, vcc
	v_ldexp_f32 v165, v165, v170
	v_log_f32_e32 v165, v165
	s_nop 0
	v_mul_f32_e32 v170, 0x3f317217, v165
	v_fma_f32 v170, v165, s70, -v170
	v_fmac_f32_e32 v170, 0x3377d1cf, v165
	v_fmac_f32_e32 v170, 0x3f317217, v165
	v_cmp_lt_f32_e64 s[2:3], |v165|, s39
	s_nop 1
	v_cndmask_b32_e64 v165, v165, v170, s[2:3]
	v_cndmask_b32_e32 v170, 0, v223, vcc
	v_sub_f32_e32 v165, v165, v170
	v_pk_add_f32 v[160:161], v[160:161], v[164:165]
	s_nop 0
	v_pk_mul_f32 v[156:157], v[156:157], v[160:161]
	global_store_dwordx4 v158, v[154:157], s[94:95]

.LBB0_500:
	s_andn2_b64 vcc, exec, s[2:3]
	s_cbranch_vccnz .LBB0_502
	v_cndmask_b32_e64 v154, v224, v225, s[16:17]
	v_lshl_add_u32 v154, v166, 6, v154
	v_or_b32_e32 v154, v154, v213
	v_lshlrev_b32_e32 v154, 2, v154
	s_nop 4
	global_store_dwordx4 v154, v[150:153], s[92:93]
	global_store_dwordx4 v154, v[142:145], s[92:93] offset:64
	v_lshl_or_b32 v154, v166, 7, v214
	v_add_u32_e32 v155, 0x23120200, v154
	v_cvt_pk_bf16_f32 v150, v150, v151
	v_cvt_pk_bf16_f32 v151, v152, v153
	v_add_u32_e32 v152, 0x23120220, v154
	global_store_dwordx2 v155, v[150:151], s[94:95]
	v_cvt_pk_bf16_f32 v150, v142, v143
	v_cvt_pk_bf16_f32 v151, v144, v145
	global_store_dwordx2 v152, v[150:151], s[94:95]

.LBB0_509:
	s_nop 0
	v_cvt_pk_bf16_f32 v153, v154, v155
	v_lshlrev_b32_e32 v154, 1, v229
	v_lshl_or_b32 v156, v166, 12, v154
	v_add_u32_e32 v154, s33, v156
	s_and_b64 vcc, exec, s[2:3]
	s_mov_b64 s[2:3], -1
	global_store_dwordx4 v154, v[150:153], s[94:95]
	s_cbranch_vccnz .LBB0_511
	s_nop 0
	v_cvt_pk_bf16_f32 v150, v138, v139
	v_cvt_pk_bf16_f32 v151, v140, v141
	v_cvt_pk_bf16_f32 v152, v134, v135
	s_mov_b64 s[2:3], 0
	v_mov_b32_e32 v155, v137
	v_mov_b32_e32 v154, v136

.LBB0_513:
	s_nop 0
	v_cvt_pk_bf16_f32 v153, v154, v155
	v_add_u32_e32 v154, s2, v156
	v_add_u32_e32 v154, 0x100, v154
	global_store_dwordx4 v154, v[150:153], s[94:95]

.LBB0_516:
	s_andn2_b64 vcc, exec, s[2:3]
	s_cbranch_vccnz .LBB0_531
	s_and_saveexec_b64 s[18:19], s[0:1]
	s_cbranch_execz .LBB0_530
	v_ashrrev_i32_e32 v150, 11, v166
	v_mul_lo_u32 v151, v166, s36
	v_mad_i32_i24 v150, v150, 3, v168
	v_mul_lo_u32 v150, v150, s36
	v_add_u32_e32 v156, v151, v228
	v_cmp_gt_i32_e64 s[2:3], s76, v166
	v_cmp_lt_u32_e32 vcc, s37, v168
	v_add_u32_e32 v150, 0xd88800, v150
	v_cvt_pk_bf16_f32 v152, v146, v147
	v_cvt_pk_bf16_f32 v153, v148, v149
	v_cvt_pk_bf16_f32 v154, v142, v143
	v_cvt_pk_bf16_f32 v155, v144, v145
	v_lshl_add_u32 v156, v156, 1, v226
	global_store_dwordx4 v156, v[152:155], s[94:95]
	s_and_saveexec_b64 s[70:71], s[2:3]
	s_xor_b64 s[70:71], exec, s[70:71]
	s_cbranch_execz .LBB0_522
	s_and_saveexec_b64 s[72:73], vcc
	s_cbranch_execz .LBB0_521
	v_add_lshl_u32 v152, v150, v228, 2
	global_store_dwordx4 v152, v[146:149], s[92:93]
	global_store_dwordx4 v152, v[142:145], s[92:93] offset:16

.LBB0_522:
	s_or_saveexec_b64 s[70:71], s[70:71]
	s_movk_i32 s33, 0x4800
	v_mul_lo_u32 v152, v166, s33
	v_add_u32_e32 v152, 0xf8b9b200, v152
	s_xor_b64 exec, exec, s[70:71]
	s_cbranch_execz .LBB0_524
	v_add_lshl_u32 v153, v152, v228, 2
	global_store_dwordx4 v153, v[146:149], s[92:93]
	global_store_dwordx4 v153, v[142:145], s[92:93] offset:16
.LBB0_524:
	s_or_b64 exec, exec, s[70:71]
	v_or_b32_e32 v153, 0x80, v228
	v_add_u32_e32 v151, v151, v153
	v_cvt_pk_bf16_f32 v154, v138, v139
	v_cvt_pk_bf16_f32 v155, v140, v141
	v_cvt_pk_bf16_f32 v156, v134, v135
	v_cvt_pk_bf16_f32 v157, v136, v137
	v_lshl_add_u32 v151, v151, 1, v226
	global_store_dwordx4 v151, v[154:157], s[94:95]
	s_and_saveexec_b64 s[70:71], s[2:3]
	s_xor_b64 s[2:3], exec, s[70:71]
	s_cbranch_execz .LBB0_528
	s_and_saveexec_b64 s[70:71], vcc
	s_cbranch_execz .LBB0_527
	v_add_lshl_u32 v150, v150, v153, 2
	global_store_dwordx4 v150, v[138:141], s[92:93]
	global_store_dwordx4 v150, v[134:137], s[92:93] offset:16

.LBB0_528:
	s_andn2_saveexec_b64 s[2:3], s[2:3]
	s_cbranch_execz .LBB0_530
	v_add_lshl_u32 v150, v152, v153, 2
	global_store_dwordx4 v150, v[138:141], s[92:93]
	global_store_dwordx4 v150, v[134:137], s[92:93] offset:16

.LBB0_532:
	s_andn2_b64 vcc, exec, s[2:3]
	s_cbranch_vccnz .LBB0_551
	v_lshl_or_b32 v186, v167, 6, v209
	v_cndmask_b32_e64 v150, 0, 1, s[6:7]
	v_cmp_ne_u32_e64 s[18:19], 1, v150
	v_lshl_add_u64 v[160:161], s[94:95], 0, v[186:187]
	s_andn2_b64 vcc, exec, s[6:7]
	v_lshl_add_u64 v[158:159], v[160:161], 0, s[44:45]
	s_cbranch_vccnz .LBB0_535
	v_add_co_u32_e32 v150, vcc, 0x140000, v160
	ds_bpermute_b32 v162, v218, v146
	s_nop 0
	v_addc_co_u32_e32 v151, vcc, 0, v161, vcc
	global_load_dwordx4 v[150:153], v[150:151], off offset:256
	s_nop 0
	global_load_dwordx4 v[154:157], v[158:159], off offset:16
	ds_bpermute_b32 v163, v218, v147
	s_waitcnt vmcnt(0)
	v_mov_b32_e32 v165, v152
	v_mov_b32_e32 v152, v151
	v_mov_b32_e32 v164, v150
	s_waitcnt lgkmcnt(0)
	v_pk_mul_f32 v[150:151], v[152:153], v[162:163]
	ds_bpermute_b32 v152, v218, v148
	ds_bpermute_b32 v153, v218, v149
	v_mov_b32_e32 v163, v156
	v_mov_b32_e32 v156, v155
	v_cndmask_b32_e64 v151, v151, -v151, s[4:5]
	v_cndmask_b32_e64 v150, v150, -v150, s[4:5]
	s_waitcnt lgkmcnt(0)
	v_pk_mul_f32 v[152:153], v[156:157], v[152:153]
	v_mov_b32_e32 v162, v154
	v_cndmask_b32_e64 v153, v153, -v153, s[4:5]
	v_cndmask_b32_e64 v152, v152, -v152, s[4:5]
	v_pk_fma_f32 v[150:151], v[146:147], v[164:165], v[150:151]
	v_pk_fma_f32 v[152:153], v[148:149], v[162:163], v[152:153]
	s_branch .LBB0_536

.LBB0_536:
	v_lshlrev_b32_e32 v154, 10, v166
	v_or_b32_e32 v163, v154, v215
	v_cmp_lt_i32_e64 s[2:3], s26, v166
	v_add_u32_e32 v162, v154, v216
	s_and_saveexec_b64 s[70:71], s[0:1]
	s_cbranch_execz .LBB0_541
	s_lshl_b32 s33, s97, 6
	v_add_lshl_u32 v164, v163, s33, 1
	v_add_u32_e32 v165, 0x220a0200, v164
	v_cvt_pk_bf16_f32 v154, v150, v151
	v_cvt_pk_bf16_f32 v155, v152, v153
	s_mov_b64 s[72:73], -1
	s_andn2_b64 vcc, exec, s[40:41]
	v_cvt_pk_bf16_f32 v156, v142, v143
	v_cvt_pk_bf16_f32 v157, v144, v145
	s_cbranch_vccnz .LBB0_543
	global_store_dwordx4 v165, v[154:157], s[94:95]
	s_cbranch_execz .LBB0_544

.LBB0_540:
	v_add_u32_e32 v154, s33, v162
	v_lshl_add_u32 v186, v154, 2, v227
	v_lshl_add_u64 v[154:155], s[94:95], 0, v[186:187]
	v_lshl_add_u64 v[154:155], v[154:155], 0, s[24:25]
	global_store_dwordx4 v186, v[150:153], s[94:95]
	global_store_dwordx4 v[154:155], v[142:145], off

.LBB0_544:
	global_store_dwordx2 v165, v[154:155], s[94:95]
	v_add_u32_e32 v154, 0x220a0220, v164
	global_store_dwordx2 v154, v[156:157], s[94:95]
	s_and_b64 exec, exec, s[2:3]
	s_cbranch_execnz .LBB0_540
	s_branch .LBB0_541

.LBB0_546:
	s_lshl_b32 s33, s97, 6
	s_bitset1_b32 s33, 7
	v_add_lshl_u32 v158, v163, s33, 1
	v_add_u32_e32 v159, 0x220a0200, v158
	v_cvt_pk_bf16_f32 v154, v150, v151
	v_cvt_pk_bf16_f32 v155, v152, v153
	s_mov_b64 s[70:71], -1
	s_andn2_b64 vcc, exec, s[40:41]
	v_cvt_pk_bf16_f32 v156, v134, v135
	v_cvt_pk_bf16_f32 v157, v136, v137
	s_cbranch_vccnz .LBB0_588
	global_store_dwordx4 v159, v[154:157], s[94:95]
	s_cbranch_execz .LBB0_589

.LBB0_549:
	v_add_u32_e32 v154, s33, v162
	v_lshl_add_u32 v186, v154, 2, v227
	v_lshl_add_u64 v[154:155], s[94:95], 0, v[186:187]
	v_lshl_add_u64 v[154:155], v[154:155], 0, s[24:25]
	global_store_dwordx4 v186, v[150:153], s[94:95]
	global_store_dwordx4 v[154:155], v[134:137], off

.LBB0_552:
	s_andn2_b64 vcc, exec, s[2:3]
	s_cbranch_vccnz .LBB0_582
	v_lshl_or_b32 v186, v167, 7, v208
	s_and_b64 vcc, exec, s[10:11]
	v_lshl_add_u64 v[154:155], s[94:95], 0, v[186:187]
	v_lshl_add_u64 v[156:157], v[154:155], 0, s[48:49]
	s_cbranch_vccnz .LBB0_555
	global_load_dwordx4 v[150:153], v[156:157], off offset:16
	v_add_co_u32_e32 v158, vcc, 0x100000, v154
	s_nop 1
	v_addc_co_u32_e32 v159, vcc, 0, v155, vcc
	global_load_dwordx4 v[158:161], v[158:159], off
	s_waitcnt vmcnt(0)
	v_mul_f32_e32 v162, v148, v150
	v_mul_f32_e32 v168, v148, v151
	v_mov_b32_e32 v148, v145
	v_mul_f32_e32 v164, v144, v151
	v_mul_f32_e32 v150, v144, v150
	v_mov_b32_e32 v144, v149
	v_pk_mul_f32 v[148:149], v[148:149], v[152:153]
	v_pk_mul_f32 v[144:145], v[144:145], v[152:153]
	v_mov_b32_e32 v151, v148
	v_mov_b32_e32 v169, v149
	v_mov_b32_e32 v153, v160
	v_mov_b32_e32 v160, v159
	v_mov_b32_e32 v163, v144
	v_mov_b32_e32 v165, v145
	v_mov_b32_e32 v152, v158
	v_pk_add_f32 v[144:145], v[150:151], v[168:169]
	v_pk_mul_f32 v[150:151], v[142:143], v[160:161]
	v_pk_mul_f32 v[158:159], v[146:147], v[160:161]
	v_pk_add_f32 v[148:149], v[162:163], v[164:165] neg_lo:[0,1] neg_hi:[0,1]
	v_pk_fma_f32 v[146:147], v[146:147], v[152:153], v[150:151] neg_lo:[0,0,1] neg_hi:[0,0,1]
	v_pk_fma_f32 v[142:143], v[142:143], v[152:153], v[158:159]
.LBB0_555:
	v_lshlrev_b32_e32 v150, 9, v166
	v_add_u32_e32 v159, s55, v150
	v_add_u32_e32 v160, s96, v150
	v_or_b32_e32 v158, v150, v176
	s_and_saveexec_b64 s[2:3], s[0:1]
	s_cbranch_execz .LBB0_567
	s_andn2_b64 vcc, exec, s[60:61]
	s_mov_b64 s[18:19], -1
	s_cbranch_vccnz .LBB0_562
	v_cndmask_b32_e64 v150, v159, v160, s[16:17]
	s_lshl_b32 s18, s87, 7
	v_or3_b32 v150, v176, v150, s18
	v_lshlrev_b32_e32 v151, 2, v150
	v_add_lshl_u32 v150, v150, s53, 2
	s_andn2_b64 vcc, exec, s[64:65]
	v_cvt_pk_bf16_f32 v152, v142, v143
	v_cvt_pk_bf16_f32 v153, v144, v145
	global_store_dwordx4 v151, v[146:149], s[92:93]
	global_store_dwordx4 v150, v[142:145], s[92:93]
	v_or_b32_e32 v150, s18, v158
	v_lshl_add_u32 v161, v150, 1, s23
	v_cvt_pk_bf16_f32 v150, v146, v147
	v_cvt_pk_bf16_f32 v151, v148, v149
	s_mov_b64 s[18:19], -1
	s_cbranch_vccnz .LBB0_559
	s_mov_b64 s[18:19], 0
	global_store_dwordx4 v161, v[150:153], s[94:95]
.LBB0_559:
	s_andn2_b64 vcc, exec, s[18:19]
	s_cbranch_vccnz .LBB0_561
	global_store_dwordx2 v161, v[150:151], s[94:95]
	v_add_u32_e32 v150, 32, v161
	global_store_dwordx2 v150, v[152:153], s[94:95]

.LBB0_562:
	s_andn2_b64 vcc, exec, s[18:19]
	s_cbranch_vccnz .LBB0_567
	s_lshl_b32 s18, s22, 9
	v_lshl_or_b32 v150, v176, 1, s18
	v_lshl_add_u32 v150, v166, 12, v150
	v_pk_mul_f32 v[148:149], v[148:149], s[50:51] op_sel_hi:[1,0]
	v_pk_mul_f32 v[146:147], v[146:147], s[50:51] op_sel_hi:[1,0]
	v_add_u32_e32 v151, 0x1ef20200, v150
	v_cvt_pk_bf16_f32 v146, v146, v147
	v_cvt_pk_bf16_f32 v147, v148, v149
	s_andn2_b64 vcc, exec, s[64:65]
	s_mov_b64 s[18:19], -1
	s_cbranch_vccnz .LBB0_565
	v_pk_mul_f32 v[152:153], v[144:145], s[50:51] op_sel_hi:[1,0]
	v_pk_mul_f32 v[148:149], v[142:143], s[50:51] op_sel_hi:[1,0]
	v_cvt_pk_bf16_f32 v148, v148, v149
	v_cvt_pk_bf16_f32 v149, v152, v153
	s_mov_b64 s[18:19], 0
	global_store_dwordx4 v151, v[146:149], s[94:95]
.LBB0_565:
	s_andn2_b64 vcc, exec, s[18:19]
	s_cbranch_vccnz .LBB0_567
	v_pk_mul_f32 v[144:145], v[144:145], s[50:51] op_sel_hi:[1,0]
	v_pk_mul_f32 v[142:143], v[142:143], s[50:51] op_sel_hi:[1,0]
	v_cvt_pk_bf16_f32 v142, v142, v143
	v_cvt_pk_bf16_f32 v143, v144, v145
	v_add_u32_e32 v144, 0x1ef20220, v150
	global_store_dwordx2 v151, v[146:147], s[94:95]
	global_store_dwordx2 v144, v[142:143], s[94:95]

.LBB0_569:
	s_and_saveexec_b64 s[2:3], s[0:1]
	s_cbranch_execz .LBB0_581
	s_andn2_b64 vcc, exec, s[60:61]
	s_mov_b64 s[0:1], -1
	s_cbranch_vccnz .LBB0_576
	s_lshl_b32 s0, s87, 7
	v_cndmask_b32_e64 v142, v159, v160, s[16:17]
	s_bitset1_b32 s0, 7
	v_or3_b32 v142, v176, v142, s0
	v_lshlrev_b32_e32 v143, 2, v142
	v_add_lshl_u32 v142, v142, s53, 2
	s_andn2_b64 vcc, exec, s[64:65]
	v_cvt_pk_bf16_f32 v144, v134, v135
	v_cvt_pk_bf16_f32 v145, v136, v137
	global_store_dwordx4 v143, v[138:141], s[92:93]
	global_store_dwordx4 v142, v[134:137], s[92:93]
	v_or_b32_e32 v142, s0, v158
	v_lshl_add_u32 v146, v142, 1, s23
	v_cvt_pk_bf16_f32 v142, v138, v139
	v_cvt_pk_bf16_f32 v143, v140, v141
	s_mov_b64 s[0:1], -1
	s_cbranch_vccnz .LBB0_573
	s_mov_b64 s[0:1], 0
	global_store_dwordx4 v146, v[142:145], s[94:95]
.LBB0_573:
	s_andn2_b64 vcc, exec, s[0:1]
	s_cbranch_vccnz .LBB0_575
	global_store_dwordx2 v146, v[142:143], s[94:95]
	v_add_u32_e32 v142, 32, v146
	global_store_dwordx2 v142, v[144:145], s[94:95]

.LBB0_576:
	s_andn2_b64 vcc, exec, s[0:1]
	s_cbranch_vccnz .LBB0_581
	s_lshl_b32 s0, s22, 9
	v_lshl_or_b32 v142, v176, 1, s0
	v_lshl_add_u32 v142, v166, 12, v142
	v_pk_mul_f32 v[140:141], v[140:141], s[50:51] op_sel_hi:[1,0]
	v_pk_mul_f32 v[138:139], v[138:139], s[50:51] op_sel_hi:[1,0]
	v_add_u32_e32 v143, 0x1ef20300, v142
	v_cvt_pk_bf16_f32 v138, v138, v139
	v_cvt_pk_bf16_f32 v139, v140, v141
	s_andn2_b64 vcc, exec, s[64:65]
	s_mov_b64 s[0:1], -1
	s_cbranch_vccnz .LBB0_579
	v_pk_mul_f32 v[144:145], v[136:137], s[50:51] op_sel_hi:[1,0]
	v_pk_mul_f32 v[140:141], v[134:135], s[50:51] op_sel_hi:[1,0]
	v_cvt_pk_bf16_f32 v140, v140, v141
	v_cvt_pk_bf16_f32 v141, v144, v145
	s_mov_b64 s[0:1], 0
	global_store_dwordx4 v143, v[138:141], s[94:95]
.LBB0_579:
	s_andn2_b64 vcc, exec, s[0:1]
	s_cbranch_vccnz .LBB0_581
	v_pk_mul_f32 v[136:137], v[136:137], s[50:51] op_sel_hi:[1,0]
	v_pk_mul_f32 v[134:135], v[134:135], s[50:51] op_sel_hi:[1,0]
	v_cvt_pk_bf16_f32 v134, v134, v135
	v_cvt_pk_bf16_f32 v135, v136, v137
	v_add_u32_e32 v136, 0x1ef20320, v142
	global_store_dwordx2 v143, v[138:139], s[94:95]
	global_store_dwordx2 v136, v[134:135], s[94:95]

.LBB0_589:
	global_store_dwordx2 v159, v[154:155], s[94:95]
	v_add_u32_e32 v154, 0x220a0220, v158
	global_store_dwordx2 v154, v[156:157], s[94:95]
	s_and_b64 exec, exec, s[2:3]
	s_cbranch_execnz .LBB0_549
	s_branch .LBB0_550
.LBB0_590:
	v_lshl_or_b32 v186, v149, 6, v209
	v_lshl_add_u64 v[114:115], s[94:95], 0, v[186:187]
	v_lshl_add_u64 v[138:139], v[114:115], 0, s[44:45]
	v_add_co_u32_e32 v114, vcc, 0x140000, v114
	s_nop 0
	s_nop 0
	v_addc_co_u32_e32 v115, vcc, 0, v115, vcc
	global_load_dwordx4 v[134:137], v[114:115], off offset:256
	s_nop 0
	global_load_dwordx4 v[138:141], v[138:139], off offset:16
	ds_bpermute_b32 v114, v218, v130
	ds_bpermute_b32 v115, v218, v131
	s_waitcnt vmcnt(0)
	v_mov_b32_e32 v143, v136
	v_mov_b32_e32 v136, v135
	s_waitcnt lgkmcnt(0)
	v_pk_mul_f32 v[114:115], v[136:137], v[114:115]
	v_mov_b32_e32 v142, v134
	v_cndmask_b32_e64 v115, v115, -v115, s[4:5]
	v_cndmask_b32_e64 v114, v114, -v114, s[4:5]
	v_pk_fma_f32 v[134:135], v[130:131], v[142:143], v[114:115]
	ds_bpermute_b32 v114, v218, v132
	ds_bpermute_b32 v115, v218, v133
	v_mov_b32_e32 v137, v140
	v_mov_b32_e32 v140, v139
	v_mov_b32_e32 v136, v138
	s_waitcnt lgkmcnt(0)
	v_pk_mul_f32 v[114:115], v[140:141], v[114:115]
	s_nop 0
	v_cndmask_b32_e64 v115, v115, -v115, s[4:5]
	v_cndmask_b32_e64 v114, v114, -v114, s[4:5]
	v_pk_fma_f32 v[136:137], v[132:133], v[136:137], v[114:115]
	s_and_saveexec_b64 s[18:19], s[0:1]
	s_cbranch_execz .LBB0_599
.LBB0_591:
	v_readlane_b32 s2, v254, 18
	v_readlane_b32 s3, v254, 19
	s_andn2_b64 vcc, exec, s[2:3]
	s_mov_b64 s[2:3], -1
	s_cbranch_vccnz .LBB0_597
	v_readlane_b32 s2, v254, 20
	v_readlane_b32 s3, v254, 21
	s_andn2_b64 vcc, exec, s[2:3]
	s_mov_b64 s[2:3], -1
	s_cbranch_vccnz .LBB0_594
	v_mul_f32_e32 v114, 0xbfb8aa3b, v134
	v_exp_f32_e32 v114, v114
	v_mul_f32_e32 v115, 0xbfb8aa3b, v135
	v_mul_f32_e32 v139, 0xbfb8aa3b, v137
	v_exp_f32_e32 v115, v115
	v_add_f32_e32 v114, 1.0, v114
	v_rcp_f32_e32 v138, v114
	v_mul_f32_e32 v114, 0xbfb8aa3b, v136
	v_exp_f32_e32 v114, v114
	v_exp_f32_e32 v141, v139
	v_add_f32_e32 v115, 1.0, v115
	v_rcp_f32_e32 v139, v115
	v_add_f32_e32 v114, 1.0, v114
	v_rcp_f32_e32 v140, v114
	v_add_f32_e32 v114, 1.0, v141
	v_rcp_f32_e32 v141, v114
	v_lshl_add_u32 v114, v148, 6, v252
	s_mov_b64 s[2:3], 0
	global_store_dwordx4 v114, v[138:141], s[94:95]
.LBB0_594:
	s_andn2_b64 vcc, exec, s[2:3]
	s_cbranch_vccnz .LBB0_596
	s_mov_b32 s2, 0x3d000000
	v_lshl_or_b32 v151, v148, 6, v203
	v_pk_mul_f32 v[140:141], v[136:137], s[2:3] op_sel_hi:[1,0]
	v_pk_mul_f32 v[138:139], v[134:135], s[2:3] op_sel_hi:[1,0]
	v_add_u32_e32 v114, 0x23230200, v151
	s_mov_b32 s33, 0x800000
	s_mov_b32 s70, 0x3f317217
	global_store_dwordx4 v114, v[138:141], s[94:95]
	v_or_b32_e32 v114, 0x6c000, v203
	global_load_dwordx4 v[138:141], v114, s[94:95]
	global_load_dwordx4 v[142:145], v114, s[94:95] offset:64
	s_waitcnt vmcnt(0)
	v_add_f32_e32 v115, v126, v142
	v_max_f32_e32 v114, 0, v115
	v_mul_f32_e64 v115, |v115|, s27
	v_exp_f32_e32 v115, v115
	v_add_f32_e32 v143, v127, v143
	v_add_f32_e32 v115, 1.0, v115
	v_cmp_gt_f32_e32 vcc, s33, v115
	s_nop 1
	v_cndmask_b32_e64 v142, 0, 32, vcc
	v_ldexp_f32 v115, v115, v142
	v_log_f32_e32 v115, v115
	s_nop 0
	v_mul_f32_e32 v142, 0x3f317217, v115
	v_fma_f32 v142, v115, s70, -v142
	v_fmac_f32_e32 v142, 0x3377d1cf, v115
	v_fmac_f32_e32 v142, 0x3f317217, v115
	v_cmp_lt_f32_e64 s[2:3], |v115|, s39
	s_nop 1
	v_cndmask_b32_e64 v115, v115, v142, s[2:3]
	v_cndmask_b32_e32 v142, 0, v223, vcc
	v_sub_f32_e32 v142, v115, v142
	v_max_f32_e32 v115, 0, v143
	v_mul_f32_e64 v143, |v143|, s27
	v_exp_f32_e32 v143, v143
	s_nop 0
	v_add_f32_e32 v143, 1.0, v143
	v_cmp_gt_f32_e32 vcc, s33, v143
	s_nop 1
	v_cndmask_b32_e64 v146, 0, 32, vcc
	v_ldexp_f32 v143, v143, v146
	v_log_f32_e32 v143, v143
	s_nop 0
	v_mul_f32_e32 v146, 0x3f317217, v143
	v_fma_f32 v146, v143, s70, -v146
	v_fmac_f32_e32 v146, 0x3377d1cf, v143
	v_fmac_f32_e32 v146, 0x3f317217, v143
	v_cmp_lt_f32_e64 s[2:3], |v143|, s39
	s_nop 1
	v_cndmask_b32_e64 v143, v143, v146, s[2:3]
	v_cndmask_b32_e32 v146, 0, v223, vcc
	v_sub_f32_e32 v143, v143, v146
	v_add_f32_e32 v146, v128, v144
	v_max_f32_e32 v144, 0, v146
	v_mul_f32_e64 v146, |v146|, s27
	v_exp_f32_e32 v146, v146
	v_pk_add_f32 v[114:115], v[114:115], v[142:143]
	v_add_f32_e32 v146, 1.0, v146
	v_cmp_gt_f32_e32 vcc, s33, v146
	v_pk_mul_f32 v[138:139], v[138:139], v[114:115]
	v_add_u32_e32 v114, 0x232b4200, v151
	v_cndmask_b32_e64 v147, 0, 32, vcc
	v_ldexp_f32 v146, v146, v147
	v_log_f32_e32 v146, v146
	s_nop 0
	v_mul_f32_e32 v147, 0x3f317217, v146
	v_fma_f32 v147, v146, s70, -v147
	v_fmac_f32_e32 v147, 0x3377d1cf, v146
	v_fmac_f32_e32 v147, 0x3f317217, v146
	v_cmp_lt_f32_e64 s[2:3], |v146|, s39
	s_nop 1
	v_cndmask_b32_e64 v146, v146, v147, s[2:3]
	v_cndmask_b32_e32 v147, 0, v223, vcc
	v_sub_f32_e32 v146, v146, v147
	v_add_f32_e32 v147, v129, v145
	v_max_f32_e32 v145, 0, v147
	v_mul_f32_e64 v147, |v147|, s27
	v_exp_f32_e32 v147, v147
	s_nop 0
	v_add_f32_e32 v147, 1.0, v147
	v_cmp_gt_f32_e32 vcc, s33, v147
	s_nop 1
	v_cndmask_b32_e64 v152, 0, 32, vcc
	v_ldexp_f32 v147, v147, v152
	v_log_f32_e32 v147, v147
	s_nop 0
	v_mul_f32_e32 v152, 0x3f317217, v147
	v_fma_f32 v152, v147, s70, -v152
	v_fmac_f32_e32 v152, 0x3377d1cf, v147
	v_fmac_f32_e32 v152, 0x3f317217, v147
	v_cmp_lt_f32_e64 s[2:3], |v147|, s39
	s_nop 1
	v_cndmask_b32_e64 v147, v147, v152, s[2:3]
	v_cndmask_b32_e32 v152, 0, v223, vcc
	v_sub_f32_e32 v147, v147, v152
	v_pk_add_f32 v[142:143], v[144:145], v[146:147]
	s_nop 0
	v_pk_mul_f32 v[140:141], v[140:141], v[142:143]
	global_store_dwordx4 v114, v[138:141], s[94:95]

.LBB0_597:
	s_andn2_b64 vcc, exec, s[2:3]
	s_cbranch_vccnz .LBB0_599
	v_cndmask_b32_e64 v114, v224, v225, s[16:17]
	v_lshl_add_u32 v114, v148, 6, v114
	v_or_b32_e32 v114, v114, v213
	v_lshlrev_b32_e32 v114, 2, v114
	v_lshl_or_b32 v138, v148, 7, v214
	s_nop 1
	global_store_dwordx4 v114, v[134:137], s[92:93]
	global_store_dwordx4 v114, v[126:129], s[92:93] offset:64
	v_add_u32_e32 v139, 0x23120200, v138
	v_cvt_pk_bf16_f32 v114, v134, v135
	v_cvt_pk_bf16_f32 v115, v136, v137
	global_store_dwordx2 v139, v[114:115], s[94:95]
	v_cvt_pk_bf16_f32 v114, v126, v127
	v_cvt_pk_bf16_f32 v115, v128, v129
	v_add_u32_e32 v134, 0x23120220, v138
	global_store_dwordx2 v134, v[114:115], s[94:95]

.LBB0_606:
	s_nop 0
	v_cvt_pk_bf16_f32 v137, v114, v115
	v_lshlrev_b32_e32 v114, 1, v229
	v_lshl_or_b32 v138, v148, 12, v114
	v_add_u32_e32 v114, s33, v138
	s_and_b64 vcc, exec, s[2:3]
	s_mov_b64 s[2:3], -1
	global_store_dwordx4 v114, v[134:137], s[94:95]
	s_cbranch_vccnz .LBB0_608
	s_nop 0
	v_cvt_pk_bf16_f32 v134, v122, v123
	v_cvt_pk_bf16_f32 v135, v124, v125
	v_cvt_pk_bf16_f32 v136, v118, v119
	s_mov_b64 s[2:3], 0
	v_mov_b32_e32 v115, v121
	v_mov_b32_e32 v114, v120

.LBB0_610:
	s_nop 0
	v_cvt_pk_bf16_f32 v137, v114, v115
	v_add_u32_e32 v114, s2, v138
	v_add_u32_e32 v114, 0x100, v114
	global_store_dwordx4 v114, v[134:137], s[94:95]

.LBB0_613:
	s_andn2_b64 vcc, exec, s[2:3]
	s_cbranch_vccnz .LBB0_628
	s_and_saveexec_b64 s[18:19], s[0:1]
	s_cbranch_execz .LBB0_627
	v_ashrrev_i32_e32 v114, 11, v148
	v_mul_lo_u32 v115, v148, s36
	v_mad_i32_i24 v114, v114, 3, v150
	v_mul_lo_u32 v114, v114, s36
	v_add_u32_e32 v138, v115, v228
	v_cmp_gt_i32_e64 s[2:3], s76, v148
	v_cmp_lt_u32_e32 vcc, s37, v150
	v_add_u32_e32 v114, 0xd88800, v114
	v_cvt_pk_bf16_f32 v134, v130, v131
	v_cvt_pk_bf16_f32 v135, v132, v133
	v_cvt_pk_bf16_f32 v136, v126, v127
	v_cvt_pk_bf16_f32 v137, v128, v129
	v_lshl_add_u32 v138, v138, 1, v226
	global_store_dwordx4 v138, v[134:137], s[94:95]
	s_and_saveexec_b64 s[70:71], s[2:3]
	s_xor_b64 s[70:71], exec, s[70:71]
	s_cbranch_execz .LBB0_619
	s_and_saveexec_b64 s[72:73], vcc
	s_cbranch_execz .LBB0_618
	v_add_lshl_u32 v134, v114, v228, 2
	global_store_dwordx4 v134, v[130:133], s[92:93]
	global_store_dwordx4 v134, v[126:129], s[92:93] offset:16

.LBB0_619:
	s_or_saveexec_b64 s[70:71], s[70:71]
	s_movk_i32 s33, 0x4800
	v_mul_lo_u32 v134, v148, s33
	v_add_u32_e32 v134, 0xf8b9b200, v134
	s_xor_b64 exec, exec, s[70:71]
	s_cbranch_execz .LBB0_621
	v_add_lshl_u32 v135, v134, v228, 2
	global_store_dwordx4 v135, v[130:133], s[92:93]
	global_store_dwordx4 v135, v[126:129], s[92:93] offset:16
.LBB0_621:
	s_or_b64 exec, exec, s[70:71]
	v_or_b32_e32 v135, 0x80, v228
	v_add_u32_e32 v115, v115, v135
	v_cvt_pk_bf16_f32 v136, v122, v123
	v_cvt_pk_bf16_f32 v137, v124, v125
	v_cvt_pk_bf16_f32 v138, v118, v119
	v_cvt_pk_bf16_f32 v139, v120, v121
	v_lshl_add_u32 v115, v115, 1, v226
	global_store_dwordx4 v115, v[136:139], s[94:95]
	s_and_saveexec_b64 s[70:71], s[2:3]
	s_xor_b64 s[2:3], exec, s[70:71]
	s_cbranch_execz .LBB0_625
	s_and_saveexec_b64 s[70:71], vcc
	s_cbranch_execz .LBB0_624
	v_add_lshl_u32 v114, v114, v135, 2
	global_store_dwordx4 v114, v[122:125], s[92:93]
	global_store_dwordx4 v114, v[118:121], s[92:93] offset:16

.LBB0_625:
	s_andn2_saveexec_b64 s[2:3], s[2:3]
	s_cbranch_execz .LBB0_627
	v_add_lshl_u32 v114, v134, v135, 2
	global_store_dwordx4 v114, v[122:125], s[92:93]
	global_store_dwordx4 v114, v[118:121], s[92:93] offset:16

.LBB0_629:
	s_andn2_b64 vcc, exec, s[2:3]
	s_cbranch_vccnz .LBB0_648
	v_lshl_or_b32 v186, v149, 6, v209
	v_cndmask_b32_e64 v114, 0, 1, s[6:7]
	v_cmp_ne_u32_e64 s[18:19], 1, v114
	v_lshl_add_u64 v[142:143], s[94:95], 0, v[186:187]
	s_andn2_b64 vcc, exec, s[6:7]
	v_lshl_add_u64 v[114:115], v[142:143], 0, s[44:45]
	s_cbranch_vccnz .LBB0_632
	v_add_co_u32_e32 v134, vcc, 0x140000, v142
	ds_bpermute_b32 v144, v218, v130
	s_nop 0
	v_addc_co_u32_e32 v135, vcc, 0, v143, vcc
	global_load_dwordx4 v[134:137], v[134:135], off offset:256
	s_nop 0
	global_load_dwordx4 v[138:141], v[114:115], off offset:16
	ds_bpermute_b32 v145, v218, v131
	s_waitcnt vmcnt(0)
	v_mov_b32_e32 v147, v136
	v_mov_b32_e32 v136, v135
	v_mov_b32_e32 v146, v134
	s_waitcnt lgkmcnt(0)
	v_pk_mul_f32 v[134:135], v[136:137], v[144:145]
	ds_bpermute_b32 v136, v218, v132
	ds_bpermute_b32 v137, v218, v133
	v_mov_b32_e32 v145, v140
	v_mov_b32_e32 v140, v139
	v_cndmask_b32_e64 v135, v135, -v135, s[4:5]
	v_cndmask_b32_e64 v134, v134, -v134, s[4:5]
	s_waitcnt lgkmcnt(0)
	v_pk_mul_f32 v[136:137], v[140:141], v[136:137]
	v_mov_b32_e32 v144, v138
	v_cndmask_b32_e64 v137, v137, -v137, s[4:5]
	v_cndmask_b32_e64 v136, v136, -v136, s[4:5]
	v_pk_fma_f32 v[134:135], v[130:131], v[146:147], v[134:135]
	v_pk_fma_f32 v[136:137], v[132:133], v[144:145], v[136:137]
	s_branch .LBB0_633

.LBB0_633:
	v_lshlrev_b32_e32 v138, 10, v148
	v_or_b32_e32 v145, v138, v215
	v_cmp_lt_i32_e64 s[2:3], s26, v148
	v_add_u32_e32 v144, v138, v216
	s_and_saveexec_b64 s[70:71], s[0:1]
	s_cbranch_execz .LBB0_638
	s_lshl_b32 s33, s97, 6
	v_add_lshl_u32 v146, v145, s33, 1
	v_add_u32_e32 v147, 0x220a0200, v146
	v_cvt_pk_bf16_f32 v138, v134, v135
	v_cvt_pk_bf16_f32 v139, v136, v137
	s_mov_b64 s[72:73], -1
	s_andn2_b64 vcc, exec, s[40:41]
	v_cvt_pk_bf16_f32 v140, v126, v127
	v_cvt_pk_bf16_f32 v141, v128, v129
	s_cbranch_vccnz .LBB0_640
	global_store_dwordx4 v147, v[138:141], s[94:95]
	s_cbranch_execz .LBB0_641

.LBB0_637:
	v_add_u32_e32 v138, s33, v144
	v_lshl_add_u32 v186, v138, 2, v227
	v_lshl_add_u64 v[138:139], s[94:95], 0, v[186:187]
	v_lshl_add_u64 v[138:139], v[138:139], 0, s[24:25]
	global_store_dwordx4 v186, v[134:137], s[94:95]
	global_store_dwordx4 v[138:139], v[126:129], off

.LBB0_641:
	global_store_dwordx2 v147, v[138:139], s[94:95]
	v_add_u32_e32 v138, 0x220a0220, v146
	global_store_dwordx2 v138, v[140:141], s[94:95]
	s_and_b64 exec, exec, s[2:3]
	s_cbranch_execnz .LBB0_637
	s_branch .LBB0_638

.LBB0_643:
	s_lshl_b32 s33, s97, 6
	s_bitset1_b32 s33, 7
	v_add_lshl_u32 v114, v145, s33, 1
	v_add_u32_e32 v115, 0x220a0200, v114
	v_cvt_pk_bf16_f32 v138, v134, v135
	v_cvt_pk_bf16_f32 v139, v136, v137
	s_mov_b64 s[70:71], -1
	s_andn2_b64 vcc, exec, s[40:41]
	v_cvt_pk_bf16_f32 v140, v118, v119
	v_cvt_pk_bf16_f32 v141, v120, v121
	s_cbranch_vccnz .LBB0_685
	global_store_dwordx4 v115, v[138:141], s[94:95]
	s_cbranch_execz .LBB0_686

.LBB0_646:
	v_add_u32_e32 v114, s33, v144
	v_lshl_add_u32 v186, v114, 2, v227
	v_lshl_add_u64 v[114:115], s[94:95], 0, v[186:187]
	v_lshl_add_u64 v[114:115], v[114:115], 0, s[24:25]
	global_store_dwordx4 v186, v[134:137], s[94:95]
	global_store_dwordx4 v[114:115], v[118:121], off

.LBB0_649:
	s_andn2_b64 vcc, exec, s[2:3]
	s_cbranch_vccnz .LBB0_679
	v_lshl_or_b32 v186, v149, 7, v208
	s_and_b64 vcc, exec, s[10:11]
	v_lshl_add_u64 v[114:115], s[94:95], 0, v[186:187]
	v_lshl_add_u64 v[138:139], v[114:115], 0, s[48:49]
	s_cbranch_vccnz .LBB0_652
	global_load_dwordx4 v[134:137], v[138:139], off offset:16
	v_add_co_u32_e32 v140, vcc, 0x100000, v114
	s_nop 1
	v_addc_co_u32_e32 v141, vcc, 0, v115, vcc
	global_load_dwordx4 v[140:143], v[140:141], off
	s_waitcnt vmcnt(0)
	v_mul_f32_e32 v144, v132, v134
	v_mul_f32_e32 v150, v132, v135
	v_mov_b32_e32 v132, v129
	v_mul_f32_e32 v146, v128, v135
	v_mul_f32_e32 v134, v128, v134
	v_mov_b32_e32 v128, v133
	v_pk_mul_f32 v[132:133], v[132:133], v[136:137]
	v_pk_mul_f32 v[128:129], v[128:129], v[136:137]
	v_mov_b32_e32 v135, v132
	v_mov_b32_e32 v151, v133
	v_mov_b32_e32 v137, v142
	v_mov_b32_e32 v142, v141
	v_mov_b32_e32 v145, v128
	v_mov_b32_e32 v147, v129
	v_mov_b32_e32 v136, v140
	v_pk_add_f32 v[128:129], v[134:135], v[150:151]
	v_pk_mul_f32 v[134:135], v[126:127], v[142:143]
	v_pk_mul_f32 v[140:141], v[130:131], v[142:143]
	v_pk_add_f32 v[132:133], v[144:145], v[146:147] neg_lo:[0,1] neg_hi:[0,1]
	v_pk_fma_f32 v[130:131], v[130:131], v[136:137], v[134:135] neg_lo:[0,0,1] neg_hi:[0,0,1]
	v_pk_fma_f32 v[126:127], v[126:127], v[136:137], v[140:141]
.LBB0_652:
	v_lshlrev_b32_e32 v134, 9, v148
	v_add_u32_e32 v141, s55, v134
	v_add_u32_e32 v142, s96, v134
	v_or_b32_e32 v140, v134, v176
	s_and_saveexec_b64 s[2:3], s[0:1]
	s_cbranch_execz .LBB0_664
	s_andn2_b64 vcc, exec, s[60:61]
	s_mov_b64 s[18:19], -1
	s_cbranch_vccnz .LBB0_659
	v_cndmask_b32_e64 v134, v141, v142, s[16:17]
	s_lshl_b32 s18, s87, 7
	v_or3_b32 v134, v176, v134, s18
	v_lshlrev_b32_e32 v135, 2, v134
	v_add_lshl_u32 v134, v134, s53, 2
	s_andn2_b64 vcc, exec, s[64:65]
	v_cvt_pk_bf16_f32 v136, v126, v127
	v_cvt_pk_bf16_f32 v137, v128, v129
	global_store_dwordx4 v135, v[130:133], s[92:93]
	global_store_dwordx4 v134, v[126:129], s[92:93]
	v_or_b32_e32 v134, s18, v140
	v_lshl_add_u32 v143, v134, 1, s23
	v_cvt_pk_bf16_f32 v134, v130, v131
	v_cvt_pk_bf16_f32 v135, v132, v133
	s_mov_b64 s[18:19], -1
	s_cbranch_vccnz .LBB0_656
	s_mov_b64 s[18:19], 0
	global_store_dwordx4 v143, v[134:137], s[94:95]
.LBB0_656:
	s_andn2_b64 vcc, exec, s[18:19]
	s_cbranch_vccnz .LBB0_658
	global_store_dwordx2 v143, v[134:135], s[94:95]
	v_add_u32_e32 v134, 32, v143
	global_store_dwordx2 v134, v[136:137], s[94:95]

.LBB0_659:
	s_andn2_b64 vcc, exec, s[18:19]
	s_cbranch_vccnz .LBB0_664
	s_lshl_b32 s18, s22, 9
	v_lshl_or_b32 v134, v176, 1, s18
	v_lshl_add_u32 v134, v148, 12, v134
	v_pk_mul_f32 v[132:133], v[132:133], s[50:51] op_sel_hi:[1,0]
	v_pk_mul_f32 v[130:131], v[130:131], s[50:51] op_sel_hi:[1,0]
	v_add_u32_e32 v135, 0x1ef20200, v134
	v_cvt_pk_bf16_f32 v130, v130, v131
	v_cvt_pk_bf16_f32 v131, v132, v133
	s_andn2_b64 vcc, exec, s[64:65]
	s_mov_b64 s[18:19], -1
	s_cbranch_vccnz .LBB0_662
	v_pk_mul_f32 v[136:137], v[128:129], s[50:51] op_sel_hi:[1,0]
	v_pk_mul_f32 v[132:133], v[126:127], s[50:51] op_sel_hi:[1,0]
	v_cvt_pk_bf16_f32 v132, v132, v133
	v_cvt_pk_bf16_f32 v133, v136, v137
	s_mov_b64 s[18:19], 0
	global_store_dwordx4 v135, v[130:133], s[94:95]
.LBB0_662:
	s_andn2_b64 vcc, exec, s[18:19]
	s_cbranch_vccnz .LBB0_664
	v_pk_mul_f32 v[128:129], v[128:129], s[50:51] op_sel_hi:[1,0]
	v_pk_mul_f32 v[126:127], v[126:127], s[50:51] op_sel_hi:[1,0]
	v_cvt_pk_bf16_f32 v126, v126, v127
	v_cvt_pk_bf16_f32 v127, v128, v129
	v_add_u32_e32 v128, 0x1ef20220, v134
	global_store_dwordx2 v135, v[130:131], s[94:95]
	global_store_dwordx2 v128, v[126:127], s[94:95]

.LBB0_666:
	s_and_saveexec_b64 s[2:3], s[0:1]
	s_cbranch_execz .LBB0_678
	s_andn2_b64 vcc, exec, s[60:61]
	s_mov_b64 s[0:1], -1
	s_cbranch_vccnz .LBB0_673
	s_lshl_b32 s0, s87, 7
	v_cndmask_b32_e64 v114, v141, v142, s[16:17]
	s_bitset1_b32 s0, 7
	v_or3_b32 v114, v176, v114, s0
	v_lshlrev_b32_e32 v115, 2, v114
	v_add_lshl_u32 v114, v114, s53, 2
	v_cvt_pk_bf16_f32 v126, v122, v123
	v_cvt_pk_bf16_f32 v127, v124, v125
	s_andn2_b64 vcc, exec, s[64:65]
	v_cvt_pk_bf16_f32 v128, v118, v119
	global_store_dwordx4 v115, v[122:125], s[92:93]
	global_store_dwordx4 v114, v[118:121], s[92:93]
	v_or_b32_e32 v114, s0, v140
	v_lshl_add_u32 v114, v114, 1, s23
	s_mov_b64 s[0:1], -1
	v_cvt_pk_bf16_f32 v129, v120, v121
	s_cbranch_vccnz .LBB0_670
	s_mov_b64 s[0:1], 0
	global_store_dwordx4 v114, v[126:129], s[94:95]
.LBB0_670:
	s_andn2_b64 vcc, exec, s[0:1]
	s_cbranch_vccnz .LBB0_672
	global_store_dwordx2 v114, v[126:127], s[94:95]
	v_add_u32_e32 v114, 32, v114
	global_store_dwordx2 v114, v[128:129], s[94:95]

.LBB0_673:
	s_andn2_b64 vcc, exec, s[0:1]
	s_cbranch_vccnz .LBB0_678
	s_lshl_b32 s0, s22, 9
	v_lshl_or_b32 v114, v176, 1, s0
	v_lshl_add_u32 v114, v148, 12, v114
	v_pk_mul_f32 v[124:125], v[124:125], s[50:51] op_sel_hi:[1,0]
	v_pk_mul_f32 v[122:123], v[122:123], s[50:51] op_sel_hi:[1,0]
	v_add_u32_e32 v115, 0x1ef20300, v114
	v_cvt_pk_bf16_f32 v122, v122, v123
	v_cvt_pk_bf16_f32 v123, v124, v125
	s_andn2_b64 vcc, exec, s[64:65]
	s_mov_b64 s[0:1], -1
	s_cbranch_vccnz .LBB0_676
	v_pk_mul_f32 v[126:127], v[120:121], s[50:51] op_sel_hi:[1,0]
	v_pk_mul_f32 v[124:125], v[118:119], s[50:51] op_sel_hi:[1,0]
	v_cvt_pk_bf16_f32 v124, v124, v125
	v_cvt_pk_bf16_f32 v125, v126, v127
	s_mov_b64 s[0:1], 0
	global_store_dwordx4 v115, v[122:125], s[94:95]
.LBB0_676:
	s_andn2_b64 vcc, exec, s[0:1]
	s_cbranch_vccnz .LBB0_678
	v_pk_mul_f32 v[120:121], v[120:121], s[50:51] op_sel_hi:[1,0]
	v_pk_mul_f32 v[118:119], v[118:119], s[50:51] op_sel_hi:[1,0]
	v_cvt_pk_bf16_f32 v118, v118, v119
	v_cvt_pk_bf16_f32 v119, v120, v121
	v_add_u32_e32 v114, 0x1ef20320, v114
	global_store_dwordx2 v115, v[122:123], s[94:95]
	global_store_dwordx2 v114, v[118:119], s[94:95]

.LBB0_686:
	v_add_u32_e32 v114, 0x220a0220, v114
	global_store_dwordx2 v115, v[138:139], s[94:95]
	global_store_dwordx2 v114, v[140:141], s[94:95]
	s_and_b64 exec, exec, s[2:3]
	s_cbranch_execnz .LBB0_646
	s_branch .LBB0_647
.LBB0_687:
	v_lshl_or_b32 v186, v131, 6, v209
	ds_bpermute_b32 v122, v218, v110
	ds_bpermute_b32 v123, v218, v111
	v_lshl_add_u64 v[114:115], s[94:95], 0, v[186:187]
	v_lshl_add_u64 v[118:119], v[114:115], 0, s[44:45]
	v_add_co_u32_e32 v114, vcc, 0x140000, v114
	s_nop 0
	s_nop 0
	v_addc_co_u32_e32 v115, vcc, 0, v115, vcc
	global_load_dwordx4 v[114:117], v[114:115], off offset:256
	s_nop 0
	global_load_dwordx4 v[118:121], v[118:119], off offset:16
	s_waitcnt vmcnt(0)
	v_mov_b32_e32 v125, v116
	v_mov_b32_e32 v116, v115
	v_mov_b32_e32 v124, v114
	s_waitcnt lgkmcnt(0)
	v_pk_mul_f32 v[114:115], v[116:117], v[122:123]
	ds_bpermute_b32 v116, v218, v112
	ds_bpermute_b32 v117, v218, v113
	v_mov_b32_e32 v123, v120
	v_mov_b32_e32 v120, v119
	v_cndmask_b32_e64 v115, v115, -v115, s[4:5]
	v_cndmask_b32_e64 v114, v114, -v114, s[4:5]
	s_waitcnt lgkmcnt(0)
	v_pk_mul_f32 v[116:117], v[120:121], v[116:117]
	v_mov_b32_e32 v122, v118
	v_cndmask_b32_e64 v117, v117, -v117, s[4:5]
	v_cndmask_b32_e64 v116, v116, -v116, s[4:5]
	v_pk_fma_f32 v[114:115], v[110:111], v[124:125], v[114:115]
	v_pk_fma_f32 v[116:117], v[112:113], v[122:123], v[116:117]
	s_and_saveexec_b64 s[18:19], s[0:1]
	s_cbranch_execz .LBB0_696
.LBB0_688:
	v_readlane_b32 s2, v254, 18
	v_readlane_b32 s3, v254, 19
	s_andn2_b64 vcc, exec, s[2:3]
	s_mov_b64 s[2:3], -1
	s_cbranch_vccnz .LBB0_694
	v_readlane_b32 s2, v254, 20
	v_readlane_b32 s3, v254, 21
	s_andn2_b64 vcc, exec, s[2:3]
	s_mov_b64 s[2:3], -1
	s_cbranch_vccnz .LBB0_691
	v_mul_f32_e32 v118, 0xbfb8aa3b, v114
	v_mul_f32_e32 v119, 0xbfb8aa3b, v115
	v_mul_f32_e32 v120, 0xbfb8aa3b, v116
	v_mul_f32_e32 v121, 0xbfb8aa3b, v117
	v_exp_f32_e32 v118, v118
	v_exp_f32_e32 v119, v119
	v_exp_f32_e32 v120, v120
	v_exp_f32_e32 v121, v121
	v_add_f32_e32 v118, 1.0, v118
	v_add_f32_e32 v119, 1.0, v119
	v_add_f32_e32 v120, 1.0, v120
	v_add_f32_e32 v121, 1.0, v121
	v_rcp_f32_e32 v118, v118
	v_rcp_f32_e32 v119, v119
	v_rcp_f32_e32 v120, v120
	v_rcp_f32_e32 v121, v121
	v_lshl_add_u32 v122, v130, 6, v252
	s_mov_b64 s[2:3], 0
	global_store_dwordx4 v122, v[118:121], s[94:95]
.LBB0_691:
	s_andn2_b64 vcc, exec, s[2:3]
	s_cbranch_vccnz .LBB0_693
	s_mov_b32 s2, 0x3d000000
	v_lshl_or_b32 v133, v130, 6, v203
	v_pk_mul_f32 v[120:121], v[116:117], s[2:3] op_sel_hi:[1,0]
	v_pk_mul_f32 v[118:119], v[114:115], s[2:3] op_sel_hi:[1,0]
	v_add_u32_e32 v122, 0x23230200, v133
	s_mov_b32 s33, 0x800000
	s_mov_b32 s70, 0x3f317217
	global_store_dwordx4 v122, v[118:121], s[94:95]
	v_or_b32_e32 v122, 0x6c000, v203
	global_load_dwordx4 v[118:121], v122, s[94:95]
	s_nop 0
	global_load_dwordx4 v[122:125], v122, s[94:95] offset:64
	s_waitcnt vmcnt(0)
	v_add_f32_e32 v126, v106, v122
	v_max_f32_e32 v122, 0, v126
	v_mul_f32_e64 v126, |v126|, s27
	v_exp_f32_e32 v126, v126
	s_nop 0
	v_add_f32_e32 v126, 1.0, v126
	v_cmp_gt_f32_e32 vcc, s33, v126
	s_nop 1
	v_cndmask_b32_e64 v127, 0, 32, vcc
	v_ldexp_f32 v126, v126, v127
	v_log_f32_e32 v126, v126
	s_nop 0
	v_mul_f32_e32 v127, 0x3f317217, v126
	v_fma_f32 v127, v126, s70, -v127
	v_fmac_f32_e32 v127, 0x3377d1cf, v126
	v_fmac_f32_e32 v127, 0x3f317217, v126
	v_cmp_lt_f32_e64 s[2:3], |v126|, s39
	s_nop 1
	v_cndmask_b32_e64 v126, v126, v127, s[2:3]
	v_cndmask_b32_e32 v127, 0, v223, vcc
	v_sub_f32_e32 v126, v126, v127
	v_add_f32_e32 v127, v107, v123
	v_max_f32_e32 v123, 0, v127
	v_mul_f32_e64 v127, |v127|, s27
	v_exp_f32_e32 v127, v127
	s_nop 0
	v_add_f32_e32 v127, 1.0, v127
	v_cmp_gt_f32_e32 vcc, s33, v127
	s_nop 1
	v_cndmask_b32_e64 v128, 0, 32, vcc
	v_ldexp_f32 v127, v127, v128
	v_log_f32_e32 v127, v127
	s_nop 0
	v_mul_f32_e32 v128, 0x3f317217, v127
	v_fma_f32 v128, v127, s70, -v128
	v_fmac_f32_e32 v128, 0x3377d1cf, v127
	v_fmac_f32_e32 v128, 0x3f317217, v127
	v_cmp_lt_f32_e64 s[2:3], |v127|, s39
	s_nop 1
	v_cndmask_b32_e64 v127, v127, v128, s[2:3]
	v_cndmask_b32_e32 v128, 0, v223, vcc
	v_sub_f32_e32 v127, v127, v128
	v_add_f32_e32 v128, v108, v124
	v_max_f32_e32 v124, 0, v128
	v_mul_f32_e64 v128, |v128|, s27
	v_exp_f32_e32 v128, v128
	v_pk_add_f32 v[122:123], v[122:123], v[126:127]
	v_add_f32_e32 v128, 1.0, v128
	v_cmp_gt_f32_e32 vcc, s33, v128
	v_pk_mul_f32 v[118:119], v[118:119], v[122:123]
	v_add_u32_e32 v122, 0x232b4200, v133
	v_cndmask_b32_e64 v129, 0, 32, vcc
	v_ldexp_f32 v128, v128, v129
	v_log_f32_e32 v128, v128
	s_nop 0
	v_mul_f32_e32 v129, 0x3f317217, v128
	v_fma_f32 v129, v128, s70, -v129
	v_fmac_f32_e32 v129, 0x3377d1cf, v128
	v_fmac_f32_e32 v129, 0x3f317217, v128
	v_cmp_lt_f32_e64 s[2:3], |v128|, s39
	s_nop 1
	v_cndmask_b32_e64 v128, v128, v129, s[2:3]
	v_cndmask_b32_e32 v129, 0, v223, vcc
	v_sub_f32_e32 v128, v128, v129
	v_add_f32_e32 v129, v109, v125
	v_max_f32_e32 v125, 0, v129
	v_mul_f32_e64 v129, |v129|, s27
	v_exp_f32_e32 v129, v129
	s_nop 0
	v_add_f32_e32 v129, 1.0, v129
	v_cmp_gt_f32_e32 vcc, s33, v129
	s_nop 1
	v_cndmask_b32_e64 v134, 0, 32, vcc
	v_ldexp_f32 v129, v129, v134
	v_log_f32_e32 v129, v129
	s_nop 0
	v_mul_f32_e32 v134, 0x3f317217, v129
	v_fma_f32 v134, v129, s70, -v134
	v_fmac_f32_e32 v134, 0x3377d1cf, v129
	v_fmac_f32_e32 v134, 0x3f317217, v129
	v_cmp_lt_f32_e64 s[2:3], |v129|, s39
	s_nop 1
	v_cndmask_b32_e64 v129, v129, v134, s[2:3]
	v_cndmask_b32_e32 v134, 0, v223, vcc
	v_sub_f32_e32 v129, v129, v134
	v_pk_add_f32 v[124:125], v[124:125], v[128:129]
	s_nop 0
	v_pk_mul_f32 v[120:121], v[120:121], v[124:125]
	global_store_dwordx4 v122, v[118:121], s[94:95]

.LBB0_694:
	s_andn2_b64 vcc, exec, s[2:3]
	s_cbranch_vccnz .LBB0_696
	v_cndmask_b32_e64 v118, v224, v225, s[16:17]
	v_lshl_add_u32 v118, v130, 6, v118
	v_or_b32_e32 v118, v118, v213
	v_lshlrev_b32_e32 v118, 2, v118
	s_nop 4
	global_store_dwordx4 v118, v[114:117], s[92:93]
	global_store_dwordx4 v118, v[106:109], s[92:93] offset:64
	v_lshl_or_b32 v118, v130, 7, v214
	v_add_u32_e32 v119, 0x23120200, v118
	v_cvt_pk_bf16_f32 v114, v114, v115
	v_cvt_pk_bf16_f32 v115, v116, v117
	v_add_u32_e32 v116, 0x23120220, v118
	global_store_dwordx2 v119, v[114:115], s[94:95]
	v_cvt_pk_bf16_f32 v114, v106, v107
	v_cvt_pk_bf16_f32 v115, v108, v109
	global_store_dwordx2 v116, v[114:115], s[94:95]

.LBB0_703:
	s_nop 0
	v_cvt_pk_bf16_f32 v117, v118, v119
	v_lshlrev_b32_e32 v118, 1, v229
	v_lshl_or_b32 v120, v130, 12, v118
	v_add_u32_e32 v118, s33, v120
	s_and_b64 vcc, exec, s[2:3]
	s_mov_b64 s[2:3], -1
	global_store_dwordx4 v118, v[114:117], s[94:95]
	s_cbranch_vccnz .LBB0_705
	s_nop 0
	v_cvt_pk_bf16_f32 v114, v102, v103
	v_cvt_pk_bf16_f32 v115, v104, v105
	v_cvt_pk_bf16_f32 v116, v98, v99
	s_mov_b64 s[2:3], 0
	v_mov_b32_e32 v119, v101
	v_mov_b32_e32 v118, v100

.LBB0_707:
	s_nop 0
	v_cvt_pk_bf16_f32 v117, v118, v119
	v_add_u32_e32 v118, s2, v120
	v_add_u32_e32 v118, 0x100, v118
	global_store_dwordx4 v118, v[114:117], s[94:95]

.LBB0_710:
	s_andn2_b64 vcc, exec, s[2:3]
	s_cbranch_vccnz .LBB0_725
	s_and_saveexec_b64 s[18:19], s[0:1]
	s_cbranch_execz .LBB0_724
	v_ashrrev_i32_e32 v114, 11, v130
	v_mul_lo_u32 v115, v130, s36
	v_mad_i32_i24 v114, v114, 3, v132
	v_mul_lo_u32 v114, v114, s36
	v_add_u32_e32 v120, v115, v228
	v_cmp_gt_i32_e64 s[2:3], s76, v130
	v_cmp_lt_u32_e32 vcc, s37, v132
	v_add_u32_e32 v114, 0xd88800, v114
	v_cvt_pk_bf16_f32 v116, v110, v111
	v_cvt_pk_bf16_f32 v117, v112, v113
	v_cvt_pk_bf16_f32 v118, v106, v107
	v_cvt_pk_bf16_f32 v119, v108, v109
	v_lshl_add_u32 v120, v120, 1, v226
	global_store_dwordx4 v120, v[116:119], s[94:95]
	s_and_saveexec_b64 s[70:71], s[2:3]
	s_xor_b64 s[70:71], exec, s[70:71]
	s_cbranch_execz .LBB0_716
	s_and_saveexec_b64 s[72:73], vcc
	s_cbranch_execz .LBB0_715
	v_add_lshl_u32 v116, v114, v228, 2
	global_store_dwordx4 v116, v[110:113], s[92:93]
	global_store_dwordx4 v116, v[106:109], s[92:93] offset:16

.LBB0_716:
	s_or_saveexec_b64 s[70:71], s[70:71]
	s_movk_i32 s33, 0x4800
	v_mul_lo_u32 v116, v130, s33
	v_add_u32_e32 v116, 0xf8b9b200, v116
	s_xor_b64 exec, exec, s[70:71]
	s_cbranch_execz .LBB0_718
	v_add_lshl_u32 v117, v116, v228, 2
	global_store_dwordx4 v117, v[110:113], s[92:93]
	global_store_dwordx4 v117, v[106:109], s[92:93] offset:16
.LBB0_718:
	s_or_b64 exec, exec, s[70:71]
	v_or_b32_e32 v117, 0x80, v228
	v_add_u32_e32 v115, v115, v117
	v_cvt_pk_bf16_f32 v118, v102, v103
	v_cvt_pk_bf16_f32 v119, v104, v105
	v_cvt_pk_bf16_f32 v120, v98, v99
	v_cvt_pk_bf16_f32 v121, v100, v101
	v_lshl_add_u32 v115, v115, 1, v226
	global_store_dwordx4 v115, v[118:121], s[94:95]
	s_and_saveexec_b64 s[70:71], s[2:3]
	s_xor_b64 s[2:3], exec, s[70:71]
	s_cbranch_execz .LBB0_722
	s_and_saveexec_b64 s[70:71], vcc
	s_cbranch_execz .LBB0_721
	v_add_lshl_u32 v114, v114, v117, 2
	global_store_dwordx4 v114, v[102:105], s[92:93]
	global_store_dwordx4 v114, v[98:101], s[92:93] offset:16

.LBB0_722:
	s_andn2_saveexec_b64 s[2:3], s[2:3]
	s_cbranch_execz .LBB0_724
	v_add_lshl_u32 v114, v116, v117, 2
	global_store_dwordx4 v114, v[102:105], s[92:93]
	global_store_dwordx4 v114, v[98:101], s[92:93] offset:16

.LBB0_726:
	s_andn2_b64 vcc, exec, s[2:3]
	s_cbranch_vccnz .LBB0_745
	v_lshl_or_b32 v186, v131, 6, v209
	v_cndmask_b32_e64 v114, 0, 1, s[6:7]
	v_cmp_ne_u32_e64 s[18:19], 1, v114
	v_lshl_add_u64 v[124:125], s[94:95], 0, v[186:187]
	s_andn2_b64 vcc, exec, s[6:7]
	v_lshl_add_u64 v[122:123], v[124:125], 0, s[44:45]
	s_cbranch_vccnz .LBB0_729
	v_add_co_u32_e32 v114, vcc, 0x140000, v124
	ds_bpermute_b32 v126, v218, v110
	s_nop 0
	v_addc_co_u32_e32 v115, vcc, 0, v125, vcc
	global_load_dwordx4 v[114:117], v[114:115], off offset:256
	s_nop 0
	global_load_dwordx4 v[118:121], v[122:123], off offset:16
	ds_bpermute_b32 v127, v218, v111
	s_waitcnt vmcnt(0)
	v_mov_b32_e32 v129, v116
	v_mov_b32_e32 v116, v115
	v_mov_b32_e32 v128, v114
	s_waitcnt lgkmcnt(0)
	v_pk_mul_f32 v[114:115], v[116:117], v[126:127]
	ds_bpermute_b32 v116, v218, v112
	ds_bpermute_b32 v117, v218, v113
	v_mov_b32_e32 v127, v120
	v_mov_b32_e32 v120, v119
	v_cndmask_b32_e64 v115, v115, -v115, s[4:5]
	v_cndmask_b32_e64 v114, v114, -v114, s[4:5]
	s_waitcnt lgkmcnt(0)
	v_pk_mul_f32 v[116:117], v[120:121], v[116:117]
	v_mov_b32_e32 v126, v118
	v_cndmask_b32_e64 v117, v117, -v117, s[4:5]
	v_cndmask_b32_e64 v116, v116, -v116, s[4:5]
	v_pk_fma_f32 v[114:115], v[110:111], v[128:129], v[114:115]
	v_pk_fma_f32 v[116:117], v[112:113], v[126:127], v[116:117]
	s_branch .LBB0_730

.LBB0_730:
	v_lshlrev_b32_e32 v118, 10, v130
	v_or_b32_e32 v127, v118, v215
	v_cmp_lt_i32_e64 s[2:3], s26, v130
	v_add_u32_e32 v126, v118, v216
	s_and_saveexec_b64 s[70:71], s[0:1]
	s_cbranch_execz .LBB0_735
	s_lshl_b32 s33, s97, 6
	v_add_lshl_u32 v128, v127, s33, 1
	v_add_u32_e32 v129, 0x220a0200, v128
	v_cvt_pk_bf16_f32 v118, v114, v115
	v_cvt_pk_bf16_f32 v119, v116, v117
	s_mov_b64 s[72:73], -1
	s_andn2_b64 vcc, exec, s[40:41]
	v_cvt_pk_bf16_f32 v120, v106, v107
	v_cvt_pk_bf16_f32 v121, v108, v109
	s_cbranch_vccnz .LBB0_737
	global_store_dwordx4 v129, v[118:121], s[94:95]
	s_cbranch_execz .LBB0_738

.LBB0_734:
	v_add_u32_e32 v118, s33, v126
	v_lshl_add_u32 v186, v118, 2, v227
	v_lshl_add_u64 v[118:119], s[94:95], 0, v[186:187]
	v_lshl_add_u64 v[118:119], v[118:119], 0, s[24:25]
	global_store_dwordx4 v186, v[114:117], s[94:95]
	global_store_dwordx4 v[118:119], v[106:109], off

.LBB0_738:
	global_store_dwordx2 v129, v[118:119], s[94:95]
	v_add_u32_e32 v118, 0x220a0220, v128
	global_store_dwordx2 v118, v[120:121], s[94:95]
	s_and_b64 exec, exec, s[2:3]
	s_cbranch_execnz .LBB0_734
	s_branch .LBB0_735

.LBB0_740:
	s_lshl_b32 s33, s97, 6
	s_bitset1_b32 s33, 7
	v_add_lshl_u32 v122, v127, s33, 1
	v_add_u32_e32 v123, 0x220a0200, v122
	v_cvt_pk_bf16_f32 v118, v114, v115
	v_cvt_pk_bf16_f32 v119, v116, v117
	s_mov_b64 s[70:71], -1
	s_andn2_b64 vcc, exec, s[40:41]
	v_cvt_pk_bf16_f32 v120, v98, v99
	v_cvt_pk_bf16_f32 v121, v100, v101
	s_cbranch_vccnz .LBB0_782
	global_store_dwordx4 v123, v[118:121], s[94:95]
	s_cbranch_execz .LBB0_783

.LBB0_743:
	v_add_u32_e32 v118, s33, v126
	v_lshl_add_u32 v186, v118, 2, v227
	v_lshl_add_u64 v[118:119], s[94:95], 0, v[186:187]
	v_lshl_add_u64 v[118:119], v[118:119], 0, s[24:25]
	global_store_dwordx4 v186, v[114:117], s[94:95]
	global_store_dwordx4 v[118:119], v[98:101], off

.LBB0_746:
	s_andn2_b64 vcc, exec, s[2:3]
	s_cbranch_vccnz .LBB0_776
	v_lshl_or_b32 v186, v131, 7, v208
	s_and_b64 vcc, exec, s[10:11]
	v_lshl_add_u64 v[118:119], s[94:95], 0, v[186:187]
	v_lshl_add_u64 v[120:121], v[118:119], 0, s[48:49]
	s_cbranch_vccnz .LBB0_749
	global_load_dwordx4 v[114:117], v[120:121], off offset:16
	v_add_co_u32_e32 v122, vcc, 0x100000, v118
	s_nop 1
	v_addc_co_u32_e32 v123, vcc, 0, v119, vcc
	global_load_dwordx4 v[122:125], v[122:123], off
	s_waitcnt vmcnt(0)
	v_mul_f32_e32 v126, v112, v114
	v_mul_f32_e32 v132, v112, v115
	v_mov_b32_e32 v112, v109
	v_mul_f32_e32 v128, v108, v115
	v_mul_f32_e32 v114, v108, v114
	v_mov_b32_e32 v108, v113
	v_pk_mul_f32 v[112:113], v[112:113], v[116:117]
	v_pk_mul_f32 v[108:109], v[108:109], v[116:117]
	v_mov_b32_e32 v115, v112
	v_mov_b32_e32 v133, v113
	v_mov_b32_e32 v117, v124
	v_mov_b32_e32 v124, v123
	v_mov_b32_e32 v127, v108
	v_mov_b32_e32 v129, v109
	v_mov_b32_e32 v116, v122
	v_pk_add_f32 v[108:109], v[114:115], v[132:133]
	v_pk_mul_f32 v[114:115], v[106:107], v[124:125]
	v_pk_mul_f32 v[122:123], v[110:111], v[124:125]
	v_pk_add_f32 v[112:113], v[126:127], v[128:129] neg_lo:[0,1] neg_hi:[0,1]
	v_pk_fma_f32 v[110:111], v[110:111], v[116:117], v[114:115] neg_lo:[0,0,1] neg_hi:[0,0,1]
	v_pk_fma_f32 v[106:107], v[106:107], v[116:117], v[122:123]
.LBB0_749:
	v_lshlrev_b32_e32 v114, 9, v130
	v_add_u32_e32 v123, s55, v114
	v_add_u32_e32 v124, s96, v114
	v_or_b32_e32 v122, v114, v176
	s_and_saveexec_b64 s[2:3], s[0:1]
	s_cbranch_execz .LBB0_761
	s_andn2_b64 vcc, exec, s[60:61]
	s_mov_b64 s[18:19], -1
	s_cbranch_vccnz .LBB0_756
	v_cndmask_b32_e64 v114, v123, v124, s[16:17]
	s_lshl_b32 s18, s87, 7
	v_or3_b32 v114, v176, v114, s18
	v_lshlrev_b32_e32 v115, 2, v114
	v_add_lshl_u32 v114, v114, s53, 2
	s_andn2_b64 vcc, exec, s[64:65]
	v_cvt_pk_bf16_f32 v116, v106, v107
	v_cvt_pk_bf16_f32 v117, v108, v109
	global_store_dwordx4 v115, v[110:113], s[92:93]
	global_store_dwordx4 v114, v[106:109], s[92:93]
	v_or_b32_e32 v114, s18, v122
	v_lshl_add_u32 v125, v114, 1, s23
	v_cvt_pk_bf16_f32 v114, v110, v111
	v_cvt_pk_bf16_f32 v115, v112, v113
	s_mov_b64 s[18:19], -1
	s_cbranch_vccnz .LBB0_753
	s_mov_b64 s[18:19], 0
	global_store_dwordx4 v125, v[114:117], s[94:95]
.LBB0_753:
	s_andn2_b64 vcc, exec, s[18:19]
	s_cbranch_vccnz .LBB0_755
	global_store_dwordx2 v125, v[114:115], s[94:95]
	v_add_u32_e32 v114, 32, v125
	global_store_dwordx2 v114, v[116:117], s[94:95]

.LBB0_756:
	s_andn2_b64 vcc, exec, s[18:19]
	s_cbranch_vccnz .LBB0_761
	s_lshl_b32 s18, s22, 9
	v_lshl_or_b32 v114, v176, 1, s18
	v_lshl_add_u32 v114, v130, 12, v114
	v_pk_mul_f32 v[112:113], v[112:113], s[50:51] op_sel_hi:[1,0]
	v_pk_mul_f32 v[110:111], v[110:111], s[50:51] op_sel_hi:[1,0]
	v_add_u32_e32 v115, 0x1ef20200, v114
	v_cvt_pk_bf16_f32 v110, v110, v111
	v_cvt_pk_bf16_f32 v111, v112, v113
	s_andn2_b64 vcc, exec, s[64:65]
	s_mov_b64 s[18:19], -1
	s_cbranch_vccnz .LBB0_759
	v_pk_mul_f32 v[116:117], v[108:109], s[50:51] op_sel_hi:[1,0]
	v_pk_mul_f32 v[112:113], v[106:107], s[50:51] op_sel_hi:[1,0]
	v_cvt_pk_bf16_f32 v112, v112, v113
	v_cvt_pk_bf16_f32 v113, v116, v117
	s_mov_b64 s[18:19], 0
	global_store_dwordx4 v115, v[110:113], s[94:95]
.LBB0_759:
	s_andn2_b64 vcc, exec, s[18:19]
	s_cbranch_vccnz .LBB0_761
	v_pk_mul_f32 v[108:109], v[108:109], s[50:51] op_sel_hi:[1,0]
	v_pk_mul_f32 v[106:107], v[106:107], s[50:51] op_sel_hi:[1,0]
	v_cvt_pk_bf16_f32 v106, v106, v107
	v_cvt_pk_bf16_f32 v107, v108, v109
	v_add_u32_e32 v108, 0x1ef20220, v114
	global_store_dwordx2 v115, v[110:111], s[94:95]
	global_store_dwordx2 v108, v[106:107], s[94:95]

.LBB0_763:
	s_and_saveexec_b64 s[2:3], s[0:1]
	s_cbranch_execz .LBB0_775
	s_andn2_b64 vcc, exec, s[60:61]
	s_mov_b64 s[0:1], -1
	s_cbranch_vccnz .LBB0_770
	s_lshl_b32 s0, s87, 7
	v_cndmask_b32_e64 v106, v123, v124, s[16:17]
	s_bitset1_b32 s0, 7
	v_or3_b32 v106, v176, v106, s0
	v_lshlrev_b32_e32 v107, 2, v106
	v_add_lshl_u32 v106, v106, s53, 2
	s_andn2_b64 vcc, exec, s[64:65]
	v_cvt_pk_bf16_f32 v108, v98, v99
	v_cvt_pk_bf16_f32 v109, v100, v101
	global_store_dwordx4 v107, v[102:105], s[92:93]
	global_store_dwordx4 v106, v[98:101], s[92:93]
	v_or_b32_e32 v106, s0, v122
	v_lshl_add_u32 v110, v106, 1, s23
	v_cvt_pk_bf16_f32 v106, v102, v103
	v_cvt_pk_bf16_f32 v107, v104, v105
	s_mov_b64 s[0:1], -1
	s_cbranch_vccnz .LBB0_767
	s_mov_b64 s[0:1], 0
	global_store_dwordx4 v110, v[106:109], s[94:95]
.LBB0_767:
	s_andn2_b64 vcc, exec, s[0:1]
	s_cbranch_vccnz .LBB0_769
	global_store_dwordx2 v110, v[106:107], s[94:95]
	v_add_u32_e32 v106, 32, v110
	global_store_dwordx2 v106, v[108:109], s[94:95]

.LBB0_770:
	s_andn2_b64 vcc, exec, s[0:1]
	s_cbranch_vccnz .LBB0_775
	s_lshl_b32 s0, s22, 9
	v_lshl_or_b32 v106, v176, 1, s0
	v_lshl_add_u32 v106, v130, 12, v106
	v_pk_mul_f32 v[104:105], v[104:105], s[50:51] op_sel_hi:[1,0]
	v_pk_mul_f32 v[102:103], v[102:103], s[50:51] op_sel_hi:[1,0]
	v_add_u32_e32 v107, 0x1ef20300, v106
	v_cvt_pk_bf16_f32 v102, v102, v103
	v_cvt_pk_bf16_f32 v103, v104, v105
	s_andn2_b64 vcc, exec, s[64:65]
	s_mov_b64 s[0:1], -1
	s_cbranch_vccnz .LBB0_773
	v_pk_mul_f32 v[108:109], v[100:101], s[50:51] op_sel_hi:[1,0]
	v_pk_mul_f32 v[104:105], v[98:99], s[50:51] op_sel_hi:[1,0]
	v_cvt_pk_bf16_f32 v104, v104, v105
	v_cvt_pk_bf16_f32 v105, v108, v109
	s_mov_b64 s[0:1], 0
	global_store_dwordx4 v107, v[102:105], s[94:95]
.LBB0_773:
	s_andn2_b64 vcc, exec, s[0:1]
	s_cbranch_vccnz .LBB0_775
	v_pk_mul_f32 v[100:101], v[100:101], s[50:51] op_sel_hi:[1,0]
	v_pk_mul_f32 v[98:99], v[98:99], s[50:51] op_sel_hi:[1,0]
	v_cvt_pk_bf16_f32 v98, v98, v99
	v_cvt_pk_bf16_f32 v99, v100, v101
	v_add_u32_e32 v100, 0x1ef20320, v106
	global_store_dwordx2 v107, v[102:103], s[94:95]
	global_store_dwordx2 v100, v[98:99], s[94:95]

.LBB0_783:
	global_store_dwordx2 v123, v[118:119], s[94:95]
	v_add_u32_e32 v118, 0x220a0220, v122
	global_store_dwordx2 v118, v[120:121], s[94:95]
	s_and_b64 exec, exec, s[2:3]
	s_cbranch_execnz .LBB0_743
	s_branch .LBB0_744
.LBB0_784:
	v_lshl_or_b32 v186, v121, 6, v209
	v_lshl_add_u64 v[102:103], s[94:95], 0, v[186:187]
	v_lshl_add_u64 v[110:111], v[102:103], 0, s[44:45]
	v_add_co_u32_e32 v102, vcc, 0x140000, v102
	s_nop 0
	s_nop 0
	v_addc_co_u32_e32 v103, vcc, 0, v103, vcc
	global_load_dwordx4 v[106:109], v[102:103], off offset:256
	s_nop 0
	global_load_dwordx4 v[110:113], v[110:111], off offset:16
	ds_bpermute_b32 v102, v218, v94
	ds_bpermute_b32 v103, v218, v95
	s_waitcnt vmcnt(0)
	v_mov_b32_e32 v115, v108
	v_mov_b32_e32 v108, v107
	s_waitcnt lgkmcnt(0)
	v_pk_mul_f32 v[102:103], v[108:109], v[102:103]
	v_mov_b32_e32 v114, v106
	v_cndmask_b32_e64 v103, v103, -v103, s[4:5]
	v_cndmask_b32_e64 v102, v102, -v102, s[4:5]
	v_pk_fma_f32 v[106:107], v[94:95], v[114:115], v[102:103]
	ds_bpermute_b32 v102, v218, v96
	ds_bpermute_b32 v103, v218, v97
	v_mov_b32_e32 v109, v112
	v_mov_b32_e32 v112, v111
	v_mov_b32_e32 v108, v110
	s_waitcnt lgkmcnt(0)
	v_pk_mul_f32 v[102:103], v[112:113], v[102:103]
	s_nop 0
	v_cndmask_b32_e64 v103, v103, -v103, s[4:5]
	v_cndmask_b32_e64 v102, v102, -v102, s[4:5]
	v_pk_fma_f32 v[108:109], v[96:97], v[108:109], v[102:103]
	s_and_saveexec_b64 s[18:19], s[0:1]
	s_cbranch_execz .LBB0_793
.LBB0_785:
	v_readlane_b32 s2, v254, 18
	v_readlane_b32 s3, v254, 19
	s_andn2_b64 vcc, exec, s[2:3]
	s_mov_b64 s[2:3], -1
	s_cbranch_vccnz .LBB0_791
	v_readlane_b32 s2, v254, 20
	v_readlane_b32 s3, v254, 21
	s_andn2_b64 vcc, exec, s[2:3]
	s_mov_b64 s[2:3], -1
	s_cbranch_vccnz .LBB0_788
	v_mul_f32_e32 v102, 0xbfb8aa3b, v106
	v_exp_f32_e32 v102, v102
	v_mul_f32_e32 v103, 0xbfb8aa3b, v107
	v_mul_f32_e32 v111, 0xbfb8aa3b, v109
	v_exp_f32_e32 v103, v103
	v_add_f32_e32 v102, 1.0, v102
	v_rcp_f32_e32 v110, v102
	v_mul_f32_e32 v102, 0xbfb8aa3b, v108
	v_exp_f32_e32 v102, v102
	v_exp_f32_e32 v113, v111
	v_add_f32_e32 v103, 1.0, v103
	v_rcp_f32_e32 v111, v103
	v_add_f32_e32 v102, 1.0, v102
	v_rcp_f32_e32 v112, v102
	v_add_f32_e32 v102, 1.0, v113
	v_rcp_f32_e32 v113, v102
	v_lshl_add_u32 v102, v120, 6, v252
	s_mov_b64 s[2:3], 0
	global_store_dwordx4 v102, v[110:113], s[94:95]
.LBB0_788:
	s_andn2_b64 vcc, exec, s[2:3]
	s_cbranch_vccnz .LBB0_790
	s_mov_b32 s2, 0x3d000000
	v_lshl_or_b32 v123, v120, 6, v203
	v_pk_mul_f32 v[112:113], v[108:109], s[2:3] op_sel_hi:[1,0]
	v_pk_mul_f32 v[110:111], v[106:107], s[2:3] op_sel_hi:[1,0]
	v_add_u32_e32 v102, 0x23230200, v123
	s_mov_b32 s33, 0x800000
	s_mov_b32 s70, 0x3f317217
	global_store_dwordx4 v102, v[110:113], s[94:95]
	v_or_b32_e32 v102, 0x6c000, v203
	global_load_dwordx4 v[110:113], v102, s[94:95]
	global_load_dwordx4 v[114:117], v102, s[94:95] offset:64
	s_waitcnt vmcnt(0)
	v_add_f32_e32 v103, v90, v114
	v_max_f32_e32 v102, 0, v103
	v_mul_f32_e64 v103, |v103|, s27
	v_exp_f32_e32 v103, v103
	v_add_f32_e32 v115, v91, v115
	v_add_f32_e32 v103, 1.0, v103
	v_cmp_gt_f32_e32 vcc, s33, v103
	s_nop 1
	v_cndmask_b32_e64 v114, 0, 32, vcc
	v_ldexp_f32 v103, v103, v114
	v_log_f32_e32 v103, v103
	s_nop 0
	v_mul_f32_e32 v114, 0x3f317217, v103
	v_fma_f32 v114, v103, s70, -v114
	v_fmac_f32_e32 v114, 0x3377d1cf, v103
	v_fmac_f32_e32 v114, 0x3f317217, v103
	v_cmp_lt_f32_e64 s[2:3], |v103|, s39
	s_nop 1
	v_cndmask_b32_e64 v103, v103, v114, s[2:3]
	v_cndmask_b32_e32 v114, 0, v223, vcc
	v_sub_f32_e32 v114, v103, v114
	v_max_f32_e32 v103, 0, v115
	v_mul_f32_e64 v115, |v115|, s27
	v_exp_f32_e32 v115, v115
	s_nop 0
	v_add_f32_e32 v115, 1.0, v115
	v_cmp_gt_f32_e32 vcc, s33, v115
	s_nop 1
	v_cndmask_b32_e64 v118, 0, 32, vcc
	v_ldexp_f32 v115, v115, v118
	v_log_f32_e32 v115, v115
	s_nop 0
	v_mul_f32_e32 v118, 0x3f317217, v115
	v_fma_f32 v118, v115, s70, -v118
	v_fmac_f32_e32 v118, 0x3377d1cf, v115
	v_fmac_f32_e32 v118, 0x3f317217, v115
	v_cmp_lt_f32_e64 s[2:3], |v115|, s39
	s_nop 1
	v_cndmask_b32_e64 v115, v115, v118, s[2:3]
	v_cndmask_b32_e32 v118, 0, v223, vcc
	v_sub_f32_e32 v115, v115, v118
	v_add_f32_e32 v118, v92, v116
	v_max_f32_e32 v116, 0, v118
	v_mul_f32_e64 v118, |v118|, s27
	v_exp_f32_e32 v118, v118
	v_pk_add_f32 v[102:103], v[102:103], v[114:115]
	v_add_f32_e32 v118, 1.0, v118
	v_cmp_gt_f32_e32 vcc, s33, v118
	v_pk_mul_f32 v[110:111], v[110:111], v[102:103]
	v_add_u32_e32 v102, 0x232b4200, v123
	v_cndmask_b32_e64 v119, 0, 32, vcc
	v_ldexp_f32 v118, v118, v119
	v_log_f32_e32 v118, v118
	s_nop 0
	v_mul_f32_e32 v119, 0x3f317217, v118
	v_fma_f32 v119, v118, s70, -v119
	v_fmac_f32_e32 v119, 0x3377d1cf, v118
	v_fmac_f32_e32 v119, 0x3f317217, v118
	v_cmp_lt_f32_e64 s[2:3], |v118|, s39
	s_nop 1
	v_cndmask_b32_e64 v118, v118, v119, s[2:3]
	v_cndmask_b32_e32 v119, 0, v223, vcc
	v_sub_f32_e32 v118, v118, v119
	v_add_f32_e32 v119, v93, v117
	v_max_f32_e32 v117, 0, v119
	v_mul_f32_e64 v119, |v119|, s27
	v_exp_f32_e32 v119, v119
	s_nop 0
	v_add_f32_e32 v119, 1.0, v119
	v_cmp_gt_f32_e32 vcc, s33, v119
	s_nop 1
	v_cndmask_b32_e64 v124, 0, 32, vcc
	v_ldexp_f32 v119, v119, v124
	v_log_f32_e32 v119, v119
	s_nop 0
	v_mul_f32_e32 v124, 0x3f317217, v119
	v_fma_f32 v124, v119, s70, -v124
	v_fmac_f32_e32 v124, 0x3377d1cf, v119
	v_fmac_f32_e32 v124, 0x3f317217, v119
	v_cmp_lt_f32_e64 s[2:3], |v119|, s39
	s_nop 1
	v_cndmask_b32_e64 v119, v119, v124, s[2:3]
	v_cndmask_b32_e32 v124, 0, v223, vcc
	v_sub_f32_e32 v119, v119, v124
	v_pk_add_f32 v[114:115], v[116:117], v[118:119]
	s_nop 0
	v_pk_mul_f32 v[112:113], v[112:113], v[114:115]
	global_store_dwordx4 v102, v[110:113], s[94:95]

.LBB0_791:
	s_andn2_b64 vcc, exec, s[2:3]
	s_cbranch_vccnz .LBB0_793
	v_cndmask_b32_e64 v102, v224, v225, s[16:17]
	v_lshl_add_u32 v102, v120, 6, v102
	v_or_b32_e32 v102, v102, v213
	v_lshlrev_b32_e32 v102, 2, v102
	v_lshl_or_b32 v110, v120, 7, v214
	s_nop 1
	global_store_dwordx4 v102, v[106:109], s[92:93]
	global_store_dwordx4 v102, v[90:93], s[92:93] offset:64
	v_add_u32_e32 v111, 0x23120200, v110
	v_cvt_pk_bf16_f32 v102, v106, v107
	v_cvt_pk_bf16_f32 v103, v108, v109
	global_store_dwordx2 v111, v[102:103], s[94:95]
	v_cvt_pk_bf16_f32 v102, v90, v91
	v_cvt_pk_bf16_f32 v103, v92, v93
	v_add_u32_e32 v106, 0x23120220, v110
	global_store_dwordx2 v106, v[102:103], s[94:95]

.LBB0_800:
	s_nop 0
	v_cvt_pk_bf16_f32 v109, v102, v103
	v_lshlrev_b32_e32 v102, 1, v229
	v_lshl_or_b32 v110, v120, 12, v102
	v_add_u32_e32 v102, s33, v110
	s_and_b64 vcc, exec, s[2:3]
	s_mov_b64 s[2:3], -1
	global_store_dwordx4 v102, v[106:109], s[94:95]
	s_cbranch_vccnz .LBB0_802
	s_nop 0
	v_cvt_pk_bf16_f32 v106, v86, v87
	v_cvt_pk_bf16_f32 v107, v88, v89
	v_cvt_pk_bf16_f32 v108, v82, v83
	s_mov_b64 s[2:3], 0
	v_mov_b32_e32 v103, v85
	v_mov_b32_e32 v102, v84

.LBB0_804:
	s_nop 0
	v_cvt_pk_bf16_f32 v109, v102, v103
	v_add_u32_e32 v102, s2, v110
	v_add_u32_e32 v102, 0x100, v102
	global_store_dwordx4 v102, v[106:109], s[94:95]

.LBB0_807:
	s_andn2_b64 vcc, exec, s[2:3]
	s_cbranch_vccnz .LBB0_822
	s_and_saveexec_b64 s[18:19], s[0:1]
	s_cbranch_execz .LBB0_821
	v_ashrrev_i32_e32 v102, 11, v120
	v_mul_lo_u32 v103, v120, s36
	v_mad_i32_i24 v102, v102, 3, v122
	v_mul_lo_u32 v102, v102, s36
	v_add_u32_e32 v110, v103, v228
	v_cmp_gt_i32_e64 s[2:3], s76, v120
	v_cmp_lt_u32_e32 vcc, s37, v122
	v_add_u32_e32 v102, 0xd88800, v102
	v_cvt_pk_bf16_f32 v106, v94, v95
	v_cvt_pk_bf16_f32 v107, v96, v97
	v_cvt_pk_bf16_f32 v108, v90, v91
	v_cvt_pk_bf16_f32 v109, v92, v93
	v_lshl_add_u32 v110, v110, 1, v226
	global_store_dwordx4 v110, v[106:109], s[94:95]
	s_and_saveexec_b64 s[70:71], s[2:3]
	s_xor_b64 s[70:71], exec, s[70:71]
	s_cbranch_execz .LBB0_813
	s_and_saveexec_b64 s[72:73], vcc
	s_cbranch_execz .LBB0_812
	v_add_lshl_u32 v106, v102, v228, 2
	global_store_dwordx4 v106, v[94:97], s[92:93]
	global_store_dwordx4 v106, v[90:93], s[92:93] offset:16

.LBB0_813:
	s_or_saveexec_b64 s[70:71], s[70:71]
	s_movk_i32 s33, 0x4800
	v_mul_lo_u32 v106, v120, s33
	v_add_u32_e32 v106, 0xf8b9b200, v106
	s_xor_b64 exec, exec, s[70:71]
	s_cbranch_execz .LBB0_815
	v_add_lshl_u32 v107, v106, v228, 2
	global_store_dwordx4 v107, v[94:97], s[92:93]
	global_store_dwordx4 v107, v[90:93], s[92:93] offset:16
.LBB0_815:
	s_or_b64 exec, exec, s[70:71]
	v_or_b32_e32 v107, 0x80, v228
	v_add_u32_e32 v103, v103, v107
	v_cvt_pk_bf16_f32 v108, v86, v87
	v_cvt_pk_bf16_f32 v109, v88, v89
	v_cvt_pk_bf16_f32 v110, v82, v83
	v_cvt_pk_bf16_f32 v111, v84, v85
	v_lshl_add_u32 v103, v103, 1, v226
	global_store_dwordx4 v103, v[108:111], s[94:95]
	s_and_saveexec_b64 s[70:71], s[2:3]
	s_xor_b64 s[2:3], exec, s[70:71]
	s_cbranch_execz .LBB0_819
	s_and_saveexec_b64 s[70:71], vcc
	s_cbranch_execz .LBB0_818
	v_add_lshl_u32 v102, v102, v107, 2
	global_store_dwordx4 v102, v[86:89], s[92:93]
	global_store_dwordx4 v102, v[82:85], s[92:93] offset:16

.LBB0_819:
	s_andn2_saveexec_b64 s[2:3], s[2:3]
	s_cbranch_execz .LBB0_821
	v_add_lshl_u32 v102, v106, v107, 2
	global_store_dwordx4 v102, v[86:89], s[92:93]
	global_store_dwordx4 v102, v[82:85], s[92:93] offset:16

.LBB0_823:
	s_andn2_b64 vcc, exec, s[2:3]
	s_cbranch_vccnz .LBB0_842
	v_lshl_or_b32 v186, v121, 6, v209
	v_cndmask_b32_e64 v102, 0, 1, s[6:7]
	v_cmp_ne_u32_e64 s[18:19], 1, v102
	v_lshl_add_u64 v[114:115], s[94:95], 0, v[186:187]
	s_andn2_b64 vcc, exec, s[6:7]
	v_lshl_add_u64 v[102:103], v[114:115], 0, s[44:45]
	s_cbranch_vccnz .LBB0_826
	v_add_co_u32_e32 v106, vcc, 0x140000, v114
	ds_bpermute_b32 v116, v218, v94
	s_nop 0
	v_addc_co_u32_e32 v107, vcc, 0, v115, vcc
	global_load_dwordx4 v[106:109], v[106:107], off offset:256
	s_nop 0
	global_load_dwordx4 v[110:113], v[102:103], off offset:16
	ds_bpermute_b32 v117, v218, v95
	s_waitcnt vmcnt(0)
	v_mov_b32_e32 v119, v108
	v_mov_b32_e32 v108, v107
	v_mov_b32_e32 v118, v106
	s_waitcnt lgkmcnt(0)
	v_pk_mul_f32 v[106:107], v[108:109], v[116:117]
	ds_bpermute_b32 v108, v218, v96
	ds_bpermute_b32 v109, v218, v97
	v_mov_b32_e32 v117, v112
	v_mov_b32_e32 v112, v111
	v_cndmask_b32_e64 v107, v107, -v107, s[4:5]
	v_cndmask_b32_e64 v106, v106, -v106, s[4:5]
	s_waitcnt lgkmcnt(0)
	v_pk_mul_f32 v[108:109], v[112:113], v[108:109]
	v_mov_b32_e32 v116, v110
	v_cndmask_b32_e64 v109, v109, -v109, s[4:5]
	v_cndmask_b32_e64 v108, v108, -v108, s[4:5]
	v_pk_fma_f32 v[106:107], v[94:95], v[118:119], v[106:107]
	v_pk_fma_f32 v[108:109], v[96:97], v[116:117], v[108:109]
	s_branch .LBB0_827

.LBB0_827:
	v_lshlrev_b32_e32 v110, 10, v120
	v_or_b32_e32 v117, v110, v215
	v_cmp_lt_i32_e64 s[2:3], s26, v120
	v_add_u32_e32 v116, v110, v216
	s_and_saveexec_b64 s[70:71], s[0:1]
	s_cbranch_execz .LBB0_832
	s_lshl_b32 s33, s97, 6
	v_add_lshl_u32 v118, v117, s33, 1
	v_add_u32_e32 v119, 0x220a0200, v118
	v_cvt_pk_bf16_f32 v110, v106, v107
	v_cvt_pk_bf16_f32 v111, v108, v109
	s_mov_b64 s[72:73], -1
	s_andn2_b64 vcc, exec, s[40:41]
	v_cvt_pk_bf16_f32 v112, v90, v91
	v_cvt_pk_bf16_f32 v113, v92, v93
	s_cbranch_vccnz .LBB0_834
	global_store_dwordx4 v119, v[110:113], s[94:95]
	s_cbranch_execz .LBB0_835

.LBB0_831:
	v_add_u32_e32 v110, s33, v116
	v_lshl_add_u32 v186, v110, 2, v227
	v_lshl_add_u64 v[110:111], s[94:95], 0, v[186:187]
	v_lshl_add_u64 v[110:111], v[110:111], 0, s[24:25]
	global_store_dwordx4 v186, v[106:109], s[94:95]
	global_store_dwordx4 v[110:111], v[90:93], off

.LBB0_835:
	global_store_dwordx2 v119, v[110:111], s[94:95]
	v_add_u32_e32 v110, 0x220a0220, v118
	global_store_dwordx2 v110, v[112:113], s[94:95]
	s_and_b64 exec, exec, s[2:3]
	s_cbranch_execnz .LBB0_831
	s_branch .LBB0_832

.LBB0_837:
	s_lshl_b32 s33, s97, 6
	s_bitset1_b32 s33, 7
	v_add_lshl_u32 v102, v117, s33, 1
	v_add_u32_e32 v103, 0x220a0200, v102
	v_cvt_pk_bf16_f32 v110, v106, v107
	v_cvt_pk_bf16_f32 v111, v108, v109
	s_mov_b64 s[70:71], -1
	s_andn2_b64 vcc, exec, s[40:41]
	v_cvt_pk_bf16_f32 v112, v82, v83
	v_cvt_pk_bf16_f32 v113, v84, v85
	s_cbranch_vccnz .LBB0_879
	global_store_dwordx4 v103, v[110:113], s[94:95]
	s_cbranch_execz .LBB0_880

.LBB0_840:
	v_add_u32_e32 v102, s33, v116
	v_lshl_add_u32 v186, v102, 2, v227
	v_lshl_add_u64 v[102:103], s[94:95], 0, v[186:187]
	v_lshl_add_u64 v[102:103], v[102:103], 0, s[24:25]
	global_store_dwordx4 v186, v[106:109], s[94:95]
	global_store_dwordx4 v[102:103], v[82:85], off

.LBB0_843:
	s_andn2_b64 vcc, exec, s[2:3]
	s_cbranch_vccnz .LBB0_873
	v_lshl_or_b32 v186, v121, 7, v208
	s_and_b64 vcc, exec, s[10:11]
	v_lshl_add_u64 v[102:103], s[94:95], 0, v[186:187]
	v_lshl_add_u64 v[110:111], v[102:103], 0, s[48:49]
	s_cbranch_vccnz .LBB0_846
	global_load_dwordx4 v[106:109], v[110:111], off offset:16
	v_add_co_u32_e32 v112, vcc, 0x100000, v102
	s_nop 1
	v_addc_co_u32_e32 v113, vcc, 0, v103, vcc
	global_load_dwordx4 v[112:115], v[112:113], off
	s_waitcnt vmcnt(0)
	v_mul_f32_e32 v116, v96, v106
	v_mul_f32_e32 v122, v96, v107
	v_mov_b32_e32 v96, v93
	v_mul_f32_e32 v118, v92, v107
	v_mul_f32_e32 v106, v92, v106
	v_mov_b32_e32 v92, v97
	v_pk_mul_f32 v[96:97], v[96:97], v[108:109]
	v_pk_mul_f32 v[92:93], v[92:93], v[108:109]
	v_mov_b32_e32 v107, v96
	v_mov_b32_e32 v123, v97
	v_mov_b32_e32 v109, v114
	v_mov_b32_e32 v114, v113
	v_mov_b32_e32 v117, v92
	v_mov_b32_e32 v119, v93
	v_mov_b32_e32 v108, v112
	v_pk_add_f32 v[92:93], v[106:107], v[122:123]
	v_pk_mul_f32 v[106:107], v[90:91], v[114:115]
	v_pk_mul_f32 v[112:113], v[94:95], v[114:115]
	v_pk_add_f32 v[96:97], v[116:117], v[118:119] neg_lo:[0,1] neg_hi:[0,1]
	v_pk_fma_f32 v[94:95], v[94:95], v[108:109], v[106:107] neg_lo:[0,0,1] neg_hi:[0,0,1]
	v_pk_fma_f32 v[90:91], v[90:91], v[108:109], v[112:113]
.LBB0_846:
	v_lshlrev_b32_e32 v106, 9, v120
	v_add_u32_e32 v113, s55, v106
	v_add_u32_e32 v114, s96, v106
	v_or_b32_e32 v112, v106, v176
	s_and_saveexec_b64 s[2:3], s[0:1]
	s_cbranch_execz .LBB0_858
	s_andn2_b64 vcc, exec, s[60:61]
	s_mov_b64 s[18:19], -1
	s_cbranch_vccnz .LBB0_853
	v_cndmask_b32_e64 v106, v113, v114, s[16:17]
	s_lshl_b32 s18, s87, 7
	v_or3_b32 v106, v176, v106, s18
	v_lshlrev_b32_e32 v107, 2, v106
	v_add_lshl_u32 v106, v106, s53, 2
	s_andn2_b64 vcc, exec, s[64:65]
	v_cvt_pk_bf16_f32 v108, v90, v91
	v_cvt_pk_bf16_f32 v109, v92, v93
	global_store_dwordx4 v107, v[94:97], s[92:93]
	global_store_dwordx4 v106, v[90:93], s[92:93]
	v_or_b32_e32 v106, s18, v112
	v_lshl_add_u32 v115, v106, 1, s23
	v_cvt_pk_bf16_f32 v106, v94, v95
	v_cvt_pk_bf16_f32 v107, v96, v97
	s_mov_b64 s[18:19], -1
	s_cbranch_vccnz .LBB0_850
	s_mov_b64 s[18:19], 0
	global_store_dwordx4 v115, v[106:109], s[94:95]
.LBB0_850:
	s_andn2_b64 vcc, exec, s[18:19]
	s_cbranch_vccnz .LBB0_852
	global_store_dwordx2 v115, v[106:107], s[94:95]
	v_add_u32_e32 v106, 32, v115
	global_store_dwordx2 v106, v[108:109], s[94:95]

.LBB0_853:
	s_andn2_b64 vcc, exec, s[18:19]
	s_cbranch_vccnz .LBB0_858
	s_lshl_b32 s18, s22, 9
	v_lshl_or_b32 v106, v176, 1, s18
	v_lshl_add_u32 v106, v120, 12, v106
	v_pk_mul_f32 v[96:97], v[96:97], s[50:51] op_sel_hi:[1,0]
	v_pk_mul_f32 v[94:95], v[94:95], s[50:51] op_sel_hi:[1,0]
	v_add_u32_e32 v107, 0x1ef20200, v106
	v_cvt_pk_bf16_f32 v94, v94, v95
	v_cvt_pk_bf16_f32 v95, v96, v97
	s_andn2_b64 vcc, exec, s[64:65]
	s_mov_b64 s[18:19], -1
	s_cbranch_vccnz .LBB0_856
	v_pk_mul_f32 v[108:109], v[92:93], s[50:51] op_sel_hi:[1,0]
	v_pk_mul_f32 v[96:97], v[90:91], s[50:51] op_sel_hi:[1,0]
	v_cvt_pk_bf16_f32 v96, v96, v97
	v_cvt_pk_bf16_f32 v97, v108, v109
	s_mov_b64 s[18:19], 0
	global_store_dwordx4 v107, v[94:97], s[94:95]
.LBB0_856:
	s_andn2_b64 vcc, exec, s[18:19]
	s_cbranch_vccnz .LBB0_858
	v_pk_mul_f32 v[92:93], v[92:93], s[50:51] op_sel_hi:[1,0]
	v_pk_mul_f32 v[90:91], v[90:91], s[50:51] op_sel_hi:[1,0]
	v_cvt_pk_bf16_f32 v90, v90, v91
	v_cvt_pk_bf16_f32 v91, v92, v93
	v_add_u32_e32 v92, 0x1ef20220, v106
	global_store_dwordx2 v107, v[94:95], s[94:95]
	global_store_dwordx2 v92, v[90:91], s[94:95]

.LBB0_860:
	s_and_saveexec_b64 s[2:3], s[0:1]
	s_cbranch_execz .LBB0_872
	s_andn2_b64 vcc, exec, s[60:61]
	s_mov_b64 s[0:1], -1
	s_cbranch_vccnz .LBB0_867
	s_lshl_b32 s0, s87, 7
	v_cndmask_b32_e64 v90, v113, v114, s[16:17]
	s_bitset1_b32 s0, 7
	v_or3_b32 v90, v176, v90, s0
	v_lshlrev_b32_e32 v91, 2, v90
	v_add_lshl_u32 v90, v90, s53, 2
	s_andn2_b64 vcc, exec, s[64:65]
	v_cvt_pk_bf16_f32 v92, v82, v83
	v_cvt_pk_bf16_f32 v93, v84, v85
	global_store_dwordx4 v91, v[86:89], s[92:93]
	global_store_dwordx4 v90, v[82:85], s[92:93]
	v_or_b32_e32 v90, s0, v112
	v_lshl_add_u32 v94, v90, 1, s23
	v_cvt_pk_bf16_f32 v90, v86, v87
	v_cvt_pk_bf16_f32 v91, v88, v89
	s_mov_b64 s[0:1], -1
	s_cbranch_vccnz .LBB0_864
	s_mov_b64 s[0:1], 0
	global_store_dwordx4 v94, v[90:93], s[94:95]
.LBB0_864:
	s_andn2_b64 vcc, exec, s[0:1]
	s_cbranch_vccnz .LBB0_866
	global_store_dwordx2 v94, v[90:91], s[94:95]
	v_add_u32_e32 v90, 32, v94
	global_store_dwordx2 v90, v[92:93], s[94:95]

.LBB0_867:
	s_andn2_b64 vcc, exec, s[0:1]
	s_cbranch_vccnz .LBB0_872
	s_lshl_b32 s0, s22, 9
	v_lshl_or_b32 v90, v176, 1, s0
	v_lshl_add_u32 v90, v120, 12, v90
	v_pk_mul_f32 v[88:89], v[88:89], s[50:51] op_sel_hi:[1,0]
	v_pk_mul_f32 v[86:87], v[86:87], s[50:51] op_sel_hi:[1,0]
	v_add_u32_e32 v91, 0x1ef20300, v90
	v_cvt_pk_bf16_f32 v86, v86, v87
	v_cvt_pk_bf16_f32 v87, v88, v89
	s_andn2_b64 vcc, exec, s[64:65]
	s_mov_b64 s[0:1], -1
	s_cbranch_vccnz .LBB0_870
	v_pk_mul_f32 v[92:93], v[84:85], s[50:51] op_sel_hi:[1,0]
	v_pk_mul_f32 v[88:89], v[82:83], s[50:51] op_sel_hi:[1,0]
	v_cvt_pk_bf16_f32 v88, v88, v89
	v_cvt_pk_bf16_f32 v89, v92, v93
	s_mov_b64 s[0:1], 0
	global_store_dwordx4 v91, v[86:89], s[94:95]
.LBB0_870:
	s_andn2_b64 vcc, exec, s[0:1]
	s_cbranch_vccnz .LBB0_872
	v_pk_mul_f32 v[84:85], v[84:85], s[50:51] op_sel_hi:[1,0]
	v_pk_mul_f32 v[82:83], v[82:83], s[50:51] op_sel_hi:[1,0]
	v_cvt_pk_bf16_f32 v82, v82, v83
	v_cvt_pk_bf16_f32 v83, v84, v85
	v_add_u32_e32 v84, 0x1ef20320, v90
	global_store_dwordx2 v91, v[86:87], s[94:95]
	global_store_dwordx2 v84, v[82:83], s[94:95]

.LBB0_880:
	v_add_u32_e32 v102, 0x220a0220, v102
	global_store_dwordx2 v103, v[110:111], s[94:95]
	global_store_dwordx2 v102, v[112:113], s[94:95]
	s_and_b64 exec, exec, s[2:3]
	s_cbranch_execnz .LBB0_840
	s_branch .LBB0_841
.LBB0_881:
	v_lshl_or_b32 v186, v103, 6, v209
	ds_bpermute_b32 v90, v218, v78
	ds_bpermute_b32 v91, v218, v79
	v_lshl_add_u64 v[82:83], s[94:95], 0, v[186:187]
	v_lshl_add_u64 v[86:87], v[82:83], 0, s[44:45]
	v_add_co_u32_e32 v82, vcc, 0x140000, v82
	s_nop 0
	s_nop 0
	v_addc_co_u32_e32 v83, vcc, 0, v83, vcc
	global_load_dwordx4 v[82:85], v[82:83], off offset:256
	s_nop 0
	global_load_dwordx4 v[86:89], v[86:87], off offset:16
	s_waitcnt vmcnt(0)
	v_mov_b32_e32 v93, v84
	v_mov_b32_e32 v84, v83
	v_mov_b32_e32 v92, v82
	s_waitcnt lgkmcnt(0)
	v_pk_mul_f32 v[82:83], v[84:85], v[90:91]
	ds_bpermute_b32 v84, v218, v80
	ds_bpermute_b32 v85, v218, v81
	v_mov_b32_e32 v91, v88
	v_mov_b32_e32 v88, v87
	v_cndmask_b32_e64 v83, v83, -v83, s[4:5]
	v_cndmask_b32_e64 v82, v82, -v82, s[4:5]
	s_waitcnt lgkmcnt(0)
	v_pk_mul_f32 v[84:85], v[88:89], v[84:85]
	v_mov_b32_e32 v90, v86
	v_cndmask_b32_e64 v85, v85, -v85, s[4:5]
	v_cndmask_b32_e64 v84, v84, -v84, s[4:5]
	v_pk_fma_f32 v[82:83], v[78:79], v[92:93], v[82:83]
	v_pk_fma_f32 v[84:85], v[80:81], v[90:91], v[84:85]
	s_and_saveexec_b64 s[18:19], s[0:1]
	s_cbranch_execz .LBB0_890
.LBB0_882:
	v_readlane_b32 s2, v254, 18
	v_readlane_b32 s3, v254, 19
	s_andn2_b64 vcc, exec, s[2:3]
	s_mov_b64 s[2:3], -1
	s_cbranch_vccnz .LBB0_888
	v_readlane_b32 s2, v254, 20
	v_readlane_b32 s3, v254, 21
	s_andn2_b64 vcc, exec, s[2:3]
	s_mov_b64 s[2:3], -1
	s_cbranch_vccnz .LBB0_885
	v_mul_f32_e32 v86, 0xbfb8aa3b, v82
	v_mul_f32_e32 v87, 0xbfb8aa3b, v83
	v_mul_f32_e32 v88, 0xbfb8aa3b, v84
	v_mul_f32_e32 v89, 0xbfb8aa3b, v85
	v_exp_f32_e32 v86, v86
	v_exp_f32_e32 v87, v87
	v_exp_f32_e32 v88, v88
	v_exp_f32_e32 v89, v89
	v_add_f32_e32 v86, 1.0, v86
	v_add_f32_e32 v87, 1.0, v87
	v_add_f32_e32 v88, 1.0, v88
	v_add_f32_e32 v89, 1.0, v89
	v_rcp_f32_e32 v86, v86
	v_rcp_f32_e32 v87, v87
	v_rcp_f32_e32 v88, v88
	v_rcp_f32_e32 v89, v89
	v_lshl_add_u32 v90, v102, 6, v252
	s_mov_b64 s[2:3], 0
	global_store_dwordx4 v90, v[86:89], s[94:95]
.LBB0_885:
	s_andn2_b64 vcc, exec, s[2:3]
	s_cbranch_vccnz .LBB0_887
	s_mov_b32 s2, 0x3d000000
	v_lshl_or_b32 v105, v102, 6, v203
	v_pk_mul_f32 v[88:89], v[84:85], s[2:3] op_sel_hi:[1,0]
	v_pk_mul_f32 v[86:87], v[82:83], s[2:3] op_sel_hi:[1,0]
	v_add_u32_e32 v90, 0x23230200, v105
	s_mov_b32 s33, 0x800000
	s_mov_b32 s70, 0x3f317217
	global_store_dwordx4 v90, v[86:89], s[94:95]
	v_or_b32_e32 v90, 0x6c000, v203
	global_load_dwordx4 v[86:89], v90, s[94:95]
	s_nop 0
	global_load_dwordx4 v[90:93], v90, s[94:95] offset:64
	s_waitcnt vmcnt(0)
	v_add_f32_e32 v94, v74, v90
	v_max_f32_e32 v90, 0, v94
	v_mul_f32_e64 v94, |v94|, s27
	v_exp_f32_e32 v94, v94
	s_nop 0
	v_add_f32_e32 v94, 1.0, v94
	v_cmp_gt_f32_e32 vcc, s33, v94
	s_nop 1
	v_cndmask_b32_e64 v95, 0, 32, vcc
	v_ldexp_f32 v94, v94, v95
	v_log_f32_e32 v94, v94
	s_nop 0
	v_mul_f32_e32 v95, 0x3f317217, v94
	v_fma_f32 v95, v94, s70, -v95
	v_fmac_f32_e32 v95, 0x3377d1cf, v94
	v_fmac_f32_e32 v95, 0x3f317217, v94
	v_cmp_lt_f32_e64 s[2:3], |v94|, s39
	s_nop 1
	v_cndmask_b32_e64 v94, v94, v95, s[2:3]
	v_cndmask_b32_e32 v95, 0, v223, vcc
	v_sub_f32_e32 v94, v94, v95
	v_add_f32_e32 v95, v75, v91
	v_max_f32_e32 v91, 0, v95
	v_mul_f32_e64 v95, |v95|, s27
	v_exp_f32_e32 v95, v95
	s_nop 0
	v_add_f32_e32 v95, 1.0, v95
	v_cmp_gt_f32_e32 vcc, s33, v95
	s_nop 1
	v_cndmask_b32_e64 v96, 0, 32, vcc
	v_ldexp_f32 v95, v95, v96
	v_log_f32_e32 v95, v95
	s_nop 0
	v_mul_f32_e32 v96, 0x3f317217, v95
	v_fma_f32 v96, v95, s70, -v96
	v_fmac_f32_e32 v96, 0x3377d1cf, v95
	v_fmac_f32_e32 v96, 0x3f317217, v95
	v_cmp_lt_f32_e64 s[2:3], |v95|, s39
	s_nop 1
	v_cndmask_b32_e64 v95, v95, v96, s[2:3]
	v_cndmask_b32_e32 v96, 0, v223, vcc
	v_sub_f32_e32 v95, v95, v96
	v_add_f32_e32 v96, v76, v92
	v_max_f32_e32 v92, 0, v96
	v_mul_f32_e64 v96, |v96|, s27
	v_exp_f32_e32 v96, v96
	v_pk_add_f32 v[90:91], v[90:91], v[94:95]
	v_add_f32_e32 v96, 1.0, v96
	v_cmp_gt_f32_e32 vcc, s33, v96
	v_pk_mul_f32 v[86:87], v[86:87], v[90:91]
	v_add_u32_e32 v90, 0x232b4200, v105
	v_cndmask_b32_e64 v97, 0, 32, vcc
	v_ldexp_f32 v96, v96, v97
	v_log_f32_e32 v96, v96
	s_nop 0
	v_mul_f32_e32 v97, 0x3f317217, v96
	v_fma_f32 v97, v96, s70, -v97
	v_fmac_f32_e32 v97, 0x3377d1cf, v96
	v_fmac_f32_e32 v97, 0x3f317217, v96
	v_cmp_lt_f32_e64 s[2:3], |v96|, s39
	s_nop 1
	v_cndmask_b32_e64 v96, v96, v97, s[2:3]
	v_cndmask_b32_e32 v97, 0, v223, vcc
	v_sub_f32_e32 v96, v96, v97
	v_add_f32_e32 v97, v77, v93
	v_max_f32_e32 v93, 0, v97
	v_mul_f32_e64 v97, |v97|, s27
	v_exp_f32_e32 v97, v97
	s_nop 0
	v_add_f32_e32 v97, 1.0, v97
	v_cmp_gt_f32_e32 vcc, s33, v97
	s_nop 1
	v_cndmask_b32_e64 v106, 0, 32, vcc
	v_ldexp_f32 v97, v97, v106
	v_log_f32_e32 v97, v97
	s_nop 0
	v_mul_f32_e32 v106, 0x3f317217, v97
	v_fma_f32 v106, v97, s70, -v106
	v_fmac_f32_e32 v106, 0x3377d1cf, v97
	v_fmac_f32_e32 v106, 0x3f317217, v97
	v_cmp_lt_f32_e64 s[2:3], |v97|, s39
	s_nop 1
	v_cndmask_b32_e64 v97, v97, v106, s[2:3]
	v_cndmask_b32_e32 v106, 0, v223, vcc
	v_sub_f32_e32 v97, v97, v106
	v_pk_add_f32 v[92:93], v[92:93], v[96:97]
	s_nop 0
	v_pk_mul_f32 v[88:89], v[88:89], v[92:93]
	global_store_dwordx4 v90, v[86:89], s[94:95]

.LBB0_888:
	s_andn2_b64 vcc, exec, s[2:3]
	s_cbranch_vccnz .LBB0_890
	v_cndmask_b32_e64 v86, v224, v225, s[16:17]
	v_lshl_add_u32 v86, v102, 6, v86
	v_or_b32_e32 v86, v86, v213
	v_lshlrev_b32_e32 v86, 2, v86
	s_nop 4
	global_store_dwordx4 v86, v[82:85], s[92:93]
	global_store_dwordx4 v86, v[74:77], s[92:93] offset:64
	v_lshl_or_b32 v86, v102, 7, v214
	v_add_u32_e32 v87, 0x23120200, v86
	v_cvt_pk_bf16_f32 v82, v82, v83
	v_cvt_pk_bf16_f32 v83, v84, v85
	v_add_u32_e32 v84, 0x23120220, v86
	global_store_dwordx2 v87, v[82:83], s[94:95]
	v_cvt_pk_bf16_f32 v82, v74, v75
	v_cvt_pk_bf16_f32 v83, v76, v77
	global_store_dwordx2 v84, v[82:83], s[94:95]

.LBB0_897:
	s_nop 0
	v_cvt_pk_bf16_f32 v85, v86, v87
	v_lshlrev_b32_e32 v86, 1, v229
	v_lshl_or_b32 v88, v102, 12, v86
	v_add_u32_e32 v86, s33, v88
	s_and_b64 vcc, exec, s[2:3]
	s_mov_b64 s[2:3], -1
	global_store_dwordx4 v86, v[82:85], s[94:95]
	s_cbranch_vccnz .LBB0_899
	s_nop 0
	v_cvt_pk_bf16_f32 v82, v70, v71
	v_cvt_pk_bf16_f32 v83, v72, v73
	v_cvt_pk_bf16_f32 v84, v66, v67
	s_mov_b64 s[2:3], 0
	v_mov_b32_e32 v87, v69
	v_mov_b32_e32 v86, v68

.LBB0_901:
	s_nop 0
	v_cvt_pk_bf16_f32 v85, v86, v87
	v_add_u32_e32 v86, s2, v88
	v_add_u32_e32 v86, 0x100, v86
	global_store_dwordx4 v86, v[82:85], s[94:95]

.LBB0_904:
	s_andn2_b64 vcc, exec, s[2:3]
	s_cbranch_vccnz .LBB0_919
	s_and_saveexec_b64 s[18:19], s[0:1]
	s_cbranch_execz .LBB0_918
	v_ashrrev_i32_e32 v82, 11, v102
	v_mul_lo_u32 v83, v102, s36
	v_mad_i32_i24 v82, v82, 3, v104
	v_mul_lo_u32 v82, v82, s36
	v_add_u32_e32 v88, v83, v228
	v_cmp_gt_i32_e64 s[2:3], s76, v102
	v_cmp_lt_u32_e32 vcc, s37, v104
	v_add_u32_e32 v82, 0xd88800, v82
	v_cvt_pk_bf16_f32 v84, v78, v79
	v_cvt_pk_bf16_f32 v85, v80, v81
	v_cvt_pk_bf16_f32 v86, v74, v75
	v_cvt_pk_bf16_f32 v87, v76, v77
	v_lshl_add_u32 v88, v88, 1, v226
	global_store_dwordx4 v88, v[84:87], s[94:95]
	s_and_saveexec_b64 s[70:71], s[2:3]
	s_xor_b64 s[70:71], exec, s[70:71]
	s_cbranch_execz .LBB0_910
	s_and_saveexec_b64 s[72:73], vcc
	s_cbranch_execz .LBB0_909
	v_add_lshl_u32 v84, v82, v228, 2
	global_store_dwordx4 v84, v[78:81], s[92:93]
	global_store_dwordx4 v84, v[74:77], s[92:93] offset:16

.LBB0_910:
	s_or_saveexec_b64 s[70:71], s[70:71]
	s_movk_i32 s33, 0x4800
	v_mul_lo_u32 v84, v102, s33
	v_add_u32_e32 v84, 0xf8b9b200, v84
	s_xor_b64 exec, exec, s[70:71]
	s_cbranch_execz .LBB0_912
	v_add_lshl_u32 v85, v84, v228, 2
	global_store_dwordx4 v85, v[78:81], s[92:93]
	global_store_dwordx4 v85, v[74:77], s[92:93] offset:16
.LBB0_912:
	s_or_b64 exec, exec, s[70:71]
	v_or_b32_e32 v85, 0x80, v228
	v_add_u32_e32 v83, v83, v85
	v_cvt_pk_bf16_f32 v86, v70, v71
	v_cvt_pk_bf16_f32 v87, v72, v73
	v_cvt_pk_bf16_f32 v88, v66, v67
	v_cvt_pk_bf16_f32 v89, v68, v69
	v_lshl_add_u32 v83, v83, 1, v226
	global_store_dwordx4 v83, v[86:89], s[94:95]
	s_and_saveexec_b64 s[70:71], s[2:3]
	s_xor_b64 s[2:3], exec, s[70:71]
	s_cbranch_execz .LBB0_916
	s_and_saveexec_b64 s[70:71], vcc
	s_cbranch_execz .LBB0_915
	v_add_lshl_u32 v82, v82, v85, 2
	global_store_dwordx4 v82, v[70:73], s[92:93]
	global_store_dwordx4 v82, v[66:69], s[92:93] offset:16

.LBB0_916:
	s_andn2_saveexec_b64 s[2:3], s[2:3]
	s_cbranch_execz .LBB0_918
	v_add_lshl_u32 v82, v84, v85, 2
	global_store_dwordx4 v82, v[70:73], s[92:93]
	global_store_dwordx4 v82, v[66:69], s[92:93] offset:16

.LBB0_920:
	s_andn2_b64 vcc, exec, s[2:3]
	s_cbranch_vccnz .LBB0_939
	v_lshl_or_b32 v186, v103, 6, v209
	v_cndmask_b32_e64 v82, 0, 1, s[6:7]
	v_cmp_ne_u32_e64 s[18:19], 1, v82
	v_lshl_add_u64 v[92:93], s[94:95], 0, v[186:187]
	s_andn2_b64 vcc, exec, s[6:7]
	v_lshl_add_u64 v[90:91], v[92:93], 0, s[44:45]
	s_cbranch_vccnz .LBB0_923
	v_add_co_u32_e32 v82, vcc, 0x140000, v92
	ds_bpermute_b32 v94, v218, v78
	s_nop 0
	v_addc_co_u32_e32 v83, vcc, 0, v93, vcc
	global_load_dwordx4 v[82:85], v[82:83], off offset:256
	s_nop 0
	global_load_dwordx4 v[86:89], v[90:91], off offset:16
	ds_bpermute_b32 v95, v218, v79
	s_waitcnt vmcnt(0)
	v_mov_b32_e32 v97, v84
	v_mov_b32_e32 v84, v83
	v_mov_b32_e32 v96, v82
	s_waitcnt lgkmcnt(0)
	v_pk_mul_f32 v[82:83], v[84:85], v[94:95]
	ds_bpermute_b32 v84, v218, v80
	ds_bpermute_b32 v85, v218, v81
	v_mov_b32_e32 v95, v88
	v_mov_b32_e32 v88, v87
	v_cndmask_b32_e64 v83, v83, -v83, s[4:5]
	v_cndmask_b32_e64 v82, v82, -v82, s[4:5]
	s_waitcnt lgkmcnt(0)
	v_pk_mul_f32 v[84:85], v[88:89], v[84:85]
	v_mov_b32_e32 v94, v86
	v_cndmask_b32_e64 v85, v85, -v85, s[4:5]
	v_cndmask_b32_e64 v84, v84, -v84, s[4:5]
	v_pk_fma_f32 v[82:83], v[78:79], v[96:97], v[82:83]
	v_pk_fma_f32 v[84:85], v[80:81], v[94:95], v[84:85]
	s_branch .LBB0_924

.LBB0_924:
	v_lshlrev_b32_e32 v86, 10, v102
	v_or_b32_e32 v95, v86, v215
	v_cmp_lt_i32_e64 s[2:3], s26, v102
	v_add_u32_e32 v94, v86, v216
	s_and_saveexec_b64 s[70:71], s[0:1]
	s_cbranch_execz .LBB0_929
	s_lshl_b32 s33, s97, 6
	v_add_lshl_u32 v96, v95, s33, 1
	v_add_u32_e32 v97, 0x220a0200, v96
	v_cvt_pk_bf16_f32 v86, v82, v83
	v_cvt_pk_bf16_f32 v87, v84, v85
	s_mov_b64 s[72:73], -1
	s_andn2_b64 vcc, exec, s[40:41]
	v_cvt_pk_bf16_f32 v88, v74, v75
	v_cvt_pk_bf16_f32 v89, v76, v77
	s_cbranch_vccnz .LBB0_931
	global_store_dwordx4 v97, v[86:89], s[94:95]
	s_cbranch_execz .LBB0_932

.LBB0_928:
	v_add_u32_e32 v86, s33, v94
	v_lshl_add_u32 v186, v86, 2, v227
	v_lshl_add_u64 v[86:87], s[94:95], 0, v[186:187]
	v_lshl_add_u64 v[86:87], v[86:87], 0, s[24:25]
	global_store_dwordx4 v186, v[82:85], s[94:95]
	global_store_dwordx4 v[86:87], v[74:77], off

.LBB0_932:
	global_store_dwordx2 v97, v[86:87], s[94:95]
	v_add_u32_e32 v86, 0x220a0220, v96
	global_store_dwordx2 v86, v[88:89], s[94:95]
	s_and_b64 exec, exec, s[2:3]
	s_cbranch_execnz .LBB0_928
	s_branch .LBB0_929

.LBB0_934:
	s_lshl_b32 s33, s97, 6
	s_bitset1_b32 s33, 7
	v_add_lshl_u32 v90, v95, s33, 1
	v_add_u32_e32 v91, 0x220a0200, v90
	v_cvt_pk_bf16_f32 v86, v82, v83
	v_cvt_pk_bf16_f32 v87, v84, v85
	s_mov_b64 s[70:71], -1
	s_andn2_b64 vcc, exec, s[40:41]
	v_cvt_pk_bf16_f32 v88, v66, v67
	v_cvt_pk_bf16_f32 v89, v68, v69
	s_cbranch_vccnz .LBB0_976
	global_store_dwordx4 v91, v[86:89], s[94:95]
	s_cbranch_execz .LBB0_977

.LBB0_937:
	v_add_u32_e32 v86, s33, v94
	v_lshl_add_u32 v186, v86, 2, v227
	v_lshl_add_u64 v[86:87], s[94:95], 0, v[186:187]
	v_lshl_add_u64 v[86:87], v[86:87], 0, s[24:25]
	global_store_dwordx4 v186, v[82:85], s[94:95]
	global_store_dwordx4 v[86:87], v[66:69], off

.LBB0_940:
	s_andn2_b64 vcc, exec, s[2:3]
	s_cbranch_vccnz .LBB0_970
	v_lshl_or_b32 v186, v103, 7, v208
	s_and_b64 vcc, exec, s[10:11]
	v_lshl_add_u64 v[86:87], s[94:95], 0, v[186:187]
	v_lshl_add_u64 v[88:89], v[86:87], 0, s[48:49]
	s_cbranch_vccnz .LBB0_943
	global_load_dwordx4 v[82:85], v[88:89], off offset:16
	v_add_co_u32_e32 v90, vcc, 0x100000, v86
	s_nop 1
	v_addc_co_u32_e32 v91, vcc, 0, v87, vcc
	global_load_dwordx4 v[90:93], v[90:91], off
	s_waitcnt vmcnt(0)
	v_mul_f32_e32 v94, v80, v82
	v_mul_f32_e32 v104, v80, v83
	v_mov_b32_e32 v80, v77
	v_mul_f32_e32 v96, v76, v83
	v_mul_f32_e32 v82, v76, v82
	v_mov_b32_e32 v76, v81
	v_pk_mul_f32 v[80:81], v[80:81], v[84:85]
	v_pk_mul_f32 v[76:77], v[76:77], v[84:85]
	v_mov_b32_e32 v83, v80
	v_mov_b32_e32 v105, v81
	v_mov_b32_e32 v85, v92
	v_mov_b32_e32 v92, v91
	v_mov_b32_e32 v95, v76
	v_mov_b32_e32 v97, v77
	v_mov_b32_e32 v84, v90
	v_pk_add_f32 v[76:77], v[82:83], v[104:105]
	v_pk_mul_f32 v[82:83], v[74:75], v[92:93]
	v_pk_mul_f32 v[90:91], v[78:79], v[92:93]
	v_pk_add_f32 v[80:81], v[94:95], v[96:97] neg_lo:[0,1] neg_hi:[0,1]
	v_pk_fma_f32 v[78:79], v[78:79], v[84:85], v[82:83] neg_lo:[0,0,1] neg_hi:[0,0,1]
	v_pk_fma_f32 v[74:75], v[74:75], v[84:85], v[90:91]
.LBB0_943:
	v_lshlrev_b32_e32 v82, 9, v102
	v_add_u32_e32 v91, s55, v82
	v_add_u32_e32 v92, s96, v82
	v_or_b32_e32 v90, v82, v176
	s_and_saveexec_b64 s[2:3], s[0:1]
	s_cbranch_execz .LBB0_955
	s_andn2_b64 vcc, exec, s[60:61]
	s_mov_b64 s[18:19], -1
	s_cbranch_vccnz .LBB0_950
	v_cndmask_b32_e64 v82, v91, v92, s[16:17]
	s_lshl_b32 s18, s87, 7
	v_or3_b32 v82, v176, v82, s18
	v_lshlrev_b32_e32 v83, 2, v82
	v_add_lshl_u32 v82, v82, s53, 2
	s_andn2_b64 vcc, exec, s[64:65]
	v_cvt_pk_bf16_f32 v84, v74, v75
	v_cvt_pk_bf16_f32 v85, v76, v77
	global_store_dwordx4 v83, v[78:81], s[92:93]
	global_store_dwordx4 v82, v[74:77], s[92:93]
	v_or_b32_e32 v82, s18, v90
	v_lshl_add_u32 v93, v82, 1, s23
	v_cvt_pk_bf16_f32 v82, v78, v79
	v_cvt_pk_bf16_f32 v83, v80, v81
	s_mov_b64 s[18:19], -1
	s_cbranch_vccnz .LBB0_947
	s_mov_b64 s[18:19], 0
	global_store_dwordx4 v93, v[82:85], s[94:95]
.LBB0_947:
	s_andn2_b64 vcc, exec, s[18:19]
	s_cbranch_vccnz .LBB0_949
	global_store_dwordx2 v93, v[82:83], s[94:95]
	v_add_u32_e32 v82, 32, v93
	global_store_dwordx2 v82, v[84:85], s[94:95]

.LBB0_950:
	s_andn2_b64 vcc, exec, s[18:19]
	s_cbranch_vccnz .LBB0_955
	s_lshl_b32 s18, s22, 9
	v_lshl_or_b32 v82, v176, 1, s18
	v_lshl_add_u32 v82, v102, 12, v82
	v_pk_mul_f32 v[80:81], v[80:81], s[50:51] op_sel_hi:[1,0]
	v_pk_mul_f32 v[78:79], v[78:79], s[50:51] op_sel_hi:[1,0]
	v_add_u32_e32 v83, 0x1ef20200, v82
	v_cvt_pk_bf16_f32 v78, v78, v79
	v_cvt_pk_bf16_f32 v79, v80, v81
	s_andn2_b64 vcc, exec, s[64:65]
	s_mov_b64 s[18:19], -1
	s_cbranch_vccnz .LBB0_953
	v_pk_mul_f32 v[84:85], v[76:77], s[50:51] op_sel_hi:[1,0]
	v_pk_mul_f32 v[80:81], v[74:75], s[50:51] op_sel_hi:[1,0]
	v_cvt_pk_bf16_f32 v80, v80, v81
	v_cvt_pk_bf16_f32 v81, v84, v85
	s_mov_b64 s[18:19], 0
	global_store_dwordx4 v83, v[78:81], s[94:95]
.LBB0_953:
	s_andn2_b64 vcc, exec, s[18:19]
	s_cbranch_vccnz .LBB0_955
	v_pk_mul_f32 v[76:77], v[76:77], s[50:51] op_sel_hi:[1,0]
	v_pk_mul_f32 v[74:75], v[74:75], s[50:51] op_sel_hi:[1,0]
	v_cvt_pk_bf16_f32 v74, v74, v75
	v_cvt_pk_bf16_f32 v75, v76, v77
	v_add_u32_e32 v76, 0x1ef20220, v82
	global_store_dwordx2 v83, v[78:79], s[94:95]
	global_store_dwordx2 v76, v[74:75], s[94:95]

.LBB0_957:
	s_and_saveexec_b64 s[2:3], s[0:1]
	s_cbranch_execz .LBB0_969
	s_andn2_b64 vcc, exec, s[60:61]
	s_mov_b64 s[0:1], -1
	s_cbranch_vccnz .LBB0_964
	s_lshl_b32 s0, s87, 7
	v_cndmask_b32_e64 v74, v91, v92, s[16:17]
	s_bitset1_b32 s0, 7
	v_or3_b32 v74, v176, v74, s0
	v_lshlrev_b32_e32 v75, 2, v74
	v_add_lshl_u32 v74, v74, s53, 2
	s_andn2_b64 vcc, exec, s[64:65]
	v_cvt_pk_bf16_f32 v76, v66, v67
	v_cvt_pk_bf16_f32 v77, v68, v69
	global_store_dwordx4 v75, v[70:73], s[92:93]
	global_store_dwordx4 v74, v[66:69], s[92:93]
	v_or_b32_e32 v74, s0, v90
	v_lshl_add_u32 v78, v74, 1, s23
	v_cvt_pk_bf16_f32 v74, v70, v71
	v_cvt_pk_bf16_f32 v75, v72, v73
	s_mov_b64 s[0:1], -1
	s_cbranch_vccnz .LBB0_961
	s_mov_b64 s[0:1], 0
	global_store_dwordx4 v78, v[74:77], s[94:95]
.LBB0_961:
	s_andn2_b64 vcc, exec, s[0:1]
	s_cbranch_vccnz .LBB0_963
	global_store_dwordx2 v78, v[74:75], s[94:95]
	v_add_u32_e32 v74, 32, v78
	global_store_dwordx2 v74, v[76:77], s[94:95]

.LBB0_964:
	s_andn2_b64 vcc, exec, s[0:1]
	s_cbranch_vccnz .LBB0_969
	s_lshl_b32 s0, s22, 9
	v_lshl_or_b32 v74, v176, 1, s0
	v_lshl_add_u32 v74, v102, 12, v74
	v_pk_mul_f32 v[72:73], v[72:73], s[50:51] op_sel_hi:[1,0]
	v_pk_mul_f32 v[70:71], v[70:71], s[50:51] op_sel_hi:[1,0]
	v_add_u32_e32 v75, 0x1ef20300, v74
	v_cvt_pk_bf16_f32 v70, v70, v71
	v_cvt_pk_bf16_f32 v71, v72, v73
	s_andn2_b64 vcc, exec, s[64:65]
	s_mov_b64 s[0:1], -1
	s_cbranch_vccnz .LBB0_967
	v_pk_mul_f32 v[76:77], v[68:69], s[50:51] op_sel_hi:[1,0]
	v_pk_mul_f32 v[72:73], v[66:67], s[50:51] op_sel_hi:[1,0]
	v_cvt_pk_bf16_f32 v72, v72, v73
	v_cvt_pk_bf16_f32 v73, v76, v77
	s_mov_b64 s[0:1], 0
	global_store_dwordx4 v75, v[70:73], s[94:95]
.LBB0_967:
	s_andn2_b64 vcc, exec, s[0:1]
	s_cbranch_vccnz .LBB0_969
	v_pk_mul_f32 v[68:69], v[68:69], s[50:51] op_sel_hi:[1,0]
	v_pk_mul_f32 v[66:67], v[66:67], s[50:51] op_sel_hi:[1,0]
	v_cvt_pk_bf16_f32 v66, v66, v67
	v_cvt_pk_bf16_f32 v67, v68, v69
	v_add_u32_e32 v68, 0x1ef20320, v74
	global_store_dwordx2 v75, v[70:71], s[94:95]
	global_store_dwordx2 v68, v[66:67], s[94:95]

.LBB0_977:
	global_store_dwordx2 v91, v[86:87], s[94:95]
	v_add_u32_e32 v86, 0x220a0220, v90
	global_store_dwordx2 v86, v[88:89], s[94:95]
	s_and_b64 exec, exec, s[2:3]
	s_cbranch_execnz .LBB0_937
	s_branch .LBB0_938
.LBB0_978:
	v_lshl_or_b32 v186, v83, 6, v209
	ds_bpermute_b32 v74, v218, v62
	ds_bpermute_b32 v75, v218, v63
	v_lshl_add_u64 v[66:67], s[94:95], 0, v[186:187]
	v_lshl_add_u64 v[70:71], v[66:67], 0, s[44:45]
	v_add_co_u32_e32 v66, vcc, 0x140000, v66
	s_nop 0
	s_nop 0
	v_addc_co_u32_e32 v67, vcc, 0, v67, vcc
	global_load_dwordx4 v[66:69], v[66:67], off offset:256
	s_nop 0
	global_load_dwordx4 v[70:73], v[70:71], off offset:16
	s_waitcnt vmcnt(0)
	v_mov_b32_e32 v77, v68
	v_mov_b32_e32 v68, v67
	v_mov_b32_e32 v76, v66
	s_waitcnt lgkmcnt(0)
	v_pk_mul_f32 v[66:67], v[68:69], v[74:75]
	ds_bpermute_b32 v68, v218, v64
	ds_bpermute_b32 v69, v218, v65
	v_mov_b32_e32 v75, v72
	v_mov_b32_e32 v72, v71
	v_cndmask_b32_e64 v67, v67, -v67, s[4:5]
	v_cndmask_b32_e64 v66, v66, -v66, s[4:5]
	s_waitcnt lgkmcnt(0)
	v_pk_mul_f32 v[68:69], v[72:73], v[68:69]
	v_mov_b32_e32 v74, v70
	v_cndmask_b32_e64 v69, v69, -v69, s[4:5]
	v_cndmask_b32_e64 v68, v68, -v68, s[4:5]
	v_pk_fma_f32 v[66:67], v[62:63], v[76:77], v[66:67]
	v_pk_fma_f32 v[68:69], v[64:65], v[74:75], v[68:69]
	s_and_saveexec_b64 s[18:19], s[0:1]
	s_cbranch_execz .LBB0_987
.LBB0_979:
	v_readlane_b32 s2, v254, 18
	v_readlane_b32 s3, v254, 19
	s_andn2_b64 vcc, exec, s[2:3]
	s_mov_b64 s[2:3], -1
	s_cbranch_vccnz .LBB0_985
	v_readlane_b32 s2, v254, 20
	v_readlane_b32 s3, v254, 21
	s_andn2_b64 vcc, exec, s[2:3]
	s_mov_b64 s[2:3], -1
	s_cbranch_vccnz .LBB0_982
	v_mul_f32_e32 v70, 0xbfb8aa3b, v66
	v_mul_f32_e32 v71, 0xbfb8aa3b, v67
	v_mul_f32_e32 v72, 0xbfb8aa3b, v68
	v_mul_f32_e32 v73, 0xbfb8aa3b, v69
	v_exp_f32_e32 v70, v70
	v_exp_f32_e32 v71, v71
	v_exp_f32_e32 v72, v72
	v_exp_f32_e32 v73, v73
	v_add_f32_e32 v70, 1.0, v70
	v_add_f32_e32 v71, 1.0, v71
	v_add_f32_e32 v72, 1.0, v72
	v_add_f32_e32 v73, 1.0, v73
	v_rcp_f32_e32 v70, v70
	v_rcp_f32_e32 v71, v71
	v_rcp_f32_e32 v72, v72
	v_rcp_f32_e32 v73, v73
	v_lshl_add_u32 v74, v82, 6, v252
	s_mov_b64 s[2:3], 0
	global_store_dwordx4 v74, v[70:73], s[94:95]
.LBB0_982:
	s_andn2_b64 vcc, exec, s[2:3]
	s_cbranch_vccnz .LBB0_984
	s_mov_b32 s2, 0x3d000000
	v_lshl_or_b32 v85, v82, 6, v203
	v_pk_mul_f32 v[72:73], v[68:69], s[2:3] op_sel_hi:[1,0]
	v_pk_mul_f32 v[70:71], v[66:67], s[2:3] op_sel_hi:[1,0]
	v_add_u32_e32 v74, 0x23230200, v85
	s_mov_b32 s33, 0x800000
	s_mov_b32 s70, 0x3f317217
	global_store_dwordx4 v74, v[70:73], s[94:95]
	v_or_b32_e32 v74, 0x6c000, v203
	global_load_dwordx4 v[70:73], v74, s[94:95]
	s_nop 0
	global_load_dwordx4 v[74:77], v74, s[94:95] offset:64
	s_waitcnt vmcnt(0)
	v_add_f32_e32 v78, v58, v74
	v_max_f32_e32 v74, 0, v78
	v_mul_f32_e64 v78, |v78|, s27
	v_exp_f32_e32 v78, v78
	s_nop 0
	v_add_f32_e32 v78, 1.0, v78
	v_cmp_gt_f32_e32 vcc, s33, v78
	s_nop 1
	v_cndmask_b32_e64 v79, 0, 32, vcc
	v_ldexp_f32 v78, v78, v79
	v_log_f32_e32 v78, v78
	s_nop 0
	v_mul_f32_e32 v79, 0x3f317217, v78
	v_fma_f32 v79, v78, s70, -v79
	v_fmac_f32_e32 v79, 0x3377d1cf, v78
	v_fmac_f32_e32 v79, 0x3f317217, v78
	v_cmp_lt_f32_e64 s[2:3], |v78|, s39
	s_nop 1
	v_cndmask_b32_e64 v78, v78, v79, s[2:3]
	v_cndmask_b32_e32 v79, 0, v223, vcc
	v_sub_f32_e32 v78, v78, v79
	v_add_f32_e32 v79, v59, v75
	v_max_f32_e32 v75, 0, v79
	v_mul_f32_e64 v79, |v79|, s27
	v_exp_f32_e32 v79, v79
	s_nop 0
	v_add_f32_e32 v79, 1.0, v79
	v_cmp_gt_f32_e32 vcc, s33, v79
	s_nop 1
	v_cndmask_b32_e64 v80, 0, 32, vcc
	v_ldexp_f32 v79, v79, v80
	v_log_f32_e32 v79, v79
	s_nop 0
	v_mul_f32_e32 v80, 0x3f317217, v79
	v_fma_f32 v80, v79, s70, -v80
	v_fmac_f32_e32 v80, 0x3377d1cf, v79
	v_fmac_f32_e32 v80, 0x3f317217, v79
	v_cmp_lt_f32_e64 s[2:3], |v79|, s39
	s_nop 1
	v_cndmask_b32_e64 v79, v79, v80, s[2:3]
	v_cndmask_b32_e32 v80, 0, v223, vcc
	v_sub_f32_e32 v79, v79, v80
	v_add_f32_e32 v80, v60, v76
	v_max_f32_e32 v76, 0, v80
	v_mul_f32_e64 v80, |v80|, s27
	v_exp_f32_e32 v80, v80
	v_pk_add_f32 v[74:75], v[74:75], v[78:79]
	v_add_f32_e32 v80, 1.0, v80
	v_cmp_gt_f32_e32 vcc, s33, v80
	v_pk_mul_f32 v[70:71], v[70:71], v[74:75]
	v_add_u32_e32 v74, 0x232b4200, v85
	v_cndmask_b32_e64 v81, 0, 32, vcc
	v_ldexp_f32 v80, v80, v81
	v_log_f32_e32 v80, v80
	s_nop 0
	v_mul_f32_e32 v81, 0x3f317217, v80
	v_fma_f32 v81, v80, s70, -v81
	v_fmac_f32_e32 v81, 0x3377d1cf, v80
	v_fmac_f32_e32 v81, 0x3f317217, v80
	v_cmp_lt_f32_e64 s[2:3], |v80|, s39
	s_nop 1
	v_cndmask_b32_e64 v80, v80, v81, s[2:3]
	v_cndmask_b32_e32 v81, 0, v223, vcc
	v_sub_f32_e32 v80, v80, v81
	v_add_f32_e32 v81, v61, v77
	v_max_f32_e32 v77, 0, v81
	v_mul_f32_e64 v81, |v81|, s27
	v_exp_f32_e32 v81, v81
	s_nop 0
	v_add_f32_e32 v81, 1.0, v81
	v_cmp_gt_f32_e32 vcc, s33, v81
	s_nop 1
	v_cndmask_b32_e64 v86, 0, 32, vcc
	v_ldexp_f32 v81, v81, v86
	v_log_f32_e32 v81, v81
	s_nop 0
	v_mul_f32_e32 v86, 0x3f317217, v81
	v_fma_f32 v86, v81, s70, -v86
	v_fmac_f32_e32 v86, 0x3377d1cf, v81
	v_fmac_f32_e32 v86, 0x3f317217, v81
	v_cmp_lt_f32_e64 s[2:3], |v81|, s39
	s_nop 1
	v_cndmask_b32_e64 v81, v81, v86, s[2:3]
	v_cndmask_b32_e32 v86, 0, v223, vcc
	v_sub_f32_e32 v81, v81, v86
	v_pk_add_f32 v[76:77], v[76:77], v[80:81]
	s_nop 0
	v_pk_mul_f32 v[72:73], v[72:73], v[76:77]
	global_store_dwordx4 v74, v[70:73], s[94:95]

.LBB0_985:
	s_andn2_b64 vcc, exec, s[2:3]
	s_cbranch_vccnz .LBB0_987
	v_cndmask_b32_e64 v70, v224, v225, s[16:17]
	v_lshl_add_u32 v70, v82, 6, v70
	v_or_b32_e32 v70, v70, v213
	v_lshlrev_b32_e32 v70, 2, v70
	s_nop 4
	global_store_dwordx4 v70, v[66:69], s[92:93]
	global_store_dwordx4 v70, v[58:61], s[92:93] offset:64
	v_lshl_or_b32 v70, v82, 7, v214
	v_add_u32_e32 v71, 0x23120200, v70
	v_cvt_pk_bf16_f32 v66, v66, v67
	v_cvt_pk_bf16_f32 v67, v68, v69
	v_add_u32_e32 v68, 0x23120220, v70
	global_store_dwordx2 v71, v[66:67], s[94:95]
	v_cvt_pk_bf16_f32 v66, v58, v59
	v_cvt_pk_bf16_f32 v67, v60, v61
	global_store_dwordx2 v68, v[66:67], s[94:95]

.LBB0_994:
	s_nop 0
	v_cvt_pk_bf16_f32 v69, v70, v71
	v_lshlrev_b32_e32 v70, 1, v229
	v_lshl_or_b32 v72, v82, 12, v70
	v_add_u32_e32 v70, s33, v72
	s_and_b64 vcc, exec, s[2:3]
	s_mov_b64 s[2:3], -1
	global_store_dwordx4 v70, v[66:69], s[94:95]
	s_cbranch_vccnz .LBB0_996
	s_nop 0
	v_cvt_pk_bf16_f32 v66, v54, v55
	v_cvt_pk_bf16_f32 v67, v56, v57
	v_cvt_pk_bf16_f32 v68, v50, v51
	s_mov_b64 s[2:3], 0
	v_mov_b32_e32 v71, v53
	v_mov_b32_e32 v70, v52

.LBB0_998:
	s_nop 0
	v_cvt_pk_bf16_f32 v69, v70, v71
	v_add_u32_e32 v70, s2, v72
	v_add_u32_e32 v70, 0x100, v70
	global_store_dwordx4 v70, v[66:69], s[94:95]

.LBB0_1001:
	s_andn2_b64 vcc, exec, s[2:3]
	s_cbranch_vccnz .LBB0_1016
	s_and_saveexec_b64 s[18:19], s[0:1]
	s_cbranch_execz .LBB0_1015
	v_ashrrev_i32_e32 v66, 11, v82
	v_mul_lo_u32 v67, v82, s36
	v_mad_i32_i24 v66, v66, 3, v84
	v_mul_lo_u32 v66, v66, s36
	v_add_u32_e32 v72, v67, v228
	v_cmp_gt_i32_e64 s[2:3], s76, v82
	v_cmp_lt_u32_e32 vcc, s37, v84
	v_add_u32_e32 v66, 0xd88800, v66
	v_cvt_pk_bf16_f32 v68, v62, v63
	v_cvt_pk_bf16_f32 v69, v64, v65
	v_cvt_pk_bf16_f32 v70, v58, v59
	v_cvt_pk_bf16_f32 v71, v60, v61
	v_lshl_add_u32 v72, v72, 1, v226
	global_store_dwordx4 v72, v[68:71], s[94:95]
	s_and_saveexec_b64 s[70:71], s[2:3]
	s_xor_b64 s[70:71], exec, s[70:71]
	s_cbranch_execz .LBB0_1007
	s_and_saveexec_b64 s[72:73], vcc
	s_cbranch_execz .LBB0_1006
	v_add_lshl_u32 v68, v66, v228, 2
	global_store_dwordx4 v68, v[62:65], s[92:93]
	global_store_dwordx4 v68, v[58:61], s[92:93] offset:16

.LBB0_1007:
	s_or_saveexec_b64 s[70:71], s[70:71]
	s_movk_i32 s33, 0x4800
	v_mul_lo_u32 v68, v82, s33
	v_add_u32_e32 v68, 0xf8b9b200, v68
	s_xor_b64 exec, exec, s[70:71]
	s_cbranch_execz .LBB0_1009
	v_add_lshl_u32 v69, v68, v228, 2
	global_store_dwordx4 v69, v[62:65], s[92:93]
	global_store_dwordx4 v69, v[58:61], s[92:93] offset:16
.LBB0_1009:
	s_or_b64 exec, exec, s[70:71]
	v_or_b32_e32 v69, 0x80, v228
	v_add_u32_e32 v67, v67, v69
	v_cvt_pk_bf16_f32 v70, v54, v55
	v_cvt_pk_bf16_f32 v71, v56, v57
	v_cvt_pk_bf16_f32 v72, v50, v51
	v_cvt_pk_bf16_f32 v73, v52, v53
	v_lshl_add_u32 v67, v67, 1, v226
	global_store_dwordx4 v67, v[70:73], s[94:95]
	s_and_saveexec_b64 s[70:71], s[2:3]
	s_xor_b64 s[2:3], exec, s[70:71]
	s_cbranch_execz .LBB0_1013
	s_and_saveexec_b64 s[70:71], vcc
	s_cbranch_execz .LBB0_1012
	v_add_lshl_u32 v66, v66, v69, 2
	global_store_dwordx4 v66, v[54:57], s[92:93]
	global_store_dwordx4 v66, v[50:53], s[92:93] offset:16

.LBB0_1013:
	s_andn2_saveexec_b64 s[2:3], s[2:3]
	s_cbranch_execz .LBB0_1015
	v_add_lshl_u32 v66, v68, v69, 2
	global_store_dwordx4 v66, v[54:57], s[92:93]
	global_store_dwordx4 v66, v[50:53], s[92:93] offset:16

.LBB0_1017:
	s_andn2_b64 vcc, exec, s[2:3]
	s_cbranch_vccnz .LBB0_1036
	v_lshl_or_b32 v186, v83, 6, v209
	v_cndmask_b32_e64 v66, 0, 1, s[6:7]
	v_cmp_ne_u32_e64 s[18:19], 1, v66
	v_lshl_add_u64 v[76:77], s[94:95], 0, v[186:187]
	s_andn2_b64 vcc, exec, s[6:7]
	v_lshl_add_u64 v[74:75], v[76:77], 0, s[44:45]
	s_cbranch_vccnz .LBB0_1020
	v_add_co_u32_e32 v66, vcc, 0x140000, v76
	ds_bpermute_b32 v78, v218, v62
	s_nop 0
	v_addc_co_u32_e32 v67, vcc, 0, v77, vcc
	global_load_dwordx4 v[66:69], v[66:67], off offset:256
	s_nop 0
	global_load_dwordx4 v[70:73], v[74:75], off offset:16
	ds_bpermute_b32 v79, v218, v63
	s_waitcnt vmcnt(0)
	v_mov_b32_e32 v81, v68
	v_mov_b32_e32 v68, v67
	v_mov_b32_e32 v80, v66
	s_waitcnt lgkmcnt(0)
	v_pk_mul_f32 v[66:67], v[68:69], v[78:79]
	ds_bpermute_b32 v68, v218, v64
	ds_bpermute_b32 v69, v218, v65
	v_mov_b32_e32 v79, v72
	v_mov_b32_e32 v72, v71
	v_cndmask_b32_e64 v67, v67, -v67, s[4:5]
	v_cndmask_b32_e64 v66, v66, -v66, s[4:5]
	s_waitcnt lgkmcnt(0)
	v_pk_mul_f32 v[68:69], v[72:73], v[68:69]
	v_mov_b32_e32 v78, v70
	v_cndmask_b32_e64 v69, v69, -v69, s[4:5]
	v_cndmask_b32_e64 v68, v68, -v68, s[4:5]
	v_pk_fma_f32 v[66:67], v[62:63], v[80:81], v[66:67]
	v_pk_fma_f32 v[68:69], v[64:65], v[78:79], v[68:69]
	s_branch .LBB0_1021

.LBB0_1021:
	v_lshlrev_b32_e32 v70, 10, v82
	v_or_b32_e32 v79, v70, v215
	v_cmp_lt_i32_e64 s[2:3], s26, v82
	v_add_u32_e32 v78, v70, v216
	s_and_saveexec_b64 s[70:71], s[0:1]
	s_cbranch_execz .LBB0_1026
	s_lshl_b32 s33, s97, 6
	v_add_lshl_u32 v80, v79, s33, 1
	v_add_u32_e32 v81, 0x220a0200, v80
	v_cvt_pk_bf16_f32 v70, v66, v67
	v_cvt_pk_bf16_f32 v71, v68, v69
	s_mov_b64 s[72:73], -1
	s_andn2_b64 vcc, exec, s[40:41]
	v_cvt_pk_bf16_f32 v72, v58, v59
	v_cvt_pk_bf16_f32 v73, v60, v61
	s_cbranch_vccnz .LBB0_1028
	global_store_dwordx4 v81, v[70:73], s[94:95]
	s_cbranch_execz .LBB0_1029

.LBB0_1025:
	v_add_u32_e32 v70, s33, v78
	v_lshl_add_u32 v186, v70, 2, v227
	v_lshl_add_u64 v[70:71], s[94:95], 0, v[186:187]
	v_lshl_add_u64 v[70:71], v[70:71], 0, s[24:25]
	global_store_dwordx4 v186, v[66:69], s[94:95]
	global_store_dwordx4 v[70:71], v[58:61], off

.LBB0_1029:
	global_store_dwordx2 v81, v[70:71], s[94:95]
	v_add_u32_e32 v70, 0x220a0220, v80
	global_store_dwordx2 v70, v[72:73], s[94:95]
	s_and_b64 exec, exec, s[2:3]
	s_cbranch_execnz .LBB0_1025
	s_branch .LBB0_1026

.LBB0_1031:
	s_lshl_b32 s33, s97, 6
	s_bitset1_b32 s33, 7
	v_add_lshl_u32 v74, v79, s33, 1
	v_add_u32_e32 v75, 0x220a0200, v74
	v_cvt_pk_bf16_f32 v70, v66, v67
	v_cvt_pk_bf16_f32 v71, v68, v69
	s_mov_b64 s[70:71], -1
	s_andn2_b64 vcc, exec, s[40:41]
	v_cvt_pk_bf16_f32 v72, v50, v51
	v_cvt_pk_bf16_f32 v73, v52, v53
	s_cbranch_vccnz .LBB0_1103
	global_store_dwordx4 v75, v[70:73], s[94:95]
	s_cbranch_execz .LBB0_1104

.LBB0_1034:
	v_add_u32_e32 v70, s33, v78
	v_lshl_add_u32 v186, v70, 2, v227
	v_lshl_add_u64 v[70:71], s[94:95], 0, v[186:187]
	v_lshl_add_u64 v[70:71], v[70:71], 0, s[24:25]
	global_store_dwordx4 v186, v[66:69], s[94:95]
	global_store_dwordx4 v[70:71], v[50:53], off

.LBB0_1037:
	s_andn2_b64 vcc, exec, s[2:3]
	s_cbranch_vccnz .LBB0_1067
	v_lshl_or_b32 v186, v83, 7, v208
	s_and_b64 vcc, exec, s[10:11]
	v_lshl_add_u64 v[70:71], s[94:95], 0, v[186:187]
	v_lshl_add_u64 v[72:73], v[70:71], 0, s[48:49]
	s_cbranch_vccnz .LBB0_1040
	global_load_dwordx4 v[66:69], v[72:73], off offset:16
	v_add_co_u32_e32 v74, vcc, 0x100000, v70
	s_nop 1
	v_addc_co_u32_e32 v75, vcc, 0, v71, vcc
	global_load_dwordx4 v[74:77], v[74:75], off
	s_waitcnt vmcnt(0)
	v_mul_f32_e32 v78, v64, v66
	v_mul_f32_e32 v84, v64, v67
	v_mov_b32_e32 v64, v61
	v_mul_f32_e32 v80, v60, v67
	v_mul_f32_e32 v66, v60, v66
	v_mov_b32_e32 v60, v65
	v_pk_mul_f32 v[64:65], v[64:65], v[68:69]
	v_pk_mul_f32 v[60:61], v[60:61], v[68:69]
	v_mov_b32_e32 v67, v64
	v_mov_b32_e32 v85, v65
	v_mov_b32_e32 v69, v76
	v_mov_b32_e32 v76, v75
	v_mov_b32_e32 v79, v60
	v_mov_b32_e32 v81, v61
	v_mov_b32_e32 v68, v74
	v_pk_add_f32 v[60:61], v[66:67], v[84:85]
	v_pk_mul_f32 v[66:67], v[58:59], v[76:77]
	v_pk_mul_f32 v[74:75], v[62:63], v[76:77]
	v_pk_add_f32 v[64:65], v[78:79], v[80:81] neg_lo:[0,1] neg_hi:[0,1]
	v_pk_fma_f32 v[62:63], v[62:63], v[68:69], v[66:67] neg_lo:[0,0,1] neg_hi:[0,0,1]
	v_pk_fma_f32 v[58:59], v[58:59], v[68:69], v[74:75]
.LBB0_1040:
	v_lshlrev_b32_e32 v66, 9, v82
	v_add_u32_e32 v75, s55, v66
	v_add_u32_e32 v76, s96, v66
	v_or_b32_e32 v74, v66, v176
	s_and_saveexec_b64 s[2:3], s[0:1]
	s_cbranch_execz .LBB0_1052
	s_andn2_b64 vcc, exec, s[60:61]
	s_mov_b64 s[18:19], -1
	s_cbranch_vccnz .LBB0_1047
	v_cndmask_b32_e64 v66, v75, v76, s[16:17]
	s_lshl_b32 s18, s87, 7
	v_or3_b32 v66, v176, v66, s18
	v_lshlrev_b32_e32 v67, 2, v66
	v_add_lshl_u32 v66, v66, s53, 2
	s_andn2_b64 vcc, exec, s[64:65]
	v_cvt_pk_bf16_f32 v68, v58, v59
	v_cvt_pk_bf16_f32 v69, v60, v61
	global_store_dwordx4 v67, v[62:65], s[92:93]
	global_store_dwordx4 v66, v[58:61], s[92:93]
	v_or_b32_e32 v66, s18, v74
	v_lshl_add_u32 v77, v66, 1, s23
	v_cvt_pk_bf16_f32 v66, v62, v63
	v_cvt_pk_bf16_f32 v67, v64, v65
	s_mov_b64 s[18:19], -1
	s_cbranch_vccnz .LBB0_1044
	s_mov_b64 s[18:19], 0
	global_store_dwordx4 v77, v[66:69], s[94:95]
.LBB0_1044:
	s_andn2_b64 vcc, exec, s[18:19]
	s_cbranch_vccnz .LBB0_1046
	global_store_dwordx2 v77, v[66:67], s[94:95]
	v_add_u32_e32 v66, 32, v77
	global_store_dwordx2 v66, v[68:69], s[94:95]

.LBB0_1047:
	s_andn2_b64 vcc, exec, s[18:19]
	s_cbranch_vccnz .LBB0_1052
	s_lshl_b32 s18, s22, 9
	v_lshl_or_b32 v66, v176, 1, s18
	v_lshl_add_u32 v66, v82, 12, v66
	v_pk_mul_f32 v[64:65], v[64:65], s[50:51] op_sel_hi:[1,0]
	v_pk_mul_f32 v[62:63], v[62:63], s[50:51] op_sel_hi:[1,0]
	v_add_u32_e32 v67, 0x1ef20200, v66
	v_cvt_pk_bf16_f32 v62, v62, v63
	v_cvt_pk_bf16_f32 v63, v64, v65
	s_andn2_b64 vcc, exec, s[64:65]
	s_mov_b64 s[18:19], -1
	s_cbranch_vccnz .LBB0_1050
	v_pk_mul_f32 v[68:69], v[60:61], s[50:51] op_sel_hi:[1,0]
	v_pk_mul_f32 v[64:65], v[58:59], s[50:51] op_sel_hi:[1,0]
	v_cvt_pk_bf16_f32 v64, v64, v65
	v_cvt_pk_bf16_f32 v65, v68, v69
	s_mov_b64 s[18:19], 0
	global_store_dwordx4 v67, v[62:65], s[94:95]
.LBB0_1050:
	s_andn2_b64 vcc, exec, s[18:19]
	s_cbranch_vccnz .LBB0_1052
	v_pk_mul_f32 v[60:61], v[60:61], s[50:51] op_sel_hi:[1,0]
	v_pk_mul_f32 v[58:59], v[58:59], s[50:51] op_sel_hi:[1,0]
	v_cvt_pk_bf16_f32 v58, v58, v59
	v_cvt_pk_bf16_f32 v59, v60, v61
	v_add_u32_e32 v60, 0x1ef20220, v66
	global_store_dwordx2 v67, v[62:63], s[94:95]
	global_store_dwordx2 v60, v[58:59], s[94:95]

.LBB0_1054:
	s_and_saveexec_b64 s[2:3], s[0:1]
	s_cbranch_execz .LBB0_1066
	s_andn2_b64 vcc, exec, s[60:61]
	s_mov_b64 s[0:1], -1
	s_cbranch_vccnz .LBB0_1061
	s_lshl_b32 s0, s87, 7
	v_cndmask_b32_e64 v58, v75, v76, s[16:17]
	s_bitset1_b32 s0, 7
	v_or3_b32 v58, v176, v58, s0
	v_lshlrev_b32_e32 v59, 2, v58
	v_add_lshl_u32 v58, v58, s53, 2
	s_andn2_b64 vcc, exec, s[64:65]
	v_cvt_pk_bf16_f32 v60, v50, v51
	v_cvt_pk_bf16_f32 v61, v52, v53
	global_store_dwordx4 v59, v[54:57], s[92:93]
	global_store_dwordx4 v58, v[50:53], s[92:93]
	v_or_b32_e32 v58, s0, v74
	v_lshl_add_u32 v62, v58, 1, s23
	v_cvt_pk_bf16_f32 v58, v54, v55
	v_cvt_pk_bf16_f32 v59, v56, v57
	s_mov_b64 s[0:1], -1
	s_cbranch_vccnz .LBB0_1058
	s_mov_b64 s[0:1], 0
	global_store_dwordx4 v62, v[58:61], s[94:95]
.LBB0_1058:
	s_andn2_b64 vcc, exec, s[0:1]
	s_cbranch_vccnz .LBB0_1060
	global_store_dwordx2 v62, v[58:59], s[94:95]
	v_add_u32_e32 v58, 32, v62
	global_store_dwordx2 v58, v[60:61], s[94:95]

.LBB0_1061:
	s_andn2_b64 vcc, exec, s[0:1]
	s_cbranch_vccnz .LBB0_1066
	s_lshl_b32 s0, s22, 9
	v_lshl_or_b32 v58, v176, 1, s0
	v_lshl_add_u32 v58, v82, 12, v58
	v_pk_mul_f32 v[56:57], v[56:57], s[50:51] op_sel_hi:[1,0]
	v_pk_mul_f32 v[54:55], v[54:55], s[50:51] op_sel_hi:[1,0]
	v_add_u32_e32 v59, 0x1ef20300, v58
	v_cvt_pk_bf16_f32 v54, v54, v55
	v_cvt_pk_bf16_f32 v55, v56, v57
	s_andn2_b64 vcc, exec, s[64:65]
	s_mov_b64 s[0:1], -1
	s_cbranch_vccnz .LBB0_1064
	v_pk_mul_f32 v[60:61], v[52:53], s[50:51] op_sel_hi:[1,0]
	v_pk_mul_f32 v[56:57], v[50:51], s[50:51] op_sel_hi:[1,0]
	v_cvt_pk_bf16_f32 v56, v56, v57
	v_cvt_pk_bf16_f32 v57, v60, v61
	s_mov_b64 s[0:1], 0
	global_store_dwordx4 v59, v[54:57], s[94:95]
.LBB0_1064:
	s_andn2_b64 vcc, exec, s[0:1]
	s_cbranch_vccnz .LBB0_1066
	v_pk_mul_f32 v[52:53], v[52:53], s[50:51] op_sel_hi:[1,0]
	v_pk_mul_f32 v[50:51], v[50:51], s[50:51] op_sel_hi:[1,0]
	v_cvt_pk_bf16_f32 v50, v50, v51
	v_cvt_pk_bf16_f32 v51, v52, v53
	v_add_u32_e32 v52, 0x1ef20320, v58
	global_store_dwordx2 v59, v[54:55], s[94:95]
	global_store_dwordx2 v52, v[50:51], s[94:95]

.LBB0_1074:
	v_lshl_or_b32 v186, v34, 7, v208
	s_and_b64 vcc, exec, s[10:11]
	v_lshl_add_u64 v[22:23], s[94:95], 0, v[186:187]
	v_lshl_add_u64 v[24:25], v[22:23], 0, s[48:49]
	s_cbranch_vccnz .LBB0_1076
	global_load_dwordx4 v[18:21], v[24:25], off offset:16
	v_add_co_u32_e32 v26, vcc, 0x100000, v22
	s_nop 1
	v_addc_co_u32_e32 v27, vcc, 0, v23, vcc
	global_load_dwordx4 v[26:29], v[26:27], off
	s_waitcnt vmcnt(0)
	v_mul_f32_e32 v30, v16, v18
	v_mul_f32_e32 v34, v16, v19
	v_mov_b32_e32 v16, v13
	v_mul_f32_e32 v32, v12, v19
	v_mul_f32_e32 v18, v12, v18
	v_mov_b32_e32 v12, v17
	v_pk_mul_f32 v[16:17], v[16:17], v[20:21]
	v_pk_mul_f32 v[12:13], v[12:13], v[20:21]
	v_mov_b32_e32 v19, v16
	v_mov_b32_e32 v35, v17
	v_mov_b32_e32 v21, v28
	v_mov_b32_e32 v28, v27
	v_mov_b32_e32 v31, v12
	v_mov_b32_e32 v33, v13
	v_mov_b32_e32 v20, v26
	v_pk_add_f32 v[12:13], v[18:19], v[34:35]
	v_pk_mul_f32 v[18:19], v[10:11], v[28:29]
	v_pk_mul_f32 v[26:27], v[14:15], v[28:29]
	v_pk_add_f32 v[16:17], v[30:31], v[32:33] neg_lo:[0,1] neg_hi:[0,1]
	v_pk_fma_f32 v[14:15], v[14:15], v[20:21], v[18:19] neg_lo:[0,0,1] neg_hi:[0,0,1]
	v_pk_fma_f32 v[10:11], v[10:11], v[20:21], v[26:27]
.LBB0_1076:
	v_lshlrev_b32_e32 v18, 9, v50
	v_add_u32_e32 v27, s55, v18
	v_add_u32_e32 v28, s96, v18
	v_or_b32_e32 v26, v18, v176
	v_cndmask_b32_e64 v18, 0, 1, s[60:61]
	v_cmp_ne_u32_e64 s[2:3], 1, v18
	s_and_saveexec_b64 s[12:13], s[0:1]
	s_cbranch_execz .LBB0_1088
	s_and_b64 vcc, exec, s[2:3]
	s_mov_b64 s[14:15], -1
	s_cbranch_vccnz .LBB0_1083
	v_cndmask_b32_e64 v18, v27, v28, s[16:17]
	s_lshl_b32 s14, s87, 7
	v_or3_b32 v18, v176, v18, s14
	v_lshlrev_b32_e32 v19, 2, v18
	v_add_lshl_u32 v18, v18, s53, 2
	s_andn2_b64 vcc, exec, s[64:65]
	v_cvt_pk_bf16_f32 v20, v10, v11
	v_cvt_pk_bf16_f32 v21, v12, v13
	global_store_dwordx4 v19, v[14:17], s[92:93]
	global_store_dwordx4 v18, v[10:13], s[92:93]
	v_or_b32_e32 v18, s14, v26
	v_lshl_add_u32 v29, v18, 1, s23
	v_cvt_pk_bf16_f32 v18, v14, v15
	v_cvt_pk_bf16_f32 v19, v16, v17
	s_mov_b64 s[14:15], -1
	s_cbranch_vccnz .LBB0_1080
	s_mov_b64 s[14:15], 0
	global_store_dwordx4 v29, v[18:21], s[94:95]
.LBB0_1080:
	s_andn2_b64 vcc, exec, s[14:15]
	s_cbranch_vccnz .LBB0_1082
	global_store_dwordx2 v29, v[18:19], s[94:95]
	v_add_u32_e32 v18, 32, v29
	global_store_dwordx2 v18, v[20:21], s[94:95]

.LBB0_1083:
	s_andn2_b64 vcc, exec, s[14:15]
	s_cbranch_vccnz .LBB0_1088
	s_lshl_b32 s14, s22, 9
	v_lshl_or_b32 v18, v176, 1, s14
	v_lshl_add_u32 v18, v50, 12, v18
	v_pk_mul_f32 v[16:17], v[16:17], s[50:51] op_sel_hi:[1,0]
	v_pk_mul_f32 v[14:15], v[14:15], s[50:51] op_sel_hi:[1,0]
	v_add_u32_e32 v19, 0x1ef20200, v18
	v_cvt_pk_bf16_f32 v14, v14, v15
	v_cvt_pk_bf16_f32 v15, v16, v17
	s_andn2_b64 vcc, exec, s[64:65]
	s_mov_b64 s[14:15], -1
	s_cbranch_vccnz .LBB0_1086
	v_pk_mul_f32 v[20:21], v[12:13], s[50:51] op_sel_hi:[1,0]
	v_pk_mul_f32 v[16:17], v[10:11], s[50:51] op_sel_hi:[1,0]
	v_cvt_pk_bf16_f32 v16, v16, v17
	v_cvt_pk_bf16_f32 v17, v20, v21
	s_mov_b64 s[14:15], 0
	global_store_dwordx4 v19, v[14:17], s[94:95]
.LBB0_1086:
	s_andn2_b64 vcc, exec, s[14:15]
	s_cbranch_vccnz .LBB0_1088
	v_pk_mul_f32 v[12:13], v[12:13], s[50:51] op_sel_hi:[1,0]
	v_pk_mul_f32 v[10:11], v[10:11], s[50:51] op_sel_hi:[1,0]
	v_cvt_pk_bf16_f32 v10, v10, v11
	v_cvt_pk_bf16_f32 v11, v12, v13
	v_add_u32_e32 v12, 0x1ef20220, v18
	global_store_dwordx2 v19, v[14:15], s[94:95]
	global_store_dwordx2 v12, v[10:11], s[94:95]

.LBB0_1104:
	global_store_dwordx2 v75, v[70:71], s[94:95]
	v_add_u32_e32 v70, 0x220a0220, v74
	global_store_dwordx2 v70, v[72:73], s[94:95]
	s_and_b64 exec, exec, s[2:3]
	s_cbranch_execnz .LBB0_1034
	s_branch .LBB0_1035
.LBB0_1105:
	v_lshl_or_b32 v186, v34, 6, v209
	ds_bpermute_b32 v26, v218, v14
	ds_bpermute_b32 v27, v218, v15
	v_lshl_add_u64 v[18:19], s[94:95], 0, v[186:187]
	v_lshl_add_u64 v[22:23], v[18:19], 0, s[44:45]
	v_add_co_u32_e32 v18, vcc, 0x140000, v18
	s_nop 0
	s_nop 0
	v_addc_co_u32_e32 v19, vcc, 0, v19, vcc
	global_load_dwordx4 v[18:21], v[18:19], off offset:256
	s_nop 0
	global_load_dwordx4 v[22:25], v[22:23], off offset:16
	s_waitcnt vmcnt(0)
	v_mov_b32_e32 v29, v20
	v_mov_b32_e32 v20, v19
	v_mov_b32_e32 v28, v18
	s_waitcnt lgkmcnt(0)
	v_pk_mul_f32 v[18:19], v[20:21], v[26:27]
	ds_bpermute_b32 v20, v218, v16
	ds_bpermute_b32 v21, v218, v17
	v_mov_b32_e32 v27, v24
	v_mov_b32_e32 v24, v23
	v_cndmask_b32_e64 v19, v19, -v19, s[4:5]
	v_cndmask_b32_e64 v18, v18, -v18, s[4:5]
	s_waitcnt lgkmcnt(0)
	v_pk_mul_f32 v[20:21], v[24:25], v[20:21]
	v_mov_b32_e32 v26, v22
	v_cndmask_b32_e64 v21, v21, -v21, s[4:5]
	v_cndmask_b32_e64 v20, v20, -v20, s[4:5]
	v_pk_fma_f32 v[18:19], v[14:15], v[28:29], v[18:19]
	v_pk_fma_f32 v[20:21], v[16:17], v[26:27], v[20:21]
	s_and_saveexec_b64 s[12:13], s[0:1]
	s_cbranch_execz .LBB0_1114
.LBB0_1106:
	v_readlane_b32 s2, v254, 18
	v_readlane_b32 s3, v254, 19
	s_andn2_b64 vcc, exec, s[2:3]
	s_mov_b64 s[2:3], -1
	s_cbranch_vccnz .LBB0_1112
	v_readlane_b32 s2, v254, 20
	v_readlane_b32 s3, v254, 21
	s_andn2_b64 vcc, exec, s[2:3]
	s_mov_b64 s[2:3], -1
	s_cbranch_vccnz .LBB0_1109
	v_mul_f32_e32 v22, 0xbfb8aa3b, v18
	v_mul_f32_e32 v23, 0xbfb8aa3b, v19
	v_mul_f32_e32 v24, 0xbfb8aa3b, v20
	v_mul_f32_e32 v25, 0xbfb8aa3b, v21
	v_exp_f32_e32 v22, v22
	v_exp_f32_e32 v23, v23
	v_exp_f32_e32 v24, v24
	v_exp_f32_e32 v25, v25
	v_add_f32_e32 v22, 1.0, v22
	v_add_f32_e32 v23, 1.0, v23
	v_add_f32_e32 v24, 1.0, v24
	v_add_f32_e32 v25, 1.0, v25
	v_rcp_f32_e32 v22, v22
	v_rcp_f32_e32 v23, v23
	v_rcp_f32_e32 v24, v24
	v_rcp_f32_e32 v25, v25
	v_lshl_add_u32 v26, v50, 6, v252
	s_mov_b64 s[2:3], 0
	global_store_dwordx4 v26, v[22:25], s[94:95]
.LBB0_1109:
	s_andn2_b64 vcc, exec, s[2:3]
	s_cbranch_vccnz .LBB0_1111
	s_mov_b32 s2, 0x3d000000
	v_lshl_or_b32 v35, v50, 6, v203
	v_pk_mul_f32 v[24:25], v[20:21], s[2:3] op_sel_hi:[1,0]
	v_pk_mul_f32 v[22:23], v[18:19], s[2:3] op_sel_hi:[1,0]
	v_add_u32_e32 v26, 0x23230200, v35
	s_mov_b32 s14, 0x800000
	s_mov_b32 s15, 0x3f317217
	global_store_dwordx4 v26, v[22:25], s[94:95]
	v_or_b32_e32 v26, 0x6c000, v203
	global_load_dwordx4 v[22:25], v26, s[94:95]
	s_nop 0
	global_load_dwordx4 v[26:29], v26, s[94:95] offset:64
	s_waitcnt vmcnt(0)
	v_add_f32_e32 v30, v10, v26
	v_max_f32_e32 v26, 0, v30
	v_mul_f32_e64 v30, |v30|, s27
	v_exp_f32_e32 v30, v30
	s_nop 0
	v_add_f32_e32 v30, 1.0, v30
	v_cmp_gt_f32_e32 vcc, s14, v30
	s_nop 1
	v_cndmask_b32_e64 v31, 0, 32, vcc
	v_ldexp_f32 v30, v30, v31
	v_log_f32_e32 v30, v30
	s_nop 0
	v_mul_f32_e32 v31, 0x3f317217, v30
	v_fma_f32 v31, v30, s15, -v31
	v_fmac_f32_e32 v31, 0x3377d1cf, v30
	v_fmac_f32_e32 v31, 0x3f317217, v30
	v_cmp_lt_f32_e64 s[2:3], |v30|, s39
	s_nop 1
	v_cndmask_b32_e64 v30, v30, v31, s[2:3]
	v_cndmask_b32_e32 v31, 0, v223, vcc
	v_sub_f32_e32 v30, v30, v31
	v_add_f32_e32 v31, v11, v27
	v_max_f32_e32 v27, 0, v31
	v_mul_f32_e64 v31, |v31|, s27
	v_exp_f32_e32 v31, v31
	s_nop 0
	v_add_f32_e32 v31, 1.0, v31
	v_cmp_gt_f32_e32 vcc, s14, v31
	s_nop 1
	v_cndmask_b32_e64 v32, 0, 32, vcc
	v_ldexp_f32 v31, v31, v32
	v_log_f32_e32 v31, v31
	s_nop 0
	v_mul_f32_e32 v32, 0x3f317217, v31
	v_fma_f32 v32, v31, s15, -v32
	v_fmac_f32_e32 v32, 0x3377d1cf, v31
	v_fmac_f32_e32 v32, 0x3f317217, v31
	v_cmp_lt_f32_e64 s[2:3], |v31|, s39
	s_nop 1
	v_cndmask_b32_e64 v31, v31, v32, s[2:3]
	v_cndmask_b32_e32 v32, 0, v223, vcc
	v_sub_f32_e32 v31, v31, v32
	v_add_f32_e32 v32, v12, v28
	v_max_f32_e32 v28, 0, v32
	v_mul_f32_e64 v32, |v32|, s27
	v_exp_f32_e32 v32, v32
	v_pk_add_f32 v[26:27], v[26:27], v[30:31]
	v_add_f32_e32 v32, 1.0, v32
	v_cmp_gt_f32_e32 vcc, s14, v32
	v_pk_mul_f32 v[22:23], v[22:23], v[26:27]
	v_add_u32_e32 v26, 0x232b4200, v35
	v_cndmask_b32_e64 v33, 0, 32, vcc
	v_ldexp_f32 v32, v32, v33
	v_log_f32_e32 v32, v32
	s_nop 0
	v_mul_f32_e32 v33, 0x3f317217, v32
	v_fma_f32 v33, v32, s15, -v33
	v_fmac_f32_e32 v33, 0x3377d1cf, v32
	v_fmac_f32_e32 v33, 0x3f317217, v32
	v_cmp_lt_f32_e64 s[2:3], |v32|, s39
	s_nop 1
	v_cndmask_b32_e64 v32, v32, v33, s[2:3]
	v_cndmask_b32_e32 v33, 0, v223, vcc
	v_sub_f32_e32 v32, v32, v33
	v_add_f32_e32 v33, v13, v29
	v_max_f32_e32 v29, 0, v33
	v_mul_f32_e64 v33, |v33|, s27
	v_exp_f32_e32 v33, v33
	s_nop 0
	v_add_f32_e32 v33, 1.0, v33
	v_cmp_gt_f32_e32 vcc, s14, v33
	s_nop 1
	v_cndmask_b32_e64 v36, 0, 32, vcc
	v_ldexp_f32 v33, v33, v36
	v_log_f32_e32 v33, v33
	s_nop 0
	v_mul_f32_e32 v36, 0x3f317217, v33
	v_fma_f32 v36, v33, s15, -v36
	v_fmac_f32_e32 v36, 0x3377d1cf, v33
	v_fmac_f32_e32 v36, 0x3f317217, v33
	v_cmp_lt_f32_e64 s[2:3], |v33|, s39
	s_nop 1
	v_cndmask_b32_e64 v33, v33, v36, s[2:3]
	v_cndmask_b32_e32 v36, 0, v223, vcc
	v_sub_f32_e32 v33, v33, v36
	v_pk_add_f32 v[28:29], v[28:29], v[32:33]
	s_nop 0
	v_pk_mul_f32 v[24:25], v[24:25], v[28:29]
	global_store_dwordx4 v26, v[22:25], s[94:95]

.LBB0_1112:
	s_andn2_b64 vcc, exec, s[2:3]
	s_cbranch_vccnz .LBB0_1114
	v_cndmask_b32_e64 v22, v224, v225, s[16:17]
	v_lshl_add_u32 v22, v50, 6, v22
	v_or_b32_e32 v22, v22, v213
	v_lshlrev_b32_e32 v22, 2, v22
	s_nop 4
	global_store_dwordx4 v22, v[18:21], s[92:93]
	global_store_dwordx4 v22, v[10:13], s[92:93] offset:64
	v_lshl_or_b32 v22, v50, 7, v214
	v_add_u32_e32 v23, 0x23120200, v22
	v_cvt_pk_bf16_f32 v18, v18, v19
	v_cvt_pk_bf16_f32 v19, v20, v21
	v_add_u32_e32 v20, 0x23120220, v22
	global_store_dwordx2 v23, v[18:19], s[94:95]
	v_cvt_pk_bf16_f32 v18, v10, v11
	v_cvt_pk_bf16_f32 v19, v12, v13
	global_store_dwordx2 v20, v[18:19], s[94:95]

.LBB0_1121:
	s_nop 0
	v_cvt_pk_bf16_f32 v21, v22, v23
	v_lshlrev_b32_e32 v22, 1, v229
	v_lshl_or_b32 v24, v50, 12, v22
	v_add_u32_e32 v22, s14, v24
	s_and_b64 vcc, exec, s[2:3]
	s_mov_b64 s[2:3], -1
	global_store_dwordx4 v22, v[18:21], s[94:95]
	s_cbranch_vccnz .LBB0_1123
	s_nop 0
	v_cvt_pk_bf16_f32 v18, v6, v7
	v_cvt_pk_bf16_f32 v19, v8, v9
	v_cvt_pk_bf16_f32 v20, v2, v3
	s_mov_b64 s[2:3], 0
	v_mov_b32_e32 v23, v5
	v_mov_b32_e32 v22, v4

.LBB0_1125:
	s_nop 0
	v_cvt_pk_bf16_f32 v21, v22, v23
	v_add_u32_e32 v22, s46, v24
	v_add_u32_e32 v22, 0x100, v22
	global_store_dwordx4 v22, v[18:21], s[94:95]

.LBB0_1128:
	s_andn2_b64 vcc, exec, s[2:3]
	s_cbranch_vccnz .LBB0_1143
	s_and_saveexec_b64 s[12:13], s[0:1]
	s_cbranch_execz .LBB0_1142
	v_ashrrev_i32_e32 v18, 11, v50
	v_mul_lo_u32 v19, v50, s36
	v_mad_i32_i24 v18, v18, 3, v51
	v_mul_lo_u32 v18, v18, s36
	v_add_u32_e32 v24, v19, v228
	v_cmp_gt_i32_e64 s[2:3], s76, v50
	v_cmp_lt_u32_e32 vcc, s37, v51
	v_add_u32_e32 v18, 0xd88800, v18
	v_cvt_pk_bf16_f32 v20, v14, v15
	v_cvt_pk_bf16_f32 v21, v16, v17
	v_cvt_pk_bf16_f32 v22, v10, v11
	v_cvt_pk_bf16_f32 v23, v12, v13
	v_lshl_add_u32 v24, v24, 1, v226
	global_store_dwordx4 v24, v[20:23], s[94:95]
	s_and_saveexec_b64 s[14:15], s[2:3]
	s_xor_b64 s[14:15], exec, s[14:15]
	s_cbranch_execz .LBB0_1134
	s_and_saveexec_b64 s[18:19], vcc
	s_cbranch_execz .LBB0_1133
	v_add_lshl_u32 v20, v18, v228, 2
	global_store_dwordx4 v20, v[14:17], s[92:93]
	global_store_dwordx4 v20, v[10:13], s[92:93] offset:16

.LBB0_1134:
	s_or_saveexec_b64 s[14:15], s[14:15]
	s_movk_i32 s18, 0x4800
	v_mul_lo_u32 v20, v50, s18
	v_add_u32_e32 v20, 0xf8b9b200, v20
	s_xor_b64 exec, exec, s[14:15]
	s_cbranch_execz .LBB0_1136
	v_add_lshl_u32 v21, v20, v228, 2
	global_store_dwordx4 v21, v[14:17], s[92:93]
	global_store_dwordx4 v21, v[10:13], s[92:93] offset:16
.LBB0_1136:
	s_or_b64 exec, exec, s[14:15]
	v_or_b32_e32 v21, 0x80, v228
	v_add_u32_e32 v19, v19, v21
	v_cvt_pk_bf16_f32 v22, v6, v7
	v_cvt_pk_bf16_f32 v23, v8, v9
	v_cvt_pk_bf16_f32 v24, v2, v3
	v_cvt_pk_bf16_f32 v25, v4, v5
	v_lshl_add_u32 v19, v19, 1, v226
	global_store_dwordx4 v19, v[22:25], s[94:95]
	s_and_saveexec_b64 s[14:15], s[2:3]
	s_xor_b64 s[2:3], exec, s[14:15]
	s_cbranch_execz .LBB0_1140
	s_and_saveexec_b64 s[14:15], vcc
	s_cbranch_execz .LBB0_1139
	v_add_lshl_u32 v18, v18, v21, 2
	global_store_dwordx4 v18, v[6:9], s[92:93]
	global_store_dwordx4 v18, v[2:5], s[92:93] offset:16

.LBB0_1140:
	s_andn2_saveexec_b64 s[2:3], s[2:3]
	s_cbranch_execz .LBB0_1142
	v_add_lshl_u32 v18, v20, v21, 2
	global_store_dwordx4 v18, v[6:9], s[92:93]
	global_store_dwordx4 v18, v[2:5], s[92:93] offset:16

.LBB0_1144:
	s_andn2_b64 vcc, exec, s[2:3]
	s_cbranch_vccnz .LBB0_1163
	v_lshl_or_b32 v186, v34, 6, v209
	v_cndmask_b32_e64 v18, 0, 1, s[6:7]
	v_cmp_ne_u32_e64 s[14:15], 1, v18
	v_lshl_add_u64 v[28:29], s[94:95], 0, v[186:187]
	s_andn2_b64 vcc, exec, s[6:7]
	v_lshl_add_u64 v[26:27], v[28:29], 0, s[44:45]
	s_cbranch_vccnz .LBB0_1147
	v_add_co_u32_e32 v18, vcc, 0x140000, v28
	ds_bpermute_b32 v30, v218, v14
	s_nop 0
	v_addc_co_u32_e32 v19, vcc, 0, v29, vcc
	global_load_dwordx4 v[18:21], v[18:19], off offset:256
	s_nop 0
	global_load_dwordx4 v[22:25], v[26:27], off offset:16
	ds_bpermute_b32 v31, v218, v15
	s_waitcnt vmcnt(0)
	v_mov_b32_e32 v33, v20
	v_mov_b32_e32 v20, v19
	v_mov_b32_e32 v32, v18
	s_waitcnt lgkmcnt(0)
	v_pk_mul_f32 v[18:19], v[20:21], v[30:31]
	ds_bpermute_b32 v20, v218, v16
	ds_bpermute_b32 v21, v218, v17
	v_mov_b32_e32 v31, v24
	v_mov_b32_e32 v24, v23
	v_cndmask_b32_e64 v19, v19, -v19, s[4:5]
	v_cndmask_b32_e64 v18, v18, -v18, s[4:5]
	s_waitcnt lgkmcnt(0)
	v_pk_mul_f32 v[20:21], v[24:25], v[20:21]
	v_mov_b32_e32 v30, v22
	v_cndmask_b32_e64 v21, v21, -v21, s[4:5]
	v_cndmask_b32_e64 v20, v20, -v20, s[4:5]
	v_pk_fma_f32 v[18:19], v[14:15], v[32:33], v[18:19]
	v_pk_fma_f32 v[20:21], v[16:17], v[30:31], v[20:21]
	s_branch .LBB0_1148

.LBB0_1148:
	v_lshlrev_b32_e32 v22, 10, v50
	v_or_b32_e32 v31, v22, v215
	v_add_u32_e32 v30, v22, v216
	v_cndmask_b32_e64 v22, 0, 1, s[40:41]
	v_cmp_lt_i32_e64 s[2:3], s26, v50
	v_cmp_ne_u32_e64 s[12:13], 1, v22
	s_and_saveexec_b64 s[18:19], s[0:1]
	s_cbranch_execz .LBB0_1153
	s_lshl_b32 s33, s97, 6
	v_add_lshl_u32 v32, v31, s33, 1
	v_add_u32_e32 v33, 0x220a0200, v32
	v_cvt_pk_bf16_f32 v22, v18, v19
	v_cvt_pk_bf16_f32 v23, v20, v21
	s_mov_b64 s[62:63], -1
	s_and_b64 vcc, exec, s[12:13]
	v_cvt_pk_bf16_f32 v24, v10, v11
	v_cvt_pk_bf16_f32 v25, v12, v13
	s_cbranch_vccnz .LBB0_1155
	global_store_dwordx4 v33, v[22:25], s[94:95]
	s_cbranch_execz .LBB0_1156

.LBB0_1152:
	v_add_u32_e32 v22, s33, v30
	v_lshl_add_u32 v186, v22, 2, v227
	v_lshl_add_u64 v[22:23], s[94:95], 0, v[186:187]
	v_lshl_add_u64 v[22:23], v[22:23], 0, s[24:25]
	global_store_dwordx4 v186, v[18:21], s[94:95]
	global_store_dwordx4 v[22:23], v[10:13], off

.LBB0_1156:
	global_store_dwordx2 v33, v[22:23], s[94:95]
	v_add_u32_e32 v22, 0x220a0220, v32
	global_store_dwordx2 v22, v[24:25], s[94:95]
	s_and_b64 exec, exec, s[2:3]
	s_cbranch_execnz .LBB0_1152
	s_branch .LBB0_1153

.LBB0_1158:
	s_lshl_b32 s33, s97, 6
	s_bitset1_b32 s33, 7
	v_add_lshl_u32 v26, v31, s33, 1
	v_add_u32_e32 v27, 0x220a0200, v26
	v_cvt_pk_bf16_f32 v22, v18, v19
	v_cvt_pk_bf16_f32 v23, v20, v21
	s_mov_b64 s[18:19], -1
	s_and_b64 vcc, exec, s[12:13]
	v_cvt_pk_bf16_f32 v24, v2, v3
	v_cvt_pk_bf16_f32 v25, v4, v5
	s_cbranch_vccnz .LBB0_1167
	global_store_dwordx4 v27, v[22:25], s[94:95]
	s_cbranch_execz .LBB0_1168

.LBB0_1161:
	v_add_u32_e32 v22, s33, v30
	v_lshl_add_u32 v186, v22, 2, v227
	v_lshl_add_u64 v[22:23], s[94:95], 0, v[186:187]
	v_lshl_add_u64 v[22:23], v[22:23], 0, s[24:25]
	global_store_dwordx4 v186, v[18:21], s[94:95]
	global_store_dwordx4 v[22:23], v[2:5], off
